# IEEE f32 division chains (div_scale/fma/div_fmas/div_fixup) replaced by v_rcp_f32 (+mul) in sigmoid/rsqrt epilogues; f32 throughout; on top of hand-written RWKV scanner
# speedup vs baseline: 1.0558x; 1.0455x over previous
.LBB0_105:
	s_waitcnt vmcnt(0) lgkmcnt(0)
	s_barrier
	s_and_saveexec_b64 s[4:5], s[0:1]
	s_cbranch_execz .LBB0_107
	v_lshl_add_u64 v[132:133], v[132:133], 4, s[2:3]
	global_load_dword v134, v[132:133], off sc1
	global_load_dword v135, v[132:133], off offset:4 sc1
	global_load_dword v136, v[132:133], off offset:8 sc1
	s_nop 0
	global_load_dword v132, v[132:133], off offset:12 sc1
	s_mov_b32 s0, 0xf800000
	v_lshl_add_u32 v30, v30, 2, 0
	s_waitcnt vmcnt(3)
	v_add_f32_e32 v133, 0, v134
	s_waitcnt vmcnt(2)
	v_add_f32_e32 v133, v133, v135
	s_waitcnt vmcnt(1)
	v_add_f32_e32 v133, v133, v136
	s_waitcnt vmcnt(0)
	v_add_f32_e32 v132, v133, v132
	v_fmamk_f32 v132, v132, 0x3a800000, v188
	v_mul_f32_e32 v133, 0x4f800000, v132
	v_cmp_gt_f32_e32 vcc, s0, v132
	s_nop 1
	v_cndmask_b32_e32 v132, v132, v133, vcc
	v_sqrt_f32_e32 v133, v132
	s_nop 0
	v_add_u32_e32 v134, -1, v133
	v_add_u32_e32 v135, 1, v133
	v_fma_f32 v136, -v134, v133, v132
	v_fma_f32 v137, -v135, v133, v132
	v_cmp_ge_f32_e64 s[0:1], 0, v136
	s_nop 1
	v_cndmask_b32_e64 v133, v133, v134, s[0:1]
	v_cmp_lt_f32_e64 s[0:1], 0, v137
	s_nop 1
	v_cndmask_b32_e64 v133, v133, v135, s[0:1]
	v_mul_f32_e32 v134, 0x37800000, v133
	v_cndmask_b32_e32 v133, v133, v134, vcc
	v_cmp_class_f32_e32 vcc, v132, v189
	s_nop 1
	v_cndmask_b32_e32 v132, v133, v132, vcc
	v_rcp_f32_e32 v132, v132
	ds_write_b32 v30, v132 offset:8192

.LBB0_247:
	s_or_b64 exec, exec, s[2:3]
	v_lshlrev_b32_e32 v136, 2, v139
	v_add_u32_e32 v172, s23, v136
	ds_read_b128 v[174:177], v172
	ds_read_b128 v[178:181], v172 offset:1024
	ds_read_b128 v[182:185], v172 offset:2048
	ds_read_b128 v[132:135], v172 offset:3072
	s_lshl_b32 s0, s27, 8
	s_or_b32 s1, s8, s18
	s_add_i32 s0, s0, s17
	v_add_u32_e32 v164, s1, v139
	v_mov_b32_dpp v139, v128 row_ror:2 row_mask:0xf bank_mask:0xf bound_ctrl:1
	v_mov_b32_dpp v157, v31 row_ror:2 row_mask:0xf bank_mask:0xf bound_ctrl:1
	v_cmp_lt_i32_e64 s[40:41], 1, v138
	v_add_u32_e32 v173, s0, v138
	v_mov_b32_dpp v137, v128 row_ror:1 row_mask:0xf bank_mask:0xf bound_ctrl:1
	v_mov_b32_dpp v156, v31 row_ror:1 row_mask:0xf bank_mask:0xf bound_ctrl:1
	v_cmp_lt_i32_e64 s[42:43], 0, v138
	v_cndmask_b32_e64 v138, v157, v139, s[40:41]
	s_waitcnt lgkmcnt(0)
	v_fma_f32 v132, v174, v138, v132
	v_cndmask_b32_e64 v137, v156, v137, s[42:43]
	v_mov_b32_dpp v138, v129 row_ror:2 row_mask:0xf bank_mask:0xf bound_ctrl:1
	v_fmac_f32_e32 v132, v178, v137
	v_mov_b32_dpp v137, v129 row_ror:1 row_mask:0xf bank_mask:0xf bound_ctrl:1
	v_cndmask_b32_e64 v138, v157, v138, s[40:41]
	v_cndmask_b32_e64 v137, v156, v137, s[42:43]
	v_fma_f32 v133, v175, v138, v133
	v_mov_b32_dpp v138, v130 row_ror:2 row_mask:0xf bank_mask:0xf bound_ctrl:1
	v_fmac_f32_e32 v133, v179, v137
	v_mov_b32_dpp v137, v130 row_ror:1 row_mask:0xf bank_mask:0xf bound_ctrl:1
	v_cndmask_b32_e64 v138, v157, v138, s[40:41]
	v_cndmask_b32_e64 v137, v156, v137, s[42:43]
	v_fma_f32 v134, v176, v138, v134
	v_mov_b32_dpp v138, v131 row_ror:2 row_mask:0xf bank_mask:0xf bound_ctrl:1
	v_fmac_f32_e32 v134, v180, v137
	v_mov_b32_dpp v137, v131 row_ror:1 row_mask:0xf bank_mask:0xf bound_ctrl:1
	v_cndmask_b32_e64 v138, v157, v138, s[40:41]
	s_movk_i32 s0, 0x3080
	v_cndmask_b32_e64 v137, v156, v137, s[42:43]
	v_fmac_f32_e32 v135, v177, v138
	v_ashrrev_i32_e32 v165, 31, v164
	v_mad_i64_i32 v[166:167], s[0:1], v173, s0, 0
	v_fmac_f32_e32 v132, v128, v182
	v_fmac_f32_e32 v133, v129, v183
	v_fmac_f32_e32 v135, v181, v137
	v_fmac_f32_e32 v134, v130, v184
	v_fmac_f32_e32 v135, v131, v185
	v_add_u32_e32 v174, s24, v136
	ds_read_b128 v[176:179], v174
	ds_read_b128 v[180:183], v174 offset:1024
	ds_read_b128 v[184:187], v174 offset:2048
	ds_read_b128 v[136:139], v174 offset:3072
	v_mov_b32_dpp v200, v120 row_ror:2 row_mask:0xf bank_mask:0xf bound_ctrl:1
	v_mov_b32_dpp v175, v120 row_ror:1 row_mask:0xf bank_mask:0xf bound_ctrl:1
	v_cndmask_b32_e64 v200, v157, v200, s[40:41]
	v_cndmask_b32_e64 v175, v156, v175, s[42:43]
	s_waitcnt lgkmcnt(0)
	v_fma_f32 v136, v176, v200, v136
	v_mov_b32_dpp v176, v121 row_ror:2 row_mask:0xf bank_mask:0xf bound_ctrl:1
	v_fmac_f32_e32 v136, v180, v175
	v_mov_b32_dpp v175, v121 row_ror:1 row_mask:0xf bank_mask:0xf bound_ctrl:1
	v_cndmask_b32_e64 v176, v157, v176, s[40:41]
	v_cndmask_b32_e64 v175, v156, v175, s[42:43]
	v_fma_f32 v137, v177, v176, v137
	v_mov_b32_dpp v176, v122 row_ror:2 row_mask:0xf bank_mask:0xf bound_ctrl:1
	v_fmac_f32_e32 v137, v181, v175
	v_mov_b32_dpp v175, v122 row_ror:1 row_mask:0xf bank_mask:0xf bound_ctrl:1
	v_cndmask_b32_e64 v176, v157, v176, s[40:41]
	v_cndmask_b32_e64 v175, v156, v175, s[42:43]
	v_fma_f32 v138, v178, v176, v138
	v_mov_b32_dpp v176, v123 row_ror:2 row_mask:0xf bank_mask:0xf bound_ctrl:1
	v_fmac_f32_e32 v138, v182, v175
	v_mov_b32_dpp v175, v123 row_ror:1 row_mask:0xf bank_mask:0xf bound_ctrl:1
	v_cndmask_b32_e64 v157, v157, v176, s[40:41]
	v_cndmask_b32_e64 v156, v156, v175, s[42:43]
	v_fmac_f32_e32 v139, v179, v157
	v_fmac_f32_e32 v139, v183, v156
	v_fmac_f32_e32 v136, v120, v184
	v_fmac_f32_e32 v137, v121, v185
	v_fmac_f32_e32 v138, v122, v186
	v_fmac_f32_e32 v139, v123, v187
	v_mul_f32_e32 v156, 0xbfb8aa3b, v132
	v_exp_f32_e32 v156, v156
	s_nop 0
	v_add_f32_e32 v156, 1.0, v156
	s_nop 0
	v_rcp_f32_e32 v156, v156
	s_nop 0
	v_mul_f32_e32 v132, v132, v156
	v_mul_f32_e32 v132, v132, v136
	v_mul_f32_e32 v136, 0xbfb8aa3b, v133
	v_exp_f32_e32 v136, v136
	s_nop 0
	v_add_f32_e32 v136, 1.0, v136
	s_nop 0
	v_rcp_f32_e32 v136, v136
	s_nop 0
	v_mul_f32_e32 v133, v133, v136
	v_mul_f32_e32 v133, v133, v137
	v_cvt_pk_bf16_f32 v132, v132, v133
	v_mul_f32_e32 v133, 0xbfb8aa3b, v134
	v_exp_f32_e32 v133, v133
	s_nop 0
	v_add_f32_e32 v133, 1.0, v133
	s_nop 0
	v_rcp_f32_e32 v133, v133
	s_nop 0
	v_mul_f32_e32 v133, v134, v133
	v_mul_f32_e32 v134, 0xbfb8aa3b, v135
	v_exp_f32_e32 v134, v134
	v_mul_f32_e32 v133, v133, v138
	v_add_f32_e32 v134, 1.0, v134
	s_nop 0
	v_rcp_f32_e32 v134, v134
	s_nop 0
	v_mul_f32_e32 v134, v135, v134
	v_mul_f32_e32 v134, v134, v139
	v_cvt_pk_bf16_f32 v133, v133, v134
	v_lshl_add_u64 v[134:135], s[34:35], 0, v[166:167]
	v_lshl_add_u64 v[166:167], v[164:165], 1, v[134:135]
	s_and_saveexec_b64 s[0:1], s[44:45]
	s_cbranch_execz .LBB0_249
	global_store_dwordx2 v[166:167], v[132:133], off offset:2048
.LBB0_249:
	s_or_b64 exec, exec, s[0:1]
	ds_read_b128 v[136:139], v172 offset:16
	ds_read_b128 v[176:179], v172 offset:1040
	ds_read_b128 v[180:183], v172 offset:2064
	ds_read_b128 v[132:135], v172 offset:3088
	v_mov_b32_dpp v157, v112 row_ror:2 row_mask:0xf bank_mask:0xf bound_ctrl:1
	v_mov_b32_dpp v200, v31 row_ror:2 row_mask:0xf bank_mask:0xf bound_ctrl:1
	v_mov_b32_dpp v156, v112 row_ror:1 row_mask:0xf bank_mask:0xf bound_ctrl:1
	v_mov_b32_dpp v175, v31 row_ror:1 row_mask:0xf bank_mask:0xf bound_ctrl:1
	v_cndmask_b32_e64 v157, v200, v157, s[40:41]
	v_cndmask_b32_e64 v156, v175, v156, s[42:43]
	s_waitcnt lgkmcnt(0)
	v_fma_f32 v132, v136, v157, v132
	v_fmac_f32_e32 v132, v176, v156
	v_mov_b32_dpp v156, v113 row_ror:2 row_mask:0xf bank_mask:0xf bound_ctrl:1
	v_mov_b32_dpp v136, v113 row_ror:1 row_mask:0xf bank_mask:0xf bound_ctrl:1
	v_cndmask_b32_e64 v156, v200, v156, s[40:41]
	v_cndmask_b32_e64 v136, v175, v136, s[42:43]
	v_fma_f32 v133, v137, v156, v133
	v_mov_b32_dpp v137, v114 row_ror:2 row_mask:0xf bank_mask:0xf bound_ctrl:1
	v_fmac_f32_e32 v133, v177, v136
	v_mov_b32_dpp v136, v114 row_ror:1 row_mask:0xf bank_mask:0xf bound_ctrl:1
	v_cndmask_b32_e64 v137, v200, v137, s[40:41]
	v_cndmask_b32_e64 v136, v175, v136, s[42:43]
	v_fma_f32 v134, v138, v137, v134
	v_mov_b32_dpp v137, v115 row_ror:2 row_mask:0xf bank_mask:0xf bound_ctrl:1
	v_fmac_f32_e32 v134, v178, v136
	v_mov_b32_dpp v136, v115 row_ror:1 row_mask:0xf bank_mask:0xf bound_ctrl:1
	v_cndmask_b32_e64 v137, v200, v137, s[40:41]
	v_cndmask_b32_e64 v136, v175, v136, s[42:43]
	v_fmac_f32_e32 v135, v139, v137
	v_fmac_f32_e32 v132, v112, v180
	v_fmac_f32_e32 v133, v113, v181
	v_fmac_f32_e32 v135, v179, v136
	v_fmac_f32_e32 v134, v114, v182
	v_fmac_f32_e32 v135, v115, v183
	ds_read_b128 v[176:179], v172 offset:528
	ds_read_b128 v[180:183], v172 offset:1552
	ds_read_b128 v[184:187], v172 offset:2576
	ds_read_b128 v[136:139], v172 offset:3600
	v_mov_b32_dpp v157, v104 row_ror:2 row_mask:0xf bank_mask:0xf bound_ctrl:1
	v_mov_b32_dpp v156, v104 row_ror:1 row_mask:0xf bank_mask:0xf bound_ctrl:1
	v_cndmask_b32_e64 v157, v200, v157, s[40:41]
	v_cndmask_b32_e64 v156, v175, v156, s[42:43]
	s_waitcnt lgkmcnt(0)
	v_fma_f32 v136, v176, v157, v136
	v_mov_b32_dpp v157, v105 row_ror:2 row_mask:0xf bank_mask:0xf bound_ctrl:1
	v_fmac_f32_e32 v136, v180, v156
	v_mov_b32_dpp v156, v105 row_ror:1 row_mask:0xf bank_mask:0xf bound_ctrl:1
	v_cndmask_b32_e64 v157, v200, v157, s[40:41]
	v_cndmask_b32_e64 v156, v175, v156, s[42:43]
	v_fma_f32 v137, v177, v157, v137
	v_mov_b32_dpp v157, v106 row_ror:2 row_mask:0xf bank_mask:0xf bound_ctrl:1
	v_fmac_f32_e32 v137, v181, v156
	v_mov_b32_dpp v156, v106 row_ror:1 row_mask:0xf bank_mask:0xf bound_ctrl:1
	v_cndmask_b32_e64 v157, v200, v157, s[40:41]
	v_cndmask_b32_e64 v156, v175, v156, s[42:43]
	v_fma_f32 v138, v178, v157, v138
	v_mov_b32_dpp v157, v107 row_ror:2 row_mask:0xf bank_mask:0xf bound_ctrl:1
	v_fmac_f32_e32 v138, v182, v156
	v_mov_b32_dpp v156, v107 row_ror:1 row_mask:0xf bank_mask:0xf bound_ctrl:1
	v_cndmask_b32_e64 v157, v200, v157, s[40:41]
	v_cndmask_b32_e64 v156, v175, v156, s[42:43]
	v_fmac_f32_e32 v139, v179, v157
	v_fmac_f32_e32 v139, v183, v156
	v_fmac_f32_e32 v136, v104, v184
	v_fmac_f32_e32 v137, v105, v185
	v_fmac_f32_e32 v138, v106, v186
	v_fmac_f32_e32 v139, v107, v187
	v_mul_f32_e32 v156, 0xbfb8aa3b, v132
	v_exp_f32_e32 v156, v156
	s_nop 0
	v_add_f32_e32 v156, 1.0, v156
	s_nop 0
	v_rcp_f32_e32 v156, v156
	s_nop 0
	v_mul_f32_e32 v132, v132, v156
	v_mul_f32_e32 v132, v132, v136
	v_mul_f32_e32 v136, 0xbfb8aa3b, v133
	v_exp_f32_e32 v136, v136
	s_nop 0
	v_add_f32_e32 v136, 1.0, v136
	s_nop 0
	v_rcp_f32_e32 v136, v136
	s_nop 0
	v_mul_f32_e32 v133, v133, v136
	v_mul_f32_e32 v133, v133, v137
	v_cvt_pk_bf16_f32 v132, v132, v133
	v_mul_f32_e32 v133, 0xbfb8aa3b, v134
	v_exp_f32_e32 v133, v133
	s_nop 0
	v_add_f32_e32 v133, 1.0, v133
	s_nop 0
	v_rcp_f32_e32 v133, v133
	s_nop 0
	v_mul_f32_e32 v133, v134, v133
	v_mul_f32_e32 v134, 0xbfb8aa3b, v135
	v_exp_f32_e32 v134, v134
	v_mul_f32_e32 v133, v133, v138
	v_add_f32_e32 v134, 1.0, v134
	s_nop 0
	v_rcp_f32_e32 v134, v134
	s_nop 0
	v_mul_f32_e32 v134, v135, v134
	v_mul_f32_e32 v134, v134, v139
	v_cvt_pk_bf16_f32 v133, v133, v134
	s_and_saveexec_b64 s[0:1], s[44:45]
	s_cbranch_execz .LBB0_251
	global_store_dwordx2 v[166:167], v[132:133], off offset:2056
.LBB0_251:
	s_or_b64 exec, exec, s[0:1]
	ds_read_b128 v[176:179], v172
	ds_read_b128 v[180:183], v172 offset:1024
	ds_read_b128 v[184:187], v172 offset:2048
	ds_read_b128 v[202:205], v172 offset:3072
	v_add_u32_e32 v224, 16, v173
	v_mov_b32_dpp v137, v124 row_ror:1 row_mask:0xf bank_mask:0xf bound_ctrl:1
	v_mov_b32_dpp v136, v124 row_ror:2 row_mask:0xf bank_mask:0xf bound_ctrl:1
	v_mov_b32_dpp v139, v128 row_ror:1 row_mask:0xf bank_mask:0xf bound_ctrl:1
	v_mov_b32_dpp v166, v128 row_ror:2 row_mask:0xf bank_mask:0xf bound_ctrl:1
	v_mov_b32_dpp v135, v125 row_ror:1 row_mask:0xf bank_mask:0xf bound_ctrl:1
	v_mov_b32_dpp v134, v125 row_ror:2 row_mask:0xf bank_mask:0xf bound_ctrl:1
	v_mov_b32_dpp v175, v129 row_ror:1 row_mask:0xf bank_mask:0xf bound_ctrl:1
	v_mov_b32_dpp v225, v129 row_ror:2 row_mask:0xf bank_mask:0xf bound_ctrl:1
	v_mov_b32_dpp v133, v126 row_ror:1 row_mask:0xf bank_mask:0xf bound_ctrl:1
	v_mov_b32_dpp v132, v126 row_ror:2 row_mask:0xf bank_mask:0xf bound_ctrl:1
	v_mov_b32_dpp v226, v130 row_ror:1 row_mask:0xf bank_mask:0xf bound_ctrl:1
	v_mov_b32_dpp v227, v130 row_ror:2 row_mask:0xf bank_mask:0xf bound_ctrl:1
	v_mov_b32_dpp v129, v127 row_ror:1 row_mask:0xf bank_mask:0xf bound_ctrl:1
	v_mov_b32_dpp v128, v127 row_ror:2 row_mask:0xf bank_mask:0xf bound_ctrl:1
	v_mov_b32_dpp v228, v131 row_ror:1 row_mask:0xf bank_mask:0xf bound_ctrl:1
	v_mov_b32_dpp v229, v131 row_ror:2 row_mask:0xf bank_mask:0xf bound_ctrl:1
	ds_read_b128 v[206:209], v174
	ds_read_b128 v[210:213], v174 offset:1024
	ds_read_b128 v[214:217], v174 offset:2048
	ds_read_b128 v[218:221], v174 offset:3072
	v_mov_b32_dpp v130, v116 row_ror:2 row_mask:0xf bank_mask:0xf bound_ctrl:1
	v_mov_b32_dpp v131, v120 row_ror:1 row_mask:0xf bank_mask:0xf bound_ctrl:1
	v_mov_b32_dpp v120, v120 row_ror:2 row_mask:0xf bank_mask:0xf bound_ctrl:1
	v_mov_b32_dpp v138, v116 row_ror:1 row_mask:0xf bank_mask:0xf bound_ctrl:1
	v_cndmask_b32_e64 v167, v120, v130, s[40:41]
	v_cndmask_b32_e64 v166, v166, v136, s[40:41]
	s_waitcnt lgkmcnt(7)
	v_mov_b32_e32 v200, v176
	s_waitcnt lgkmcnt(3)
	v_mov_b32_e32 v201, v206
	v_mov_b32_e32 v222, v202
	s_waitcnt lgkmcnt(0)
	v_mov_b32_e32 v223, v218
	v_cndmask_b32_e64 v157, v131, v138, s[42:43]
	v_cndmask_b32_e64 v156, v139, v137, s[42:43]
	v_pk_fma_f32 v[166:167], v[200:201], v[166:167], v[222:223]
	v_mov_b32_e32 v200, v180
	v_mov_b32_e32 v201, v210
	v_pk_fma_f32 v[156:157], v[200:201], v[156:157], v[166:167]
	v_mov_b32_e32 v166, v124
	v_mov_b32_e32 v167, v116
	v_mov_b32_e32 v200, v184
	v_mov_b32_e32 v201, v214
	v_mov_b32_dpp v131, v117 row_ror:2 row_mask:0xf bank_mask:0xf bound_ctrl:1
	v_mov_b32_dpp v124, v121 row_ror:2 row_mask:0xf bank_mask:0xf bound_ctrl:1
	v_pk_fma_f32 v[156:157], v[166:167], v[200:201], v[156:157]
	v_mov_b32_dpp v166, v117 row_ror:1 row_mask:0xf bank_mask:0xf bound_ctrl:1
	v_mov_b32_dpp v116, v121 row_ror:1 row_mask:0xf bank_mask:0xf bound_ctrl:1
	v_cndmask_b32_e64 v201, v124, v131, s[40:41]
	v_cndmask_b32_e64 v200, v225, v134, s[40:41]
	v_mov_b32_e32 v206, v177
	v_mov_b32_e32 v218, v203
	v_cndmask_b32_e64 v121, v116, v166, s[42:43]
	v_cndmask_b32_e64 v120, v175, v135, s[42:43]
	v_pk_fma_f32 v[176:177], v[206:207], v[200:201], v[218:219]
	v_mov_b32_e32 v210, v181
	v_pk_fma_f32 v[120:121], v[210:211], v[120:121], v[176:177]
	v_mov_b32_e32 v116, v125
	v_mov_b32_e32 v214, v185
	v_pk_fma_f32 v[124:125], v[116:117], v[214:215], v[120:121]
	v_mov_b32_dpp v139, v118 row_ror:2 row_mask:0xf bank_mask:0xf bound_ctrl:1
	v_mov_b32_dpp v120, v122 row_ror:2 row_mask:0xf bank_mask:0xf bound_ctrl:1
	v_mov_b32_dpp v175, v118 row_ror:1 row_mask:0xf bank_mask:0xf bound_ctrl:1
	v_mov_b32_dpp v116, v122 row_ror:1 row_mask:0xf bank_mask:0xf bound_ctrl:1
	v_cndmask_b32_e64 v121, v120, v139, s[40:41]
	v_cndmask_b32_e64 v120, v227, v132, s[40:41]
	v_mov_b32_e32 v176, v178
	v_mov_b32_e32 v177, v208
	v_mov_b32_e32 v180, v204
	v_mov_b32_e32 v181, v220
	v_cndmask_b32_e64 v117, v116, v175, s[42:43]
	v_cndmask_b32_e64 v116, v226, v133, s[42:43]
	v_pk_fma_f32 v[120:121], v[176:177], v[120:121], v[180:181]
	v_mov_b32_e32 v176, v182
	v_mov_b32_e32 v177, v212
	v_pk_fma_f32 v[116:117], v[176:177], v[116:117], v[120:121]
	v_mov_b32_e32 v120, v126
	v_mov_b32_e32 v121, v118
	v_mov_b32_e32 v176, v186
	v_mov_b32_e32 v177, v216
	v_mov_b32_dpp v167, v119 row_ror:2 row_mask:0xf bank_mask:0xf bound_ctrl:1
	v_mov_b32_dpp v118, v123 row_ror:2 row_mask:0xf bank_mask:0xf bound_ctrl:1
	v_pk_fma_f32 v[120:121], v[120:121], v[176:177], v[116:117]
	v_mov_b32_dpp v176, v119 row_ror:1 row_mask:0xf bank_mask:0xf bound_ctrl:1
	v_mov_b32_dpp v116, v123 row_ror:1 row_mask:0xf bank_mask:0xf bound_ctrl:1
	v_cndmask_b32_e64 v123, v118, v167, s[40:41]
	v_cndmask_b32_e64 v122, v229, v128, s[40:41]
	v_mov_b32_e32 v208, v179
	v_mov_b32_e32 v220, v205
	v_cndmask_b32_e64 v117, v116, v176, s[42:43]
	v_cndmask_b32_e64 v116, v228, v129, s[42:43]
	v_pk_fma_f32 v[122:123], v[208:209], v[122:123], v[220:221]
	v_mov_b32_e32 v212, v183
	v_pk_fma_f32 v[116:117], v[212:213], v[116:117], v[122:123]
	v_mov_b32_e32 v118, v127
	v_mov_b32_e32 v216, v187
	v_pk_fma_f32 v[116:117], v[118:119], v[216:217], v[116:117]
	v_mul_f32_e32 v118, 0xbfb8aa3b, v156
	v_exp_f32_e32 v118, v118
	s_movk_i32 s2, 0x3080
	v_add_f32_e32 v118, 1.0, v118
	s_nop 0
	v_rcp_f32_e32 v118, v118
	v_mul_f32_e32 v119, 0xbfb8aa3b, v124
	v_exp_f32_e32 v119, v119
	v_mul_f32_e32 v118, v156, v118
	v_mul_f32_e32 v118, v118, v157
	v_add_f32_e32 v119, 1.0, v119
	s_nop 0
	v_rcp_f32_e32 v119, v119
	s_nop 0
	v_mul_f32_e32 v119, v124, v119
	v_mul_f32_e32 v119, v119, v125
	v_cvt_pk_bf16_f32 v122, v118, v119
	v_mul_f32_e32 v118, 0xbfb8aa3b, v120
	v_exp_f32_e32 v118, v118
	s_nop 0
	v_add_f32_e32 v118, 1.0, v118
	s_nop 0
	v_rcp_f32_e32 v118, v118
	v_mul_f32_e32 v119, 0xbfb8aa3b, v116
	v_exp_f32_e32 v119, v119
	v_mul_f32_e32 v118, v120, v118
	v_mul_f32_e32 v118, v118, v121
	v_add_f32_e32 v119, 1.0, v119
	s_nop 0
	v_rcp_f32_e32 v119, v119
	s_nop 0
	v_mul_f32_e32 v116, v116, v119
	v_mul_f32_e32 v116, v116, v117
	v_cvt_pk_bf16_f32 v123, v118, v116
	v_mov_b64_e32 v[118:119], s[34:35]
	v_mad_i64_i32 v[120:121], s[0:1], v224, s2, v[118:119]
	v_lshlrev_b64 v[116:117], 1, v[164:165]
	v_lshl_add_u64 v[120:121], v[120:121], 0, v[116:117]
	global_store_dwordx2 v[120:121], v[122:123], off offset:2048
	ds_read_b128 v[180:183], v172 offset:16
	ds_read_b128 v[184:187], v172 offset:1040
	ds_read_b128 v[202:205], v172 offset:2064
	ds_read_b128 v[206:209], v172 offset:3088
	v_mov_b32_dpp v127, v108 row_ror:1 row_mask:0xf bank_mask:0xf bound_ctrl:1
	v_mov_b32_dpp v126, v108 row_ror:2 row_mask:0xf bank_mask:0xf bound_ctrl:1
	v_mov_b32_dpp v156, v112 row_ror:1 row_mask:0xf bank_mask:0xf bound_ctrl:1
	v_mov_b32_dpp v178, v112 row_ror:2 row_mask:0xf bank_mask:0xf bound_ctrl:1
	v_mov_b32_dpp v125, v109 row_ror:1 row_mask:0xf bank_mask:0xf bound_ctrl:1
	v_mov_b32_dpp v124, v109 row_ror:2 row_mask:0xf bank_mask:0xf bound_ctrl:1
	v_mov_b32_dpp v228, v113 row_ror:1 row_mask:0xf bank_mask:0xf bound_ctrl:1
	v_mov_b32_dpp v229, v113 row_ror:2 row_mask:0xf bank_mask:0xf bound_ctrl:1
	v_mov_b32_dpp v123, v110 row_ror:1 row_mask:0xf bank_mask:0xf bound_ctrl:1
	v_mov_b32_dpp v122, v110 row_ror:2 row_mask:0xf bank_mask:0xf bound_ctrl:1
	v_mov_b32_dpp v230, v114 row_ror:1 row_mask:0xf bank_mask:0xf bound_ctrl:1
	v_mov_b32_dpp v231, v114 row_ror:2 row_mask:0xf bank_mask:0xf bound_ctrl:1
	v_mov_b32_dpp v113, v111 row_ror:1 row_mask:0xf bank_mask:0xf bound_ctrl:1
	v_mov_b32_dpp v112, v111 row_ror:2 row_mask:0xf bank_mask:0xf bound_ctrl:1
	v_mov_b32_dpp v232, v115 row_ror:1 row_mask:0xf bank_mask:0xf bound_ctrl:1
	v_mov_b32_dpp v233, v115 row_ror:2 row_mask:0xf bank_mask:0xf bound_ctrl:1
	ds_read_b128 v[210:213], v172 offset:528
	ds_read_b128 v[214:217], v172 offset:1552
	ds_read_b128 v[218:221], v172 offset:2576
	ds_read_b128 v[222:225], v172 offset:3600
	v_mov_b32_dpp v114, v100 row_ror:2 row_mask:0xf bank_mask:0xf bound_ctrl:1
	v_mov_b32_dpp v115, v104 row_ror:1 row_mask:0xf bank_mask:0xf bound_ctrl:1
	v_mov_b32_dpp v104, v104 row_ror:2 row_mask:0xf bank_mask:0xf bound_ctrl:1
	v_mov_b32_dpp v177, v100 row_ror:1 row_mask:0xf bank_mask:0xf bound_ctrl:1
	v_cndmask_b32_e64 v179, v104, v114, s[40:41]
	v_cndmask_b32_e64 v178, v178, v126, s[40:41]
	s_waitcnt lgkmcnt(7)
	v_mov_b32_e32 v200, v180
	s_waitcnt lgkmcnt(3)
	v_mov_b32_e32 v201, v210
	v_mov_b32_e32 v226, v206
	s_waitcnt lgkmcnt(0)
	v_mov_b32_e32 v227, v222
	v_cndmask_b32_e64 v157, v115, v177, s[42:43]
	v_cndmask_b32_e64 v156, v156, v127, s[42:43]
	v_pk_fma_f32 v[178:179], v[200:201], v[178:179], v[226:227]
	v_mov_b32_e32 v200, v184
	v_mov_b32_e32 v201, v214
	v_pk_fma_f32 v[156:157], v[200:201], v[156:157], v[178:179]
	v_mov_b32_e32 v178, v108
	v_mov_b32_e32 v179, v100
	v_mov_b32_e32 v200, v202
	v_mov_b32_e32 v201, v218
	v_mov_b32_dpp v115, v101 row_ror:2 row_mask:0xf bank_mask:0xf bound_ctrl:1
	v_mov_b32_dpp v108, v105 row_ror:2 row_mask:0xf bank_mask:0xf bound_ctrl:1
	v_pk_fma_f32 v[156:157], v[178:179], v[200:201], v[156:157]
	v_mov_b32_dpp v179, v101 row_ror:1 row_mask:0xf bank_mask:0xf bound_ctrl:1
	v_mov_b32_dpp v100, v105 row_ror:1 row_mask:0xf bank_mask:0xf bound_ctrl:1
	v_cndmask_b32_e64 v201, v108, v115, s[40:41]
	v_cndmask_b32_e64 v200, v229, v124, s[40:41]
	v_mov_b32_e32 v210, v181
	v_mov_b32_e32 v222, v207
	v_cndmask_b32_e64 v105, v100, v179, s[42:43]
	v_cndmask_b32_e64 v104, v228, v125, s[42:43]
	v_pk_fma_f32 v[180:181], v[210:211], v[200:201], v[222:223]
	v_mov_b32_e32 v214, v185
	v_pk_fma_f32 v[104:105], v[214:215], v[104:105], v[180:181]
	v_mov_b32_e32 v100, v109
	v_mov_b32_e32 v218, v203
	v_pk_fma_f32 v[108:109], v[100:101], v[218:219], v[104:105]
	v_mov_b32_dpp v178, v102 row_ror:2 row_mask:0xf bank_mask:0xf bound_ctrl:1
	v_mov_b32_dpp v104, v106 row_ror:2 row_mask:0xf bank_mask:0xf bound_ctrl:1
	v_mov_b32_dpp v180, v102 row_ror:1 row_mask:0xf bank_mask:0xf bound_ctrl:1
	v_mov_b32_dpp v100, v106 row_ror:1 row_mask:0xf bank_mask:0xf bound_ctrl:1
	v_cndmask_b32_e64 v105, v104, v178, s[40:41]
	v_cndmask_b32_e64 v104, v231, v122, s[40:41]
	v_mov_b32_e32 v184, v182
	v_mov_b32_e32 v185, v212
	v_mov_b32_e32 v200, v208
	v_mov_b32_e32 v201, v224
	v_cndmask_b32_e64 v101, v100, v180, s[42:43]
	v_cndmask_b32_e64 v100, v230, v123, s[42:43]
	v_pk_fma_f32 v[104:105], v[184:185], v[104:105], v[200:201]
	v_mov_b32_e32 v184, v186
	v_mov_b32_e32 v185, v216
	v_pk_fma_f32 v[100:101], v[184:185], v[100:101], v[104:105]
	v_mov_b32_e32 v104, v110
	v_mov_b32_e32 v105, v102
	v_mov_b32_e32 v184, v204
	v_mov_b32_e32 v185, v220
	v_mov_b32_dpp v110, v103 row_ror:2 row_mask:0xf bank_mask:0xf bound_ctrl:1
	v_mov_b32_dpp v102, v107 row_ror:2 row_mask:0xf bank_mask:0xf bound_ctrl:1
	v_pk_fma_f32 v[104:105], v[104:105], v[184:185], v[100:101]
	v_mov_b32_dpp v181, v103 row_ror:1 row_mask:0xf bank_mask:0xf bound_ctrl:1
	v_mov_b32_dpp v100, v107 row_ror:1 row_mask:0xf bank_mask:0xf bound_ctrl:1
	v_cndmask_b32_e64 v107, v102, v110, s[40:41]
	v_cndmask_b32_e64 v106, v233, v112, s[40:41]
	v_mov_b32_e32 v212, v183
	v_mov_b32_e32 v224, v209
	v_cndmask_b32_e64 v101, v100, v181, s[42:43]
	v_cndmask_b32_e64 v100, v232, v113, s[42:43]
	v_pk_fma_f32 v[106:107], v[212:213], v[106:107], v[224:225]
	v_mov_b32_e32 v216, v187
	v_pk_fma_f32 v[100:101], v[216:217], v[100:101], v[106:107]
	v_mov_b32_e32 v102, v111
	v_mov_b32_e32 v220, v205
	v_pk_fma_f32 v[100:101], v[102:103], v[220:221], v[100:101]
	v_mul_f32_e32 v102, 0xbfb8aa3b, v156
	v_exp_f32_e32 v102, v102
	s_nop 0
	v_add_f32_e32 v102, 1.0, v102
	s_nop 0
	v_rcp_f32_e32 v102, v102
	v_mul_f32_e32 v103, 0xbfb8aa3b, v108
	v_exp_f32_e32 v103, v103
	v_mul_f32_e32 v102, v156, v102
	v_mul_f32_e32 v102, v102, v157
	v_add_f32_e32 v103, 1.0, v103
	s_nop 0
	v_rcp_f32_e32 v103, v103
	s_nop 0
	v_mul_f32_e32 v103, v108, v103
	v_mul_f32_e32 v103, v103, v109
	v_cvt_pk_bf16_f32 v102, v102, v103
	v_mul_f32_e32 v103, 0xbfb8aa3b, v104
	v_exp_f32_e32 v103, v103
	s_nop 0
	v_add_f32_e32 v103, 1.0, v103
	s_nop 0
	v_rcp_f32_e32 v103, v103
	s_nop 0
	v_mul_f32_e32 v103, v104, v103
	v_mul_f32_e32 v104, 0xbfb8aa3b, v100
	v_exp_f32_e32 v104, v104
	v_mul_f32_e32 v103, v103, v105
	v_add_f32_e32 v104, 1.0, v104
	s_nop 0
	v_rcp_f32_e32 v104, v104
	s_nop 0
	v_mul_f32_e32 v100, v100, v104
	v_mul_f32_e32 v100, v100, v101
	v_cvt_pk_bf16_f32 v103, v103, v100
	global_store_dwordx2 v[120:121], v[102:103], off offset:2056
	ds_read_b128 v[184:187], v172
	ds_read_b128 v[202:205], v172 offset:1024
	ds_read_b128 v[206:209], v172 offset:2048
	ds_read_b128 v[210:213], v172 offset:3072
	v_add_u32_e32 v107, 32, v173
	v_mov_b32_dpp v108, v96 row_ror:1 row_mask:0xf bank_mask:0xf bound_ctrl:1
	v_mov_b32_dpp v106, v96 row_ror:2 row_mask:0xf bank_mask:0xf bound_ctrl:1
	v_mov_b32_dpp v105, v97 row_ror:1 row_mask:0xf bank_mask:0xf bound_ctrl:1
	v_mov_b32_dpp v104, v97 row_ror:2 row_mask:0xf bank_mask:0xf bound_ctrl:1
	v_mov_b32_dpp v103, v98 row_ror:1 row_mask:0xf bank_mask:0xf bound_ctrl:1
	v_mov_b32_dpp v102, v98 row_ror:2 row_mask:0xf bank_mask:0xf bound_ctrl:1
	v_mov_b32_dpp v101, v99 row_ror:1 row_mask:0xf bank_mask:0xf bound_ctrl:1
	v_mov_b32_dpp v100, v99 row_ror:2 row_mask:0xf bank_mask:0xf bound_ctrl:1
	ds_read_b128 v[214:217], v174
	ds_read_b128 v[218:221], v174 offset:1024
	ds_read_b128 v[222:225], v174 offset:2048
	ds_read_b128 v[226:229], v174 offset:3072
	v_mov_b32_dpp v111, v92 row_ror:2 row_mask:0xf bank_mask:0xf bound_ctrl:1
	v_mov_b32_dpp v182, v92 row_ror:1 row_mask:0xf bank_mask:0xf bound_ctrl:1
	v_cndmask_b32_e64 v120, v137, v108, s[42:43]
	v_cndmask_b32_e64 v137, v130, v111, s[40:41]
	v_cndmask_b32_e64 v136, v136, v106, s[40:41]
	s_waitcnt lgkmcnt(7)
	v_mov_b32_e32 v156, v184
	s_waitcnt lgkmcnt(3)
	v_mov_b32_e32 v157, v214
	v_mov_b32_e32 v200, v210
	s_waitcnt lgkmcnt(0)
	v_mov_b32_e32 v201, v226
	v_cndmask_b32_e64 v121, v138, v182, s[42:43]
	v_pk_fma_f32 v[136:137], v[156:157], v[136:137], v[200:201]
	v_mov_b32_e32 v156, v202
	v_mov_b32_e32 v157, v218
	v_pk_fma_f32 v[120:121], v[156:157], v[120:121], v[136:137]
	v_mov_b32_e32 v136, v96
	v_mov_b32_e32 v137, v92
	v_mov_b32_e32 v156, v206
	v_mov_b32_e32 v157, v222
	v_pk_fma_f32 v[156:157], v[136:137], v[156:157], v[120:121]
	v_mov_b32_dpp v120, v93 row_ror:2 row_mask:0xf bank_mask:0xf bound_ctrl:1
	v_mov_b32_dpp v136, v93 row_ror:1 row_mask:0xf bank_mask:0xf bound_ctrl:1
	v_cndmask_b32_e64 v131, v131, v120, s[40:41]
	v_cndmask_b32_e64 v130, v134, v104, s[40:41]
	v_mov_b32_e32 v214, v185
	v_mov_b32_e32 v226, v211
	v_cndmask_b32_e64 v201, v166, v136, s[42:43]
	v_cndmask_b32_e64 v200, v135, v105, s[42:43]
	v_pk_fma_f32 v[130:131], v[214:215], v[130:131], v[226:227]
	v_mov_b32_e32 v218, v203
	v_pk_fma_f32 v[130:131], v[218:219], v[200:201], v[130:131]
	v_mov_b32_e32 v92, v97
	v_mov_b32_e32 v222, v207
	v_mov_b32_dpp v121, v94 row_ror:2 row_mask:0xf bank_mask:0xf bound_ctrl:1
	v_pk_fma_f32 v[134:135], v[92:93], v[222:223], v[130:131]
	v_mov_b32_dpp v131, v94 row_ror:1 row_mask:0xf bank_mask:0xf bound_ctrl:1
	v_cndmask_b32_e64 v92, v133, v103, s[42:43]
	v_cndmask_b32_e64 v97, v139, v121, s[40:41]
	v_cndmask_b32_e64 v96, v132, v102, s[40:41]
	v_mov_b32_e32 v132, v186
	v_mov_b32_e32 v133, v216
	v_mov_b32_e32 v138, v212
	v_mov_b32_e32 v139, v228
	v_cndmask_b32_e64 v93, v175, v131, s[42:43]
	v_pk_fma_f32 v[96:97], v[132:133], v[96:97], v[138:139]
	v_mov_b32_e32 v132, v204
	v_mov_b32_e32 v133, v220
	v_pk_fma_f32 v[92:93], v[132:133], v[92:93], v[96:97]
	v_mov_b32_e32 v96, v98
	v_mov_b32_e32 v97, v94
	v_mov_b32_e32 v132, v208
	v_mov_b32_e32 v133, v224
	v_mov_b32_dpp v130, v95 row_ror:2 row_mask:0xf bank_mask:0xf bound_ctrl:1
	v_pk_fma_f32 v[96:97], v[96:97], v[132:133], v[92:93]
	v_mov_b32_dpp v132, v95 row_ror:1 row_mask:0xf bank_mask:0xf bound_ctrl:1
	v_cndmask_b32_e64 v92, v129, v101, s[42:43]
	v_cndmask_b32_e64 v129, v167, v130, s[40:41]
	v_cndmask_b32_e64 v128, v128, v100, s[40:41]
	v_mov_b32_e32 v216, v187
	v_mov_b32_e32 v228, v213
	v_cndmask_b32_e64 v93, v176, v132, s[42:43]
	v_pk_fma_f32 v[128:129], v[216:217], v[128:129], v[228:229]
	v_mov_b32_e32 v220, v205
	v_pk_fma_f32 v[92:93], v[220:221], v[92:93], v[128:129]
	v_mov_b32_e32 v94, v99
	v_mov_b32_e32 v224, v209
	v_pk_fma_f32 v[92:93], v[94:95], v[224:225], v[92:93]
	v_mul_f32_e32 v94, 0xbfb8aa3b, v156
	v_exp_f32_e32 v94, v94
	s_nop 0
	v_add_f32_e32 v94, 1.0, v94
	s_nop 0
	v_rcp_f32_e32 v94, v94
	v_mul_f32_e32 v95, 0xbfb8aa3b, v134
	v_exp_f32_e32 v95, v95
	v_mul_f32_e32 v94, v156, v94
	v_mul_f32_e32 v94, v94, v157
	v_add_f32_e32 v95, 1.0, v95
	s_nop 0
	v_rcp_f32_e32 v95, v95
	s_nop 0
	v_mul_f32_e32 v95, v134, v95
	v_mul_f32_e32 v95, v95, v135
	v_cvt_pk_bf16_f32 v94, v94, v95
	v_mul_f32_e32 v95, 0xbfb8aa3b, v96
	v_exp_f32_e32 v95, v95
	s_nop 0
	v_add_f32_e32 v95, 1.0, v95
	s_nop 0
	v_rcp_f32_e32 v95, v95
	s_nop 0
	v_mul_f32_e32 v95, v96, v95
	v_mul_f32_e32 v96, 0xbfb8aa3b, v92
	v_exp_f32_e32 v96, v96
	v_mul_f32_e32 v95, v95, v97
	v_add_f32_e32 v96, 1.0, v96
	s_nop 0
	v_rcp_f32_e32 v96, v96
	s_nop 0
	v_mul_f32_e32 v92, v92, v96
	v_mul_f32_e32 v92, v92, v93
	v_cvt_pk_bf16_f32 v95, v95, v92
	v_mad_i64_i32 v[92:93], s[0:1], v107, s2, v[118:119]
	v_lshl_add_u64 v[92:93], v[92:93], 0, v[116:117]
	global_store_dwordx2 v[92:93], v[94:95], off offset:2048
	ds_read_b128 v[184:187], v172 offset:16
	ds_read_b128 v[202:205], v172 offset:1040
	ds_read_b128 v[206:209], v172 offset:2064
	ds_read_b128 v[210:213], v172 offset:3088
	v_mov_b32_dpp v109, v88 row_ror:1 row_mask:0xf bank_mask:0xf bound_ctrl:1
	v_mov_b32_dpp v107, v88 row_ror:2 row_mask:0xf bank_mask:0xf bound_ctrl:1
	v_mov_b32_dpp v99, v89 row_ror:1 row_mask:0xf bank_mask:0xf bound_ctrl:1
	v_mov_b32_dpp v98, v89 row_ror:2 row_mask:0xf bank_mask:0xf bound_ctrl:1
	v_mov_b32_dpp v97, v90 row_ror:1 row_mask:0xf bank_mask:0xf bound_ctrl:1
	v_mov_b32_dpp v96, v90 row_ror:2 row_mask:0xf bank_mask:0xf bound_ctrl:1
	v_mov_b32_dpp v95, v91 row_ror:1 row_mask:0xf bank_mask:0xf bound_ctrl:1
	v_mov_b32_dpp v94, v91 row_ror:2 row_mask:0xf bank_mask:0xf bound_ctrl:1
	ds_read_b128 v[214:217], v172 offset:528
	ds_read_b128 v[218:221], v172 offset:1552
	ds_read_b128 v[222:225], v172 offset:2576
	ds_read_b128 v[226:229], v172 offset:3600
	v_mov_b32_dpp v128, v84 row_ror:2 row_mask:0xf bank_mask:0xf bound_ctrl:1
	v_mov_b32_dpp v129, v84 row_ror:1 row_mask:0xf bank_mask:0xf bound_ctrl:1
	v_cndmask_b32_e64 v134, v127, v109, s[42:43]
	v_cndmask_b32_e64 v127, v114, v128, s[40:41]
	v_cndmask_b32_e64 v126, v126, v107, s[40:41]
	s_waitcnt lgkmcnt(7)
	v_mov_b32_e32 v138, v184
	s_waitcnt lgkmcnt(3)
	v_mov_b32_e32 v139, v214
	v_mov_b32_e32 v156, v210
	s_waitcnt lgkmcnt(0)
	v_mov_b32_e32 v157, v226
	v_cndmask_b32_e64 v135, v177, v129, s[42:43]
	v_pk_fma_f32 v[126:127], v[138:139], v[126:127], v[156:157]
	v_mov_b32_e32 v138, v202
	v_mov_b32_e32 v139, v218
	v_pk_fma_f32 v[126:127], v[138:139], v[134:135], v[126:127]
	v_mov_b32_e32 v134, v88
	v_mov_b32_e32 v135, v84
	v_mov_b32_e32 v138, v206
	v_mov_b32_e32 v139, v222
	v_mov_b32_dpp v114, v85 row_ror:2 row_mask:0xf bank_mask:0xf bound_ctrl:1
	v_pk_fma_f32 v[134:135], v[134:135], v[138:139], v[126:127]
	v_mov_b32_dpp v126, v85 row_ror:1 row_mask:0xf bank_mask:0xf bound_ctrl:1
	v_cndmask_b32_e64 v138, v125, v99, s[42:43]
	v_cndmask_b32_e64 v125, v115, v114, s[40:41]
	v_cndmask_b32_e64 v124, v124, v98, s[40:41]
	v_mov_b32_e32 v214, v185
	v_mov_b32_e32 v226, v211
	v_cndmask_b32_e64 v139, v179, v126, s[42:43]
	v_pk_fma_f32 v[124:125], v[214:215], v[124:125], v[226:227]
	v_mov_b32_e32 v218, v203
	v_pk_fma_f32 v[124:125], v[218:219], v[138:139], v[124:125]
	v_mov_b32_e32 v84, v89
	v_mov_b32_e32 v222, v207
	v_mov_b32_dpp v115, v86 row_ror:2 row_mask:0xf bank_mask:0xf bound_ctrl:1
	v_pk_fma_f32 v[138:139], v[84:85], v[222:223], v[124:125]
	v_mov_b32_dpp v124, v86 row_ror:1 row_mask:0xf bank_mask:0xf bound_ctrl:1
	v_cndmask_b32_e64 v84, v123, v97, s[42:43]
	v_cndmask_b32_e64 v89, v178, v115, s[40:41]
	v_cndmask_b32_e64 v88, v122, v96, s[40:41]
	v_mov_b32_e32 v122, v186
	v_mov_b32_e32 v123, v216
	v_mov_b32_e32 v156, v212
	v_mov_b32_e32 v157, v228
	v_cndmask_b32_e64 v85, v180, v124, s[42:43]
	v_pk_fma_f32 v[88:89], v[122:123], v[88:89], v[156:157]
	v_mov_b32_e32 v122, v204
	v_mov_b32_e32 v123, v220
	v_pk_fma_f32 v[84:85], v[122:123], v[84:85], v[88:89]
	v_mov_b32_e32 v88, v90
	v_mov_b32_e32 v89, v86
	v_mov_b32_e32 v122, v208
	v_mov_b32_e32 v123, v224
	v_mov_b32_dpp v90, v87 row_ror:2 row_mask:0xf bank_mask:0xf bound_ctrl:1
	v_pk_fma_f32 v[88:89], v[88:89], v[122:123], v[84:85]
	v_mov_b32_dpp v122, v87 row_ror:1 row_mask:0xf bank_mask:0xf bound_ctrl:1
	v_cndmask_b32_e64 v84, v113, v95, s[42:43]
	v_cndmask_b32_e64 v113, v110, v90, s[40:41]
	v_cndmask_b32_e64 v112, v112, v94, s[40:41]
	v_mov_b32_e32 v216, v187
	v_mov_b32_e32 v228, v213
	v_cndmask_b32_e64 v85, v181, v122, s[42:43]
	v_pk_fma_f32 v[112:113], v[216:217], v[112:113], v[228:229]
	v_mov_b32_e32 v220, v205
	v_pk_fma_f32 v[84:85], v[220:221], v[84:85], v[112:113]
	v_mov_b32_e32 v86, v91
	v_mov_b32_e32 v224, v209
	v_pk_fma_f32 v[84:85], v[86:87], v[224:225], v[84:85]
	v_mul_f32_e32 v86, 0xbfb8aa3b, v134
	v_exp_f32_e32 v86, v86
	s_nop 0
	v_add_f32_e32 v86, 1.0, v86
	s_nop 0
	v_rcp_f32_e32 v86, v86
	v_mul_f32_e32 v87, 0xbfb8aa3b, v138
	v_exp_f32_e32 v87, v87
	v_mul_f32_e32 v86, v134, v86
	v_mul_f32_e32 v86, v86, v135
	v_add_f32_e32 v87, 1.0, v87
	s_nop 0
	v_rcp_f32_e32 v87, v87
	s_nop 0
	v_mul_f32_e32 v87, v138, v87
	v_mul_f32_e32 v87, v87, v139
	v_cvt_pk_bf16_f32 v86, v86, v87
	v_mul_f32_e32 v87, 0xbfb8aa3b, v88
	v_exp_f32_e32 v87, v87
	s_nop 0
	v_add_f32_e32 v87, 1.0, v87
	s_nop 0
	v_rcp_f32_e32 v87, v87
	s_nop 0
	v_mul_f32_e32 v87, v88, v87
	v_mul_f32_e32 v88, 0xbfb8aa3b, v84
	v_exp_f32_e32 v88, v88
	v_mul_f32_e32 v87, v87, v89
	v_add_f32_e32 v88, 1.0, v88
	s_nop 0
	v_rcp_f32_e32 v88, v88
	s_nop 0
	v_mul_f32_e32 v84, v84, v88
	v_mul_f32_e32 v84, v84, v85
	v_cvt_pk_bf16_f32 v87, v87, v84
	global_store_dwordx2 v[92:93], v[86:87], off offset:2056
	ds_read_b128 v[84:87], v172
	ds_read_b128 v[176:179], v172 offset:1024
	ds_read_b128 v[184:187], v172 offset:2048
	ds_read_b128 v[202:205], v172 offset:3072
	v_add_u32_e32 v91, 48, v173
	v_mov_b32_dpp v88, v80 row_ror:1 row_mask:0xf bank_mask:0xf bound_ctrl:1
	v_mov_b32_dpp v92, v80 row_ror:2 row_mask:0xf bank_mask:0xf bound_ctrl:1
	v_mov_b32_dpp v123, v81 row_ror:1 row_mask:0xf bank_mask:0xf bound_ctrl:1
	v_mov_b32_dpp v125, v81 row_ror:2 row_mask:0xf bank_mask:0xf bound_ctrl:1
	v_mov_b32_dpp v127, v82 row_ror:1 row_mask:0xf bank_mask:0xf bound_ctrl:1
	v_mov_b32_dpp v133, v82 row_ror:2 row_mask:0xf bank_mask:0xf bound_ctrl:1
	v_mov_b32_dpp v134, v83 row_ror:1 row_mask:0xf bank_mask:0xf bound_ctrl:1
	v_mov_b32_dpp v135, v83 row_ror:2 row_mask:0xf bank_mask:0xf bound_ctrl:1
	ds_read_b128 v[206:209], v174
	ds_read_b128 v[210:213], v174 offset:1024
	ds_read_b128 v[214:217], v174 offset:2048
	ds_read_b128 v[218:221], v174 offset:3072
	v_mov_b32_dpp v93, v76 row_ror:2 row_mask:0xf bank_mask:0xf bound_ctrl:1
	v_mov_b32_dpp v89, v76 row_ror:1 row_mask:0xf bank_mask:0xf bound_ctrl:1
	v_cndmask_b32_e64 v93, v111, v93, s[40:41]
	v_cndmask_b32_e64 v92, v106, v92, s[40:41]
	s_waitcnt lgkmcnt(7)
	v_mov_b32_e32 v110, v84
	s_waitcnt lgkmcnt(3)
	v_mov_b32_e32 v111, v206
	v_mov_b32_e32 v112, v202
	s_waitcnt lgkmcnt(0)
	v_mov_b32_e32 v113, v218
	v_cndmask_b32_e64 v89, v182, v89, s[42:43]
	v_cndmask_b32_e64 v88, v108, v88, s[42:43]
	v_pk_fma_f32 v[92:93], v[110:111], v[92:93], v[112:113]
	v_mov_b32_e32 v110, v176
	v_mov_b32_e32 v111, v210
	v_pk_fma_f32 v[88:89], v[110:111], v[88:89], v[92:93]
	v_mov_b32_e32 v92, v80
	v_mov_b32_e32 v93, v76
	v_mov_b32_e32 v110, v184
	v_mov_b32_e32 v111, v214
	v_mov_b32_dpp v80, v77 row_ror:2 row_mask:0xf bank_mask:0xf bound_ctrl:1
	v_pk_fma_f32 v[88:89], v[92:93], v[110:111], v[88:89]
	v_mov_b32_dpp v76, v77 row_ror:1 row_mask:0xf bank_mask:0xf bound_ctrl:1
	v_cndmask_b32_e64 v92, v105, v123, s[42:43]
	v_cndmask_b32_e64 v105, v120, v80, s[40:41]
	v_cndmask_b32_e64 v104, v104, v125, s[40:41]
	v_mov_b32_e32 v206, v85
	v_mov_b32_e32 v218, v203
	v_cndmask_b32_e64 v93, v136, v76, s[42:43]
	v_pk_fma_f32 v[84:85], v[206:207], v[104:105], v[218:219]
	v_mov_b32_e32 v210, v177
	v_pk_fma_f32 v[84:85], v[210:211], v[92:93], v[84:85]
	v_mov_b32_e32 v76, v81
	v_mov_b32_e32 v214, v185
	v_pk_fma_f32 v[84:85], v[76:77], v[214:215], v[84:85]
	v_mov_b32_dpp v76, v78 row_ror:1 row_mask:0xf bank_mask:0xf bound_ctrl:1
	v_mov_b32_dpp v80, v78 row_ror:2 row_mask:0xf bank_mask:0xf bound_ctrl:1
	v_cndmask_b32_e64 v77, v131, v76, s[42:43]
	v_cndmask_b32_e64 v76, v103, v127, s[42:43]
	v_cndmask_b32_e64 v81, v121, v80, s[40:41]
	v_cndmask_b32_e64 v80, v102, v133, s[40:41]
	v_mov_b32_e32 v92, v86
	v_mov_b32_e32 v93, v208
	v_mov_b32_e32 v102, v204
	v_mov_b32_e32 v103, v220
	v_pk_fma_f32 v[80:81], v[92:93], v[80:81], v[102:103]
	v_mov_b32_e32 v92, v178
	v_mov_b32_e32 v93, v212
	v_pk_fma_f32 v[76:77], v[92:93], v[76:77], v[80:81]
	v_mov_b32_e32 v80, v82
	v_mov_b32_e32 v81, v78
	v_mov_b32_e32 v92, v186
	v_mov_b32_e32 v93, v216
	v_mov_b32_dpp v78, v79 row_ror:2 row_mask:0xf bank_mask:0xf bound_ctrl:1
	v_pk_fma_f32 v[80:81], v[80:81], v[92:93], v[76:77]
	v_mov_b32_dpp v76, v79 row_ror:1 row_mask:0xf bank_mask:0xf bound_ctrl:1
	v_cndmask_b32_e64 v93, v130, v78, s[40:41]
	v_cndmask_b32_e64 v92, v100, v135, s[40:41]
	v_mov_b32_e32 v208, v87
	v_mov_b32_e32 v220, v205
	v_cndmask_b32_e64 v77, v132, v76, s[42:43]
	v_cndmask_b32_e64 v76, v101, v134, s[42:43]
	v_pk_fma_f32 v[86:87], v[208:209], v[92:93], v[220:221]
	v_mov_b32_e32 v212, v179
	v_pk_fma_f32 v[76:77], v[212:213], v[76:77], v[86:87]
	v_mov_b32_e32 v78, v83
	v_mov_b32_e32 v216, v187
	v_pk_fma_f32 v[76:77], v[78:79], v[216:217], v[76:77]
	v_mul_f32_e32 v78, 0xbfb8aa3b, v88
	v_exp_f32_e32 v78, v78
	s_nop 0
	v_add_f32_e32 v78, 1.0, v78
	s_nop 0
	v_rcp_f32_e32 v78, v78
	v_mul_f32_e32 v79, 0xbfb8aa3b, v84
	v_exp_f32_e32 v79, v79
	v_mul_f32_e32 v78, v88, v78
	v_mul_f32_e32 v78, v78, v89
	v_add_f32_e32 v79, 1.0, v79
	s_nop 0
	v_rcp_f32_e32 v79, v79
	s_nop 0
	v_mul_f32_e32 v79, v84, v79
	v_mul_f32_e32 v79, v79, v85
	v_cvt_pk_bf16_f32 v78, v78, v79
	v_mul_f32_e32 v79, 0xbfb8aa3b, v80
	v_exp_f32_e32 v79, v79
	s_nop 0
	v_add_f32_e32 v79, 1.0, v79
	s_nop 0
	v_rcp_f32_e32 v79, v79
	s_nop 0
	v_mul_f32_e32 v79, v80, v79
	v_mul_f32_e32 v80, 0xbfb8aa3b, v76
	v_exp_f32_e32 v80, v80
	v_mul_f32_e32 v79, v79, v81
	v_add_f32_e32 v80, 1.0, v80
	s_nop 0
	v_rcp_f32_e32 v80, v80
	s_nop 0
	v_mul_f32_e32 v76, v76, v80
	v_mul_f32_e32 v76, v76, v77
	v_cvt_pk_bf16_f32 v79, v79, v76
	v_mad_i64_i32 v[76:77], s[0:1], v91, s2, v[118:119]
	v_lshl_add_u64 v[76:77], v[76:77], 0, v[116:117]
	global_store_dwordx2 v[76:77], v[78:79], off offset:2048
	ds_read_b128 v[78:81], v172 offset:16
	ds_read_b128 v[82:85], v172 offset:1040
	ds_read_b128 v[86:89], v172 offset:2064
	ds_read_b128 v[100:103], v172 offset:3088
	v_mov_b32_dpp v91, v72 row_ror:1 row_mask:0xf bank_mask:0xf bound_ctrl:1
	v_mov_b32_dpp v104, v72 row_ror:2 row_mask:0xf bank_mask:0xf bound_ctrl:1
	v_mov_b32_dpp v123, v73 row_ror:1 row_mask:0xf bank_mask:0xf bound_ctrl:1
	v_mov_b32_dpp v125, v73 row_ror:2 row_mask:0xf bank_mask:0xf bound_ctrl:1
	v_mov_b32_dpp v127, v74 row_ror:1 row_mask:0xf bank_mask:0xf bound_ctrl:1
	v_mov_b32_dpp v138, v74 row_ror:2 row_mask:0xf bank_mask:0xf bound_ctrl:1
	v_mov_b32_dpp v139, v75 row_ror:1 row_mask:0xf bank_mask:0xf bound_ctrl:1
	v_mov_b32_dpp v156, v75 row_ror:2 row_mask:0xf bank_mask:0xf bound_ctrl:1
	ds_read_b128 v[110:113], v172 offset:528
	ds_read_b128 v[118:121], v172 offset:1552
	ds_read_b128 v[130:133], v172 offset:2576
	ds_read_b128 v[134:137], v172 offset:3600
	v_mov_b32_dpp v92, v68 row_ror:1 row_mask:0xf bank_mask:0xf bound_ctrl:1
	v_mov_b32_dpp v105, v68 row_ror:2 row_mask:0xf bank_mask:0xf bound_ctrl:1
	v_cndmask_b32_e64 v93, v129, v92, s[42:43]
	v_cndmask_b32_e64 v92, v109, v91, s[42:43]
	v_cndmask_b32_e64 v105, v128, v105, s[40:41]
	v_cndmask_b32_e64 v104, v107, v104, s[40:41]
	s_waitcnt lgkmcnt(7)
	v_mov_b32_e32 v106, v78
	s_waitcnt lgkmcnt(3)
	v_mov_b32_e32 v107, v110
	v_mov_b32_e32 v108, v100
	s_waitcnt lgkmcnt(0)
	v_mov_b32_e32 v109, v134
	v_pk_fma_f32 v[104:105], v[106:107], v[104:105], v[108:109]
	v_mov_b32_e32 v106, v82
	v_mov_b32_e32 v107, v118
	v_pk_fma_f32 v[92:93], v[106:107], v[92:93], v[104:105]
	v_mov_b32_e32 v104, v72
	v_mov_b32_e32 v105, v68
	v_mov_b32_e32 v106, v86
	v_mov_b32_e32 v107, v130
	v_mov_b32_dpp v72, v69 row_ror:2 row_mask:0xf bank_mask:0xf bound_ctrl:1
	v_pk_fma_f32 v[92:93], v[104:105], v[106:107], v[92:93]
	v_mov_b32_dpp v68, v69 row_ror:1 row_mask:0xf bank_mask:0xf bound_ctrl:1
	v_cndmask_b32_e64 v104, v99, v123, s[42:43]
	v_cndmask_b32_e64 v99, v114, v72, s[40:41]
	v_cndmask_b32_e64 v98, v98, v125, s[40:41]
	v_mov_b32_e32 v110, v79
	v_mov_b32_e32 v134, v101
	v_cndmask_b32_e64 v105, v126, v68, s[42:43]
	v_pk_fma_f32 v[78:79], v[110:111], v[98:99], v[134:135]
	v_mov_b32_e32 v118, v83
	v_pk_fma_f32 v[78:79], v[118:119], v[104:105], v[78:79]
	v_mov_b32_e32 v68, v73
	v_mov_b32_e32 v130, v87
	v_mov_b32_dpp v72, v70 row_ror:2 row_mask:0xf bank_mask:0xf bound_ctrl:1
	v_pk_fma_f32 v[78:79], v[68:69], v[130:131], v[78:79]
	v_mov_b32_dpp v68, v70 row_ror:1 row_mask:0xf bank_mask:0xf bound_ctrl:1
	v_cndmask_b32_e64 v73, v115, v72, s[40:41]
	v_cndmask_b32_e64 v72, v96, v138, s[40:41]
	v_mov_b32_e32 v82, v80
	v_mov_b32_e32 v83, v112
	v_mov_b32_e32 v86, v102
	v_mov_b32_e32 v87, v136
	v_cndmask_b32_e64 v69, v124, v68, s[42:43]
	v_cndmask_b32_e64 v68, v97, v127, s[42:43]
	v_pk_fma_f32 v[72:73], v[82:83], v[72:73], v[86:87]
	v_mov_b32_e32 v82, v84
	v_mov_b32_e32 v83, v120
	v_pk_fma_f32 v[68:69], v[82:83], v[68:69], v[72:73]
	v_mov_b32_e32 v72, v74
	v_mov_b32_e32 v73, v70
	v_mov_b32_e32 v82, v88
	v_mov_b32_e32 v83, v132
	v_mov_b32_dpp v70, v71 row_ror:2 row_mask:0xf bank_mask:0xf bound_ctrl:1
	v_pk_fma_f32 v[72:73], v[72:73], v[82:83], v[68:69]
	v_mov_b32_dpp v68, v71 row_ror:1 row_mask:0xf bank_mask:0xf bound_ctrl:1
	v_cndmask_b32_e64 v83, v90, v70, s[40:41]
	v_cndmask_b32_e64 v82, v94, v156, s[40:41]
	v_mov_b32_e32 v112, v81
	v_mov_b32_e32 v136, v103
	v_cndmask_b32_e64 v69, v122, v68, s[42:43]
	v_cndmask_b32_e64 v68, v95, v139, s[42:43]
	v_pk_fma_f32 v[80:81], v[112:113], v[82:83], v[136:137]
	v_mov_b32_e32 v120, v85
	v_pk_fma_f32 v[68:69], v[120:121], v[68:69], v[80:81]
	v_mov_b32_e32 v70, v75
	v_mov_b32_e32 v132, v89
	v_pk_fma_f32 v[68:69], v[70:71], v[132:133], v[68:69]
	v_mul_f32_e32 v70, 0xbfb8aa3b, v92
	v_exp_f32_e32 v70, v70
	s_nop 0
	v_add_f32_e32 v70, 1.0, v70
	s_nop 0
	v_rcp_f32_e32 v70, v70
	v_mul_f32_e32 v71, 0xbfb8aa3b, v78
	v_exp_f32_e32 v71, v71
	v_mul_f32_e32 v70, v92, v70
	v_mul_f32_e32 v70, v70, v93
	v_add_f32_e32 v71, 1.0, v71
	s_nop 0
	v_rcp_f32_e32 v71, v71
	s_nop 0
	v_mul_f32_e32 v71, v78, v71
	v_mul_f32_e32 v71, v71, v79
	v_cvt_pk_bf16_f32 v70, v70, v71
	v_mul_f32_e32 v71, 0xbfb8aa3b, v72
	v_exp_f32_e32 v71, v71
	s_nop 0
	v_add_f32_e32 v71, 1.0, v71
	s_nop 0
	v_rcp_f32_e32 v71, v71
	s_nop 0
	v_mul_f32_e32 v71, v72, v71
	v_mul_f32_e32 v72, 0xbfb8aa3b, v68
	v_exp_f32_e32 v72, v72
	v_mul_f32_e32 v71, v71, v73
	v_add_f32_e32 v72, 1.0, v72
	s_nop 0
	v_rcp_f32_e32 v72, v72
	s_nop 0
	v_mul_f32_e32 v68, v68, v72
	v_mul_f32_e32 v68, v68, v69
	v_cvt_pk_bf16_f32 v71, v71, v68
	global_store_dwordx2 v[76:77], v[70:71], off offset:2056
	v_add_u32_e32 v68, 0x80, v173
	v_mad_i64_i32 v[76:77], s[0:1], v68, s2, 0
	ds_read_b128 v[72:75], v172
	ds_read_b128 v[78:81], v172 offset:1024
	ds_read_b128 v[82:85], v172 offset:2048
	ds_read_b128 v[68:71], v172 offset:3072
	v_mov_b32_dpp v87, v64 row_ror:2 row_mask:0xf bank_mask:0xf bound_ctrl:1
	v_mov_b32_dpp v91, v31 row_ror:2 row_mask:0xf bank_mask:0xf bound_ctrl:1
	v_mov_b32_dpp v86, v64 row_ror:1 row_mask:0xf bank_mask:0xf bound_ctrl:1
	v_mov_b32_dpp v90, v31 row_ror:1 row_mask:0xf bank_mask:0xf bound_ctrl:1
	v_cndmask_b32_e64 v87, v91, v87, s[40:41]
	v_cndmask_b32_e64 v86, v90, v86, s[42:43]
	s_waitcnt lgkmcnt(0)
	v_fma_f32 v68, v72, v87, v68
	v_fmac_f32_e32 v68, v78, v86
	v_mov_b32_dpp v78, v65 row_ror:2 row_mask:0xf bank_mask:0xf bound_ctrl:1
	v_mov_b32_dpp v72, v65 row_ror:1 row_mask:0xf bank_mask:0xf bound_ctrl:1
	v_cndmask_b32_e64 v78, v91, v78, s[40:41]
	v_cndmask_b32_e64 v72, v90, v72, s[42:43]
	v_fma_f32 v69, v73, v78, v69
	v_mov_b32_dpp v73, v66 row_ror:2 row_mask:0xf bank_mask:0xf bound_ctrl:1
	v_fmac_f32_e32 v69, v79, v72
	v_mov_b32_dpp v72, v66 row_ror:1 row_mask:0xf bank_mask:0xf bound_ctrl:1
	v_cndmask_b32_e64 v73, v91, v73, s[40:41]
	v_cndmask_b32_e64 v72, v90, v72, s[42:43]
	v_fma_f32 v70, v74, v73, v70
	v_mov_b32_dpp v73, v67 row_ror:2 row_mask:0xf bank_mask:0xf bound_ctrl:1
	v_fmac_f32_e32 v70, v80, v72
	v_mov_b32_dpp v72, v67 row_ror:1 row_mask:0xf bank_mask:0xf bound_ctrl:1
	v_cndmask_b32_e64 v73, v91, v73, s[40:41]
	v_cndmask_b32_e64 v72, v90, v72, s[42:43]
	v_fmac_f32_e32 v71, v75, v73
	v_fmac_f32_e32 v68, v64, v82
	v_fmac_f32_e32 v69, v65, v83
	v_fmac_f32_e32 v71, v81, v72
	v_fmac_f32_e32 v70, v66, v84
	v_fmac_f32_e32 v71, v67, v85
	ds_read_b128 v[78:81], v174
	ds_read_b128 v[82:85], v174 offset:1024
	ds_read_b128 v[86:89], v174 offset:2048
	ds_read_b128 v[72:75], v174 offset:3072
	v_mov_b32_dpp v93, v56 row_ror:2 row_mask:0xf bank_mask:0xf bound_ctrl:1
	v_mov_b32_dpp v92, v56 row_ror:1 row_mask:0xf bank_mask:0xf bound_ctrl:1
	v_cndmask_b32_e64 v93, v91, v93, s[40:41]
	v_cndmask_b32_e64 v92, v90, v92, s[42:43]
	s_waitcnt lgkmcnt(0)
	v_fma_f32 v72, v78, v93, v72
	v_fmac_f32_e32 v72, v82, v92
	v_mov_b32_dpp v82, v57 row_ror:2 row_mask:0xf bank_mask:0xf bound_ctrl:1
	v_mov_b32_dpp v78, v57 row_ror:1 row_mask:0xf bank_mask:0xf bound_ctrl:1
	v_cndmask_b32_e64 v82, v91, v82, s[40:41]
	v_cndmask_b32_e64 v78, v90, v78, s[42:43]
	v_fma_f32 v73, v79, v82, v73
	v_mov_b32_dpp v79, v58 row_ror:2 row_mask:0xf bank_mask:0xf bound_ctrl:1
	v_fmac_f32_e32 v73, v83, v78
	v_mov_b32_dpp v78, v58 row_ror:1 row_mask:0xf bank_mask:0xf bound_ctrl:1
	v_cndmask_b32_e64 v79, v91, v79, s[40:41]
	v_cndmask_b32_e64 v78, v90, v78, s[42:43]
	v_fma_f32 v74, v80, v79, v74
	v_mov_b32_dpp v79, v59 row_ror:2 row_mask:0xf bank_mask:0xf bound_ctrl:1
	v_fmac_f32_e32 v74, v84, v78
	v_mov_b32_dpp v78, v59 row_ror:1 row_mask:0xf bank_mask:0xf bound_ctrl:1
	v_cndmask_b32_e64 v79, v91, v79, s[40:41]
	v_cndmask_b32_e64 v78, v90, v78, s[42:43]
	v_fmac_f32_e32 v75, v81, v79
	v_fmac_f32_e32 v75, v85, v78
	v_fmac_f32_e32 v72, v56, v86
	v_fmac_f32_e32 v73, v57, v87
	v_fmac_f32_e32 v74, v58, v88
	v_fmac_f32_e32 v75, v59, v89
	v_mul_f32_e32 v78, 0xbfb8aa3b, v68
	v_exp_f32_e32 v78, v78
	s_nop 0
	v_add_f32_e32 v78, 1.0, v78
	s_nop 0
	v_rcp_f32_e32 v78, v78
	s_nop 0
	v_mul_f32_e32 v68, v68, v78
	v_mul_f32_e32 v68, v68, v72
	v_mul_f32_e32 v72, 0xbfb8aa3b, v69
	v_exp_f32_e32 v72, v72
	s_nop 0
	v_add_f32_e32 v72, 1.0, v72
	s_nop 0
	v_rcp_f32_e32 v72, v72
	s_nop 0
	v_mul_f32_e32 v69, v69, v72
	v_mul_f32_e32 v69, v69, v73
	v_cvt_pk_bf16_f32 v68, v68, v69
	v_mul_f32_e32 v69, 0xbfb8aa3b, v70
	v_exp_f32_e32 v69, v69
	s_nop 0
	v_add_f32_e32 v69, 1.0, v69
	s_nop 0
	v_rcp_f32_e32 v69, v69
	s_nop 0
	v_mul_f32_e32 v69, v70, v69
	v_mul_f32_e32 v70, 0xbfb8aa3b, v71
	v_exp_f32_e32 v70, v70
	v_mul_f32_e32 v69, v69, v74
	v_add_f32_e32 v70, 1.0, v70
	s_nop 0
	v_rcp_f32_e32 v70, v70
	s_nop 0
	v_mul_f32_e32 v70, v71, v70
	v_mul_f32_e32 v70, v70, v75
	v_cvt_pk_bf16_f32 v69, v69, v70
	v_lshl_add_u64 v[70:71], s[34:35], 0, v[76:77]
	v_lshl_add_u64 v[76:77], v[164:165], 1, v[70:71]
	s_and_saveexec_b64 s[0:1], s[44:45]
	s_cbranch_execz .LBB0_253
	global_store_dwordx2 v[76:77], v[68:69], off offset:2048
.LBB0_253:
	s_or_b64 exec, exec, s[0:1]
	ds_read_b128 v[72:75], v172 offset:16
	ds_read_b128 v[78:81], v172 offset:1040
	ds_read_b128 v[82:85], v172 offset:2064
	ds_read_b128 v[68:71], v172 offset:3088
	v_mov_b32_dpp v87, v48 row_ror:2 row_mask:0xf bank_mask:0xf bound_ctrl:1
	v_mov_b32_dpp v91, v31 row_ror:2 row_mask:0xf bank_mask:0xf bound_ctrl:1
	v_mov_b32_dpp v86, v48 row_ror:1 row_mask:0xf bank_mask:0xf bound_ctrl:1
	v_mov_b32_dpp v90, v31 row_ror:1 row_mask:0xf bank_mask:0xf bound_ctrl:1
	v_cndmask_b32_e64 v87, v91, v87, s[40:41]
	v_cndmask_b32_e64 v86, v90, v86, s[42:43]
	s_waitcnt lgkmcnt(0)
	v_fma_f32 v68, v72, v87, v68
	v_fmac_f32_e32 v68, v78, v86
	v_mov_b32_dpp v78, v49 row_ror:2 row_mask:0xf bank_mask:0xf bound_ctrl:1
	v_mov_b32_dpp v72, v49 row_ror:1 row_mask:0xf bank_mask:0xf bound_ctrl:1
	v_cndmask_b32_e64 v78, v91, v78, s[40:41]
	v_cndmask_b32_e64 v72, v90, v72, s[42:43]
	v_fma_f32 v69, v73, v78, v69
	v_mov_b32_dpp v73, v50 row_ror:2 row_mask:0xf bank_mask:0xf bound_ctrl:1
	v_fmac_f32_e32 v69, v79, v72
	v_mov_b32_dpp v72, v50 row_ror:1 row_mask:0xf bank_mask:0xf bound_ctrl:1
	v_cndmask_b32_e64 v73, v91, v73, s[40:41]
	v_cndmask_b32_e64 v72, v90, v72, s[42:43]
	v_fma_f32 v70, v74, v73, v70
	v_mov_b32_dpp v73, v51 row_ror:2 row_mask:0xf bank_mask:0xf bound_ctrl:1
	v_fmac_f32_e32 v70, v80, v72
	v_mov_b32_dpp v72, v51 row_ror:1 row_mask:0xf bank_mask:0xf bound_ctrl:1
	v_cndmask_b32_e64 v73, v91, v73, s[40:41]
	v_cndmask_b32_e64 v72, v90, v72, s[42:43]
	v_fmac_f32_e32 v71, v75, v73
	v_fmac_f32_e32 v68, v48, v82
	v_fmac_f32_e32 v69, v49, v83
	v_fmac_f32_e32 v71, v81, v72
	v_fmac_f32_e32 v70, v50, v84
	v_fmac_f32_e32 v71, v51, v85
	ds_read_b128 v[78:81], v172 offset:528
	ds_read_b128 v[82:85], v172 offset:1552
	ds_read_b128 v[86:89], v172 offset:2576
	ds_read_b128 v[72:75], v172 offset:3600
	v_mov_b32_dpp v93, v40 row_ror:2 row_mask:0xf bank_mask:0xf bound_ctrl:1
	v_mov_b32_dpp v92, v40 row_ror:1 row_mask:0xf bank_mask:0xf bound_ctrl:1
	v_cndmask_b32_e64 v93, v91, v93, s[40:41]
	v_cndmask_b32_e64 v92, v90, v92, s[42:43]
	s_waitcnt lgkmcnt(0)
	v_fma_f32 v72, v78, v93, v72
	v_fmac_f32_e32 v72, v82, v92
	v_mov_b32_dpp v82, v41 row_ror:2 row_mask:0xf bank_mask:0xf bound_ctrl:1
	v_mov_b32_dpp v78, v41 row_ror:1 row_mask:0xf bank_mask:0xf bound_ctrl:1
	v_cndmask_b32_e64 v82, v91, v82, s[40:41]
	v_cndmask_b32_e64 v78, v90, v78, s[42:43]
	v_fma_f32 v73, v79, v82, v73
	v_mov_b32_dpp v79, v42 row_ror:2 row_mask:0xf bank_mask:0xf bound_ctrl:1
	v_fmac_f32_e32 v73, v83, v78
	v_mov_b32_dpp v78, v42 row_ror:1 row_mask:0xf bank_mask:0xf bound_ctrl:1
	v_cndmask_b32_e64 v79, v91, v79, s[40:41]
	v_cndmask_b32_e64 v78, v90, v78, s[42:43]
	v_fma_f32 v74, v80, v79, v74
	v_mov_b32_dpp v79, v43 row_ror:2 row_mask:0xf bank_mask:0xf bound_ctrl:1
	v_fmac_f32_e32 v74, v84, v78
	v_mov_b32_dpp v78, v43 row_ror:1 row_mask:0xf bank_mask:0xf bound_ctrl:1
	v_cndmask_b32_e64 v79, v91, v79, s[40:41]
	v_cndmask_b32_e64 v78, v90, v78, s[42:43]
	v_fmac_f32_e32 v75, v81, v79
	v_fmac_f32_e32 v75, v85, v78
	v_fmac_f32_e32 v72, v40, v86
	v_fmac_f32_e32 v73, v41, v87
	v_fmac_f32_e32 v74, v42, v88
	v_fmac_f32_e32 v75, v43, v89
	v_mul_f32_e32 v78, 0xbfb8aa3b, v68
	v_exp_f32_e32 v78, v78
	s_nop 0
	v_add_f32_e32 v78, 1.0, v78
	s_nop 0
	v_rcp_f32_e32 v78, v78
	s_nop 0
	v_mul_f32_e32 v68, v68, v78
	v_mul_f32_e32 v68, v68, v72
	v_mul_f32_e32 v72, 0xbfb8aa3b, v69
	v_exp_f32_e32 v72, v72
	s_nop 0
	v_add_f32_e32 v72, 1.0, v72
	s_nop 0
	v_rcp_f32_e32 v72, v72
	s_nop 0
	v_mul_f32_e32 v69, v69, v72
	v_mul_f32_e32 v69, v69, v73
	v_cvt_pk_bf16_f32 v68, v68, v69
	v_mul_f32_e32 v69, 0xbfb8aa3b, v70
	v_exp_f32_e32 v69, v69
	s_nop 0
	v_add_f32_e32 v69, 1.0, v69
	s_nop 0
	v_rcp_f32_e32 v69, v69
	s_nop 0
	v_mul_f32_e32 v69, v70, v69
	v_mul_f32_e32 v70, 0xbfb8aa3b, v71
	v_exp_f32_e32 v70, v70
	v_mul_f32_e32 v69, v69, v74
	v_add_f32_e32 v70, 1.0, v70
	s_nop 0
	v_rcp_f32_e32 v70, v70
	s_nop 0
	v_mul_f32_e32 v70, v71, v70
	v_mul_f32_e32 v70, v70, v75
	v_cvt_pk_bf16_f32 v69, v69, v70
	s_and_saveexec_b64 s[0:1], s[44:45]
	s_cbranch_execz .LBB0_255
	global_store_dwordx2 v[76:77], v[68:69], off offset:2056
.LBB0_255:
	s_or_b64 exec, exec, s[0:1]
	ds_read_b128 v[76:79], v172
	ds_read_b128 v[80:83], v172 offset:1024
	ds_read_b128 v[84:87], v172 offset:2048
	ds_read_b128 v[88:91], v172 offset:3072
	v_add_u32_e32 v118, 0x90, v173
	v_mov_b32_dpp v73, v60 row_ror:1 row_mask:0xf bank_mask:0xf bound_ctrl:1
	v_mov_b32_dpp v72, v60 row_ror:2 row_mask:0xf bank_mask:0xf bound_ctrl:1
	v_mov_b32_dpp v75, v64 row_ror:1 row_mask:0xf bank_mask:0xf bound_ctrl:1
	v_mov_b32_dpp v110, v64 row_ror:2 row_mask:0xf bank_mask:0xf bound_ctrl:1
	v_mov_b32_dpp v71, v61 row_ror:1 row_mask:0xf bank_mask:0xf bound_ctrl:1
	v_mov_b32_dpp v70, v61 row_ror:2 row_mask:0xf bank_mask:0xf bound_ctrl:1
	v_mov_b32_dpp v119, v65 row_ror:1 row_mask:0xf bank_mask:0xf bound_ctrl:1
	v_mov_b32_dpp v120, v65 row_ror:2 row_mask:0xf bank_mask:0xf bound_ctrl:1
	v_mov_b32_dpp v69, v62 row_ror:1 row_mask:0xf bank_mask:0xf bound_ctrl:1
	v_mov_b32_dpp v68, v62 row_ror:2 row_mask:0xf bank_mask:0xf bound_ctrl:1
	v_mov_b32_dpp v121, v66 row_ror:1 row_mask:0xf bank_mask:0xf bound_ctrl:1
	v_mov_b32_dpp v122, v66 row_ror:2 row_mask:0xf bank_mask:0xf bound_ctrl:1
	v_mov_b32_dpp v65, v63 row_ror:1 row_mask:0xf bank_mask:0xf bound_ctrl:1
	v_mov_b32_dpp v64, v63 row_ror:2 row_mask:0xf bank_mask:0xf bound_ctrl:1
	v_mov_b32_dpp v123, v67 row_ror:1 row_mask:0xf bank_mask:0xf bound_ctrl:1
	v_mov_b32_dpp v124, v67 row_ror:2 row_mask:0xf bank_mask:0xf bound_ctrl:1
	ds_read_b128 v[92:95], v174
	ds_read_b128 v[96:99], v174 offset:1024
	ds_read_b128 v[100:103], v174 offset:2048
	ds_read_b128 v[104:107], v174 offset:3072
	v_mov_b32_dpp v66, v52 row_ror:2 row_mask:0xf bank_mask:0xf bound_ctrl:1
	v_mov_b32_dpp v67, v56 row_ror:1 row_mask:0xf bank_mask:0xf bound_ctrl:1
	v_mov_b32_dpp v56, v56 row_ror:2 row_mask:0xf bank_mask:0xf bound_ctrl:1
	v_mov_b32_dpp v74, v52 row_ror:1 row_mask:0xf bank_mask:0xf bound_ctrl:1
	v_cndmask_b32_e64 v111, v56, v66, s[40:41]
	v_cndmask_b32_e64 v110, v110, v72, s[40:41]
	s_waitcnt lgkmcnt(7)
	v_mov_b32_e32 v112, v76
	s_waitcnt lgkmcnt(3)
	v_mov_b32_e32 v113, v92
	v_mov_b32_e32 v114, v88
	s_waitcnt lgkmcnt(0)
	v_mov_b32_e32 v115, v104
	v_cndmask_b32_e64 v109, v67, v74, s[42:43]
	v_cndmask_b32_e64 v108, v75, v73, s[42:43]
	v_pk_fma_f32 v[110:111], v[112:113], v[110:111], v[114:115]
	v_mov_b32_e32 v112, v80
	v_mov_b32_e32 v113, v96
	v_pk_fma_f32 v[108:109], v[112:113], v[108:109], v[110:111]
	v_mov_b32_e32 v110, v60
	v_mov_b32_e32 v111, v52
	v_mov_b32_e32 v112, v84
	v_mov_b32_e32 v113, v100
	v_mov_b32_dpp v67, v53 row_ror:2 row_mask:0xf bank_mask:0xf bound_ctrl:1
	v_mov_b32_dpp v60, v57 row_ror:2 row_mask:0xf bank_mask:0xf bound_ctrl:1
	v_pk_fma_f32 v[108:109], v[110:111], v[112:113], v[108:109]
	v_mov_b32_dpp v76, v53 row_ror:1 row_mask:0xf bank_mask:0xf bound_ctrl:1
	v_mov_b32_dpp v52, v57 row_ror:1 row_mask:0xf bank_mask:0xf bound_ctrl:1
	v_cndmask_b32_e64 v111, v60, v67, s[40:41]
	v_cndmask_b32_e64 v110, v120, v70, s[40:41]
	v_mov_b32_e32 v92, v77
	v_mov_b32_e32 v104, v89
	v_cndmask_b32_e64 v57, v52, v76, s[42:43]
	v_cndmask_b32_e64 v56, v119, v71, s[42:43]
	v_pk_fma_f32 v[88:89], v[92:93], v[110:111], v[104:105]
	v_mov_b32_e32 v96, v81
	v_pk_fma_f32 v[56:57], v[96:97], v[56:57], v[88:89]
	v_mov_b32_e32 v52, v61
	v_mov_b32_e32 v100, v85
	v_pk_fma_f32 v[60:61], v[52:53], v[100:101], v[56:57]
	v_mov_b32_dpp v75, v54 row_ror:2 row_mask:0xf bank_mask:0xf bound_ctrl:1
	v_mov_b32_dpp v56, v58 row_ror:2 row_mask:0xf bank_mask:0xf bound_ctrl:1
	v_mov_b32_dpp v77, v54 row_ror:1 row_mask:0xf bank_mask:0xf bound_ctrl:1
	v_mov_b32_dpp v52, v58 row_ror:1 row_mask:0xf bank_mask:0xf bound_ctrl:1
	v_cndmask_b32_e64 v57, v56, v75, s[40:41]
	v_cndmask_b32_e64 v56, v122, v68, s[40:41]
	v_mov_b32_e32 v80, v78
	v_mov_b32_e32 v81, v94
	v_mov_b32_e32 v84, v90
	v_mov_b32_e32 v85, v106
	v_cndmask_b32_e64 v53, v52, v77, s[42:43]
	v_cndmask_b32_e64 v52, v121, v69, s[42:43]
	v_pk_fma_f32 v[56:57], v[80:81], v[56:57], v[84:85]
	v_mov_b32_e32 v80, v82
	v_mov_b32_e32 v81, v98
	v_pk_fma_f32 v[52:53], v[80:81], v[52:53], v[56:57]
	v_mov_b32_e32 v56, v62
	v_mov_b32_e32 v57, v54
	v_mov_b32_e32 v80, v86
	v_mov_b32_e32 v81, v102
	v_mov_b32_dpp v62, v55 row_ror:2 row_mask:0xf bank_mask:0xf bound_ctrl:1
	v_mov_b32_dpp v54, v59 row_ror:2 row_mask:0xf bank_mask:0xf bound_ctrl:1
	v_pk_fma_f32 v[56:57], v[56:57], v[80:81], v[52:53]
	v_mov_b32_dpp v78, v55 row_ror:1 row_mask:0xf bank_mask:0xf bound_ctrl:1
	v_mov_b32_dpp v52, v59 row_ror:1 row_mask:0xf bank_mask:0xf bound_ctrl:1
	v_cndmask_b32_e64 v59, v54, v62, s[40:41]
	v_cndmask_b32_e64 v58, v124, v64, s[40:41]
	v_mov_b32_e32 v94, v79
	v_mov_b32_e32 v106, v91
	v_cndmask_b32_e64 v53, v52, v78, s[42:43]
	v_cndmask_b32_e64 v52, v123, v65, s[42:43]
	v_pk_fma_f32 v[58:59], v[94:95], v[58:59], v[106:107]
	v_mov_b32_e32 v98, v83
	v_pk_fma_f32 v[52:53], v[98:99], v[52:53], v[58:59]
	v_mov_b32_e32 v54, v63
	v_mov_b32_e32 v102, v87
	v_pk_fma_f32 v[52:53], v[54:55], v[102:103], v[52:53]
	v_mul_f32_e32 v54, 0xbfb8aa3b, v108
	v_exp_f32_e32 v54, v54
	s_nop 0
	v_add_f32_e32 v54, 1.0, v54
	s_nop 0
	v_rcp_f32_e32 v54, v54
	v_mul_f32_e32 v55, 0xbfb8aa3b, v60
	v_exp_f32_e32 v55, v55
	v_mul_f32_e32 v54, v108, v54
	v_mul_f32_e32 v54, v54, v109
	v_add_f32_e32 v55, 1.0, v55
	s_nop 0
	v_rcp_f32_e32 v55, v55
	s_nop 0
	v_mul_f32_e32 v55, v60, v55
	v_mul_f32_e32 v55, v55, v61
	v_cvt_pk_bf16_f32 v58, v54, v55
	v_mul_f32_e32 v54, 0xbfb8aa3b, v56
	v_exp_f32_e32 v54, v54
	s_nop 0
	v_add_f32_e32 v54, 1.0, v54
	s_nop 0
	v_rcp_f32_e32 v54, v54
	v_mul_f32_e32 v55, 0xbfb8aa3b, v52
	v_exp_f32_e32 v55, v55
	v_mul_f32_e32 v54, v56, v54
	v_mul_f32_e32 v54, v54, v57
	v_add_f32_e32 v55, 1.0, v55
	s_nop 0
	v_rcp_f32_e32 v55, v55
	s_nop 0
	v_mul_f32_e32 v52, v52, v55
	v_mul_f32_e32 v52, v52, v53
	v_cvt_pk_bf16_f32 v59, v54, v52
	v_mov_b64_e32 v[52:53], s[34:35]
	v_mad_i64_i32 v[54:55], s[0:1], v118, s2, v[52:53]
	v_lshl_add_u64 v[54:55], v[54:55], 0, v[116:117]
	global_store_dwordx2 v[54:55], v[58:59], off offset:2048
	ds_read_b128 v[80:83], v172 offset:16
	ds_read_b128 v[84:87], v172 offset:1040
	ds_read_b128 v[88:91], v172 offset:2064
	ds_read_b128 v[92:95], v172 offset:3088
	v_mov_b32_dpp v61, v44 row_ror:1 row_mask:0xf bank_mask:0xf bound_ctrl:1
	v_mov_b32_dpp v60, v44 row_ror:2 row_mask:0xf bank_mask:0xf bound_ctrl:1
	v_mov_b32_dpp v79, v48 row_ror:1 row_mask:0xf bank_mask:0xf bound_ctrl:1
	v_mov_b32_dpp v114, v48 row_ror:2 row_mask:0xf bank_mask:0xf bound_ctrl:1
	v_mov_b32_dpp v59, v45 row_ror:1 row_mask:0xf bank_mask:0xf bound_ctrl:1
	v_mov_b32_dpp v58, v45 row_ror:2 row_mask:0xf bank_mask:0xf bound_ctrl:1
	v_mov_b32_dpp v122, v49 row_ror:1 row_mask:0xf bank_mask:0xf bound_ctrl:1
	v_mov_b32_dpp v123, v49 row_ror:2 row_mask:0xf bank_mask:0xf bound_ctrl:1
	v_mov_b32_dpp v57, v46 row_ror:1 row_mask:0xf bank_mask:0xf bound_ctrl:1
	v_mov_b32_dpp v56, v46 row_ror:2 row_mask:0xf bank_mask:0xf bound_ctrl:1
	v_mov_b32_dpp v124, v50 row_ror:1 row_mask:0xf bank_mask:0xf bound_ctrl:1
	v_mov_b32_dpp v125, v50 row_ror:2 row_mask:0xf bank_mask:0xf bound_ctrl:1
	v_mov_b32_dpp v49, v47 row_ror:1 row_mask:0xf bank_mask:0xf bound_ctrl:1
	v_mov_b32_dpp v48, v47 row_ror:2 row_mask:0xf bank_mask:0xf bound_ctrl:1
	v_mov_b32_dpp v126, v51 row_ror:1 row_mask:0xf bank_mask:0xf bound_ctrl:1
	v_mov_b32_dpp v127, v51 row_ror:2 row_mask:0xf bank_mask:0xf bound_ctrl:1
	ds_read_b128 v[96:99], v172 offset:528
	ds_read_b128 v[100:103], v172 offset:1552
	ds_read_b128 v[104:107], v172 offset:2576
	ds_read_b128 v[108:111], v172 offset:3600
	v_mov_b32_dpp v50, v36 row_ror:2 row_mask:0xf bank_mask:0xf bound_ctrl:1
	v_mov_b32_dpp v51, v40 row_ror:1 row_mask:0xf bank_mask:0xf bound_ctrl:1
	v_mov_b32_dpp v40, v40 row_ror:2 row_mask:0xf bank_mask:0xf bound_ctrl:1
	v_mov_b32_dpp v63, v36 row_ror:1 row_mask:0xf bank_mask:0xf bound_ctrl:1
	v_cndmask_b32_e64 v115, v40, v50, s[40:41]
	v_cndmask_b32_e64 v114, v114, v60, s[40:41]
	s_waitcnt lgkmcnt(7)
	v_mov_b32_e32 v118, v80
	s_waitcnt lgkmcnt(3)
	v_mov_b32_e32 v119, v96
	v_mov_b32_e32 v120, v92
	s_waitcnt lgkmcnt(0)
	v_mov_b32_e32 v121, v108
	v_cndmask_b32_e64 v113, v51, v63, s[42:43]
	v_cndmask_b32_e64 v112, v79, v61, s[42:43]
	v_pk_fma_f32 v[114:115], v[118:119], v[114:115], v[120:121]
	v_mov_b32_e32 v118, v84
	v_mov_b32_e32 v119, v100
	v_pk_fma_f32 v[112:113], v[118:119], v[112:113], v[114:115]
	v_mov_b32_e32 v114, v44
	v_mov_b32_e32 v115, v36
	v_mov_b32_e32 v118, v88
	v_mov_b32_e32 v119, v104
	v_mov_b32_dpp v51, v37 row_ror:2 row_mask:0xf bank_mask:0xf bound_ctrl:1
	v_mov_b32_dpp v44, v41 row_ror:2 row_mask:0xf bank_mask:0xf bound_ctrl:1
	v_pk_fma_f32 v[112:113], v[114:115], v[118:119], v[112:113]
	v_mov_b32_dpp v80, v37 row_ror:1 row_mask:0xf bank_mask:0xf bound_ctrl:1
	v_mov_b32_dpp v36, v41 row_ror:1 row_mask:0xf bank_mask:0xf bound_ctrl:1
	v_cndmask_b32_e64 v115, v44, v51, s[40:41]
	v_cndmask_b32_e64 v114, v123, v58, s[40:41]
	v_mov_b32_e32 v96, v81
	v_mov_b32_e32 v108, v93
	v_cndmask_b32_e64 v41, v36, v80, s[42:43]
	v_cndmask_b32_e64 v40, v122, v59, s[42:43]
	v_pk_fma_f32 v[92:93], v[96:97], v[114:115], v[108:109]
	v_mov_b32_e32 v100, v85
	v_pk_fma_f32 v[40:41], v[100:101], v[40:41], v[92:93]
	v_mov_b32_e32 v36, v45
	v_mov_b32_e32 v104, v89
	v_pk_fma_f32 v[44:45], v[36:37], v[104:105], v[40:41]
	v_mov_b32_dpp v79, v38 row_ror:2 row_mask:0xf bank_mask:0xf bound_ctrl:1
	v_mov_b32_dpp v40, v42 row_ror:2 row_mask:0xf bank_mask:0xf bound_ctrl:1
	v_mov_b32_dpp v81, v38 row_ror:1 row_mask:0xf bank_mask:0xf bound_ctrl:1
	v_mov_b32_dpp v36, v42 row_ror:1 row_mask:0xf bank_mask:0xf bound_ctrl:1
	v_cndmask_b32_e64 v41, v40, v79, s[40:41]
	v_cndmask_b32_e64 v40, v125, v56, s[40:41]
	v_mov_b32_e32 v84, v82
	v_mov_b32_e32 v85, v98
	v_mov_b32_e32 v88, v94
	v_mov_b32_e32 v89, v110
	v_cndmask_b32_e64 v37, v36, v81, s[42:43]
	v_cndmask_b32_e64 v36, v124, v57, s[42:43]
	v_pk_fma_f32 v[40:41], v[84:85], v[40:41], v[88:89]
	v_mov_b32_e32 v84, v86
	v_mov_b32_e32 v85, v102
	v_pk_fma_f32 v[36:37], v[84:85], v[36:37], v[40:41]
	v_mov_b32_e32 v40, v46
	v_mov_b32_e32 v41, v38
	v_mov_b32_e32 v84, v90
	v_mov_b32_e32 v85, v106
	v_mov_b32_dpp v46, v39 row_ror:2 row_mask:0xf bank_mask:0xf bound_ctrl:1
	v_mov_b32_dpp v38, v43 row_ror:2 row_mask:0xf bank_mask:0xf bound_ctrl:1
	v_pk_fma_f32 v[40:41], v[40:41], v[84:85], v[36:37]
	v_mov_b32_dpp v82, v39 row_ror:1 row_mask:0xf bank_mask:0xf bound_ctrl:1
	v_mov_b32_dpp v36, v43 row_ror:1 row_mask:0xf bank_mask:0xf bound_ctrl:1
	v_cndmask_b32_e64 v43, v38, v46, s[40:41]
	v_cndmask_b32_e64 v42, v127, v48, s[40:41]
	v_mov_b32_e32 v98, v83
	v_mov_b32_e32 v110, v95
	v_cndmask_b32_e64 v37, v36, v82, s[42:43]
	v_cndmask_b32_e64 v36, v126, v49, s[42:43]
	v_pk_fma_f32 v[42:43], v[98:99], v[42:43], v[110:111]
	v_mov_b32_e32 v102, v87
	v_pk_fma_f32 v[36:37], v[102:103], v[36:37], v[42:43]
	v_mov_b32_e32 v38, v47
	v_mov_b32_e32 v106, v91
	v_pk_fma_f32 v[36:37], v[38:39], v[106:107], v[36:37]
	v_mul_f32_e32 v38, 0xbfb8aa3b, v112
	v_exp_f32_e32 v38, v38
	s_nop 0
	v_add_f32_e32 v38, 1.0, v38
	s_nop 0
	v_rcp_f32_e32 v38, v38
	v_mul_f32_e32 v39, 0xbfb8aa3b, v44
	v_exp_f32_e32 v39, v39
	v_mul_f32_e32 v38, v112, v38
	v_mul_f32_e32 v38, v38, v113
	v_add_f32_e32 v39, 1.0, v39
	s_nop 0
	v_rcp_f32_e32 v39, v39
	s_nop 0
	v_mul_f32_e32 v39, v44, v39
	v_mul_f32_e32 v39, v39, v45
	v_cvt_pk_bf16_f32 v38, v38, v39
	v_mul_f32_e32 v39, 0xbfb8aa3b, v40
	v_exp_f32_e32 v39, v39
	s_nop 0
	v_add_f32_e32 v39, 1.0, v39
	s_nop 0
	v_rcp_f32_e32 v39, v39
	s_nop 0
	v_mul_f32_e32 v39, v40, v39
	v_mul_f32_e32 v40, 0xbfb8aa3b, v36
	v_exp_f32_e32 v40, v40
	v_mul_f32_e32 v39, v39, v41
	v_add_f32_e32 v40, 1.0, v40
	s_nop 0
	v_rcp_f32_e32 v40, v40
	s_nop 0
	v_mul_f32_e32 v36, v36, v40
	v_mul_f32_e32 v36, v36, v37
	v_cvt_pk_bf16_f32 v39, v39, v36
	global_store_dwordx2 v[54:55], v[38:39], off offset:2056
	ds_read_b128 v[84:87], v172
	ds_read_b128 v[88:91], v172 offset:1024
	ds_read_b128 v[92:95], v172 offset:2048
	ds_read_b128 v[96:99], v172 offset:3072
	v_add_u32_e32 v42, 0xa0, v173
	v_mov_b32_dpp v45, v32 row_ror:1 row_mask:0xf bank_mask:0xf bound_ctrl:1
	v_mov_b32_dpp v43, v32 row_ror:2 row_mask:0xf bank_mask:0xf bound_ctrl:1
	v_mov_b32_dpp v41, v33 row_ror:1 row_mask:0xf bank_mask:0xf bound_ctrl:1
	v_mov_b32_dpp v40, v33 row_ror:2 row_mask:0xf bank_mask:0xf bound_ctrl:1
	v_mov_b32_dpp v39, v34 row_ror:1 row_mask:0xf bank_mask:0xf bound_ctrl:1
	v_mov_b32_dpp v38, v34 row_ror:2 row_mask:0xf bank_mask:0xf bound_ctrl:1
	v_mov_b32_dpp v37, v35 row_ror:1 row_mask:0xf bank_mask:0xf bound_ctrl:1
	v_mov_b32_dpp v36, v35 row_ror:2 row_mask:0xf bank_mask:0xf bound_ctrl:1
	ds_read_b128 v[100:103], v174
	ds_read_b128 v[104:107], v174 offset:1024
	ds_read_b128 v[108:111], v174 offset:2048
	ds_read_b128 v[112:115], v174 offset:3072
	v_mov_b32_dpp v54, v24 row_ror:2 row_mask:0xf bank_mask:0xf bound_ctrl:1
	v_mov_b32_dpp v83, v24 row_ror:1 row_mask:0xf bank_mask:0xf bound_ctrl:1
	v_cndmask_b32_e64 v118, v73, v45, s[42:43]
	v_cndmask_b32_e64 v73, v66, v54, s[40:41]
	v_cndmask_b32_e64 v72, v72, v43, s[40:41]
	s_waitcnt lgkmcnt(7)
	v_mov_b32_e32 v120, v84
	s_waitcnt lgkmcnt(3)
	v_mov_b32_e32 v121, v100
	v_mov_b32_e32 v122, v96
	s_waitcnt lgkmcnt(0)
	v_mov_b32_e32 v123, v112
	v_cndmask_b32_e64 v119, v74, v83, s[42:43]
	v_pk_fma_f32 v[72:73], v[120:121], v[72:73], v[122:123]
	v_mov_b32_e32 v120, v88
	v_mov_b32_e32 v121, v104
	v_pk_fma_f32 v[72:73], v[120:121], v[118:119], v[72:73]
	v_mov_b32_e32 v118, v32
	v_mov_b32_e32 v119, v24
	v_mov_b32_e32 v120, v92
	v_mov_b32_e32 v121, v108
	v_mov_b32_dpp v55, v25 row_ror:2 row_mask:0xf bank_mask:0xf bound_ctrl:1
	v_pk_fma_f32 v[118:119], v[118:119], v[120:121], v[72:73]
	v_mov_b32_dpp v72, v25 row_ror:1 row_mask:0xf bank_mask:0xf bound_ctrl:1
	v_cndmask_b32_e64 v67, v67, v55, s[40:41]
	v_cndmask_b32_e64 v66, v70, v40, s[40:41]
	v_mov_b32_e32 v100, v85
	v_mov_b32_e32 v112, v97
	v_cndmask_b32_e64 v121, v76, v72, s[42:43]
	v_cndmask_b32_e64 v120, v71, v41, s[42:43]
	v_pk_fma_f32 v[66:67], v[100:101], v[66:67], v[112:113]
	v_mov_b32_e32 v104, v89
	v_pk_fma_f32 v[66:67], v[104:105], v[120:121], v[66:67]
	v_mov_b32_e32 v24, v33
	v_mov_b32_e32 v108, v93
	v_pk_fma_f32 v[84:85], v[24:25], v[108:109], v[66:67]
	v_mov_b32_dpp v66, v26 row_ror:2 row_mask:0xf bank_mask:0xf bound_ctrl:1
	v_mov_b32_dpp v70, v26 row_ror:1 row_mask:0xf bank_mask:0xf bound_ctrl:1
	v_cndmask_b32_e64 v24, v69, v39, s[42:43]
	v_cndmask_b32_e64 v33, v75, v66, s[40:41]
	v_cndmask_b32_e64 v32, v68, v38, s[40:41]
	v_mov_b32_e32 v68, v86
	v_mov_b32_e32 v69, v102
	v_mov_b32_e32 v74, v98
	v_mov_b32_e32 v75, v114
	v_cndmask_b32_e64 v25, v77, v70, s[42:43]
	v_pk_fma_f32 v[32:33], v[68:69], v[32:33], v[74:75]
	v_mov_b32_e32 v68, v90
	v_mov_b32_e32 v69, v106
	v_pk_fma_f32 v[24:25], v[68:69], v[24:25], v[32:33]
	v_mov_b32_e32 v32, v34
	v_mov_b32_e32 v33, v26
	v_mov_b32_e32 v68, v94
	v_mov_b32_e32 v69, v110
	v_mov_b32_dpp v67, v27 row_ror:2 row_mask:0xf bank_mask:0xf bound_ctrl:1
	v_pk_fma_f32 v[32:33], v[32:33], v[68:69], v[24:25]
	v_mov_b32_dpp v68, v27 row_ror:1 row_mask:0xf bank_mask:0xf bound_ctrl:1
	v_cndmask_b32_e64 v24, v65, v37, s[42:43]
	v_cndmask_b32_e64 v65, v62, v67, s[40:41]
	v_cndmask_b32_e64 v64, v64, v36, s[40:41]
	v_mov_b32_e32 v102, v87
	v_mov_b32_e32 v114, v99
	v_cndmask_b32_e64 v25, v78, v68, s[42:43]
	v_pk_fma_f32 v[64:65], v[102:103], v[64:65], v[114:115]
	v_mov_b32_e32 v106, v91
	v_pk_fma_f32 v[24:25], v[106:107], v[24:25], v[64:65]
	v_mov_b32_e32 v26, v35
	v_mov_b32_e32 v110, v95
	v_pk_fma_f32 v[24:25], v[26:27], v[110:111], v[24:25]
	v_mul_f32_e32 v26, 0xbfb8aa3b, v118
	v_exp_f32_e32 v26, v26
	s_nop 0
	v_add_f32_e32 v26, 1.0, v26
	s_nop 0
	v_rcp_f32_e32 v26, v26
	v_mul_f32_e32 v27, 0xbfb8aa3b, v84
	v_exp_f32_e32 v27, v27
	v_mul_f32_e32 v26, v118, v26
	v_mul_f32_e32 v26, v26, v119
	v_add_f32_e32 v27, 1.0, v27
	s_nop 0
	v_rcp_f32_e32 v27, v27
	s_nop 0
	v_mul_f32_e32 v27, v84, v27
	v_mul_f32_e32 v27, v27, v85
	v_cvt_pk_bf16_f32 v26, v26, v27
	v_mul_f32_e32 v27, 0xbfb8aa3b, v32
	v_exp_f32_e32 v27, v27
	s_nop 0
	v_add_f32_e32 v27, 1.0, v27
	s_nop 0
	v_rcp_f32_e32 v27, v27
	s_nop 0
	v_mul_f32_e32 v27, v32, v27
	v_mul_f32_e32 v32, 0xbfb8aa3b, v24
	v_exp_f32_e32 v32, v32
	v_mul_f32_e32 v27, v27, v33
	v_add_f32_e32 v32, 1.0, v32
	s_nop 0
	v_rcp_f32_e32 v32, v32
	s_nop 0
	v_mul_f32_e32 v24, v24, v32
	v_mul_f32_e32 v24, v24, v25
	v_cvt_pk_bf16_f32 v27, v27, v24
	v_mad_i64_i32 v[24:25], s[0:1], v42, s2, v[52:53]
	v_lshl_add_u64 v[24:25], v[24:25], 0, v[116:117]
	global_store_dwordx2 v[24:25], v[26:27], off offset:2048
	ds_read_b128 v[74:77], v172 offset:16
	ds_read_b128 v[84:87], v172 offset:1040
	ds_read_b128 v[88:91], v172 offset:2064
	ds_read_b128 v[92:95], v172 offset:3088
	v_mov_b32_dpp v44, v20 row_ror:1 row_mask:0xf bank_mask:0xf bound_ctrl:1
	v_mov_b32_dpp v42, v20 row_ror:2 row_mask:0xf bank_mask:0xf bound_ctrl:1
	v_mov_b32_dpp v35, v21 row_ror:1 row_mask:0xf bank_mask:0xf bound_ctrl:1
	v_mov_b32_dpp v34, v21 row_ror:2 row_mask:0xf bank_mask:0xf bound_ctrl:1
	v_mov_b32_dpp v33, v22 row_ror:1 row_mask:0xf bank_mask:0xf bound_ctrl:1
	v_mov_b32_dpp v32, v22 row_ror:2 row_mask:0xf bank_mask:0xf bound_ctrl:1
	v_mov_b32_dpp v27, v23 row_ror:1 row_mask:0xf bank_mask:0xf bound_ctrl:1
	v_mov_b32_dpp v26, v23 row_ror:2 row_mask:0xf bank_mask:0xf bound_ctrl:1
	ds_read_b128 v[96:99], v172 offset:528
	ds_read_b128 v[100:103], v172 offset:1552
	ds_read_b128 v[104:107], v172 offset:2576
	ds_read_b128 v[108:111], v172 offset:3600
	v_mov_b32_dpp v47, v16 row_ror:2 row_mask:0xf bank_mask:0xf bound_ctrl:1
	v_mov_b32_dpp v62, v16 row_ror:1 row_mask:0xf bank_mask:0xf bound_ctrl:1
	v_cndmask_b32_e64 v64, v61, v44, s[42:43]
	v_cndmask_b32_e64 v61, v50, v47, s[40:41]
	v_cndmask_b32_e64 v60, v60, v42, s[40:41]
	s_waitcnt lgkmcnt(7)
	v_mov_b32_e32 v112, v74
	s_waitcnt lgkmcnt(3)
	v_mov_b32_e32 v113, v96
	v_mov_b32_e32 v114, v92
	s_waitcnt lgkmcnt(0)
	v_mov_b32_e32 v115, v108
	v_cndmask_b32_e64 v65, v63, v62, s[42:43]
	v_pk_fma_f32 v[60:61], v[112:113], v[60:61], v[114:115]
	v_mov_b32_e32 v112, v84
	v_mov_b32_e32 v113, v100
	v_pk_fma_f32 v[60:61], v[112:113], v[64:65], v[60:61]
	v_mov_b32_e32 v64, v20
	v_mov_b32_e32 v65, v16
	v_mov_b32_e32 v112, v88
	v_mov_b32_e32 v113, v104
	v_mov_b32_dpp v50, v17 row_ror:2 row_mask:0xf bank_mask:0xf bound_ctrl:1
	v_pk_fma_f32 v[64:65], v[64:65], v[112:113], v[60:61]
	v_mov_b32_dpp v60, v17 row_ror:1 row_mask:0xf bank_mask:0xf bound_ctrl:1
	v_cndmask_b32_e64 v112, v59, v35, s[42:43]
	v_cndmask_b32_e64 v59, v51, v50, s[40:41]
	v_cndmask_b32_e64 v58, v58, v34, s[40:41]
	v_mov_b32_e32 v96, v75
	v_mov_b32_e32 v108, v93
	v_cndmask_b32_e64 v113, v80, v60, s[42:43]
	v_pk_fma_f32 v[58:59], v[96:97], v[58:59], v[108:109]
	v_mov_b32_e32 v100, v85
	v_pk_fma_f32 v[58:59], v[100:101], v[112:113], v[58:59]
	v_mov_b32_e32 v16, v21
	v_mov_b32_e32 v104, v89
	v_mov_b32_dpp v51, v18 row_ror:2 row_mask:0xf bank_mask:0xf bound_ctrl:1
	v_pk_fma_f32 v[74:75], v[16:17], v[104:105], v[58:59]
	v_mov_b32_dpp v58, v18 row_ror:1 row_mask:0xf bank_mask:0xf bound_ctrl:1
	v_cndmask_b32_e64 v16, v57, v33, s[42:43]
	v_cndmask_b32_e64 v21, v79, v51, s[40:41]
	v_cndmask_b32_e64 v20, v56, v32, s[40:41]
	v_mov_b32_e32 v56, v76
	v_mov_b32_e32 v57, v98
	v_mov_b32_e32 v78, v94
	v_mov_b32_e32 v79, v110
	v_cndmask_b32_e64 v17, v81, v58, s[42:43]
	v_pk_fma_f32 v[20:21], v[56:57], v[20:21], v[78:79]
	v_mov_b32_e32 v56, v86
	v_mov_b32_e32 v57, v102
	v_pk_fma_f32 v[16:17], v[56:57], v[16:17], v[20:21]
	v_mov_b32_e32 v20, v22
	v_mov_b32_e32 v21, v18
	v_mov_b32_e32 v56, v90
	v_mov_b32_e32 v57, v106
	v_mov_b32_dpp v22, v19 row_ror:2 row_mask:0xf bank_mask:0xf bound_ctrl:1
	v_pk_fma_f32 v[20:21], v[20:21], v[56:57], v[16:17]
	v_mov_b32_dpp v56, v19 row_ror:1 row_mask:0xf bank_mask:0xf bound_ctrl:1
	v_cndmask_b32_e64 v16, v49, v27, s[42:43]
	v_cndmask_b32_e64 v49, v46, v22, s[40:41]
	v_cndmask_b32_e64 v48, v48, v26, s[40:41]
	v_mov_b32_e32 v98, v77
	v_mov_b32_e32 v110, v95
	v_cndmask_b32_e64 v17, v82, v56, s[42:43]
	v_pk_fma_f32 v[48:49], v[98:99], v[48:49], v[110:111]
	v_mov_b32_e32 v102, v87
	v_pk_fma_f32 v[16:17], v[102:103], v[16:17], v[48:49]
	v_mov_b32_e32 v18, v23
	v_mov_b32_e32 v106, v91
	v_pk_fma_f32 v[16:17], v[18:19], v[106:107], v[16:17]
	v_mul_f32_e32 v18, 0xbfb8aa3b, v64
	v_exp_f32_e32 v18, v18
	s_nop 0
	v_add_f32_e32 v18, 1.0, v18
	s_nop 0
	v_rcp_f32_e32 v18, v18
	v_mul_f32_e32 v19, 0xbfb8aa3b, v74
	v_exp_f32_e32 v19, v19
	v_mul_f32_e32 v18, v64, v18
	v_mul_f32_e32 v18, v18, v65
	v_add_f32_e32 v19, 1.0, v19
	s_nop 0
	v_rcp_f32_e32 v19, v19
	s_nop 0
	v_mul_f32_e32 v19, v74, v19
	v_mul_f32_e32 v19, v19, v75
	v_cvt_pk_bf16_f32 v18, v18, v19
	v_mul_f32_e32 v19, 0xbfb8aa3b, v20
	v_exp_f32_e32 v19, v19
	s_nop 0
	v_add_f32_e32 v19, 1.0, v19
	s_nop 0
	v_rcp_f32_e32 v19, v19
	s_nop 0
	v_mul_f32_e32 v19, v20, v19
	v_mul_f32_e32 v20, 0xbfb8aa3b, v16
	v_exp_f32_e32 v20, v20
	v_mul_f32_e32 v19, v19, v21
	v_add_f32_e32 v20, 1.0, v20
	s_nop 0
	v_rcp_f32_e32 v20, v20
	s_nop 0
	v_mul_f32_e32 v16, v16, v20
	v_mul_f32_e32 v16, v16, v17
	v_cvt_pk_bf16_f32 v19, v19, v16
	global_store_dwordx2 v[24:25], v[18:19], off offset:2056
	ds_read_b128 v[16:19], v172
	ds_read_b128 v[74:77], v172 offset:1024
	ds_read_b128 v[78:81], v172 offset:2048
	ds_read_b128 v[84:87], v172 offset:3072
	v_add_u32_e32 v23, 0xb0, v173
	v_mov_b32_dpp v20, v12 row_ror:1 row_mask:0xf bank_mask:0xf bound_ctrl:1
	v_mov_b32_dpp v24, v12 row_ror:2 row_mask:0xf bank_mask:0xf bound_ctrl:1
	v_mov_b32_dpp v46, v13 row_ror:1 row_mask:0xf bank_mask:0xf bound_ctrl:1
	v_mov_b32_dpp v57, v13 row_ror:2 row_mask:0xf bank_mask:0xf bound_ctrl:1
	v_mov_b32_dpp v59, v14 row_ror:1 row_mask:0xf bank_mask:0xf bound_ctrl:1
	v_mov_b32_dpp v61, v14 row_ror:2 row_mask:0xf bank_mask:0xf bound_ctrl:1
	v_mov_b32_dpp v63, v15 row_ror:1 row_mask:0xf bank_mask:0xf bound_ctrl:1
	v_mov_b32_dpp v69, v15 row_ror:2 row_mask:0xf bank_mask:0xf bound_ctrl:1
	ds_read_b128 v[88:91], v174
	ds_read_b128 v[92:95], v174 offset:1024
	ds_read_b128 v[96:99], v174 offset:2048
	ds_read_b128 v[100:103], v174 offset:3072
	v_mov_b32_dpp v25, v8 row_ror:2 row_mask:0xf bank_mask:0xf bound_ctrl:1
	v_mov_b32_dpp v21, v8 row_ror:1 row_mask:0xf bank_mask:0xf bound_ctrl:1
	v_cndmask_b32_e64 v25, v54, v25, s[40:41]
	v_cndmask_b32_e64 v24, v43, v24, s[40:41]
	s_waitcnt lgkmcnt(7)
	v_mov_b32_e32 v48, v16
	s_waitcnt lgkmcnt(3)
	v_mov_b32_e32 v49, v88
	v_mov_b32_e32 v64, v84
	s_waitcnt lgkmcnt(0)
	v_mov_b32_e32 v65, v100
	v_cndmask_b32_e64 v21, v83, v21, s[42:43]
	v_cndmask_b32_e64 v20, v45, v20, s[42:43]
	v_pk_fma_f32 v[24:25], v[48:49], v[24:25], v[64:65]
	v_mov_b32_e32 v48, v74
	v_mov_b32_e32 v49, v92
	v_pk_fma_f32 v[20:21], v[48:49], v[20:21], v[24:25]
	v_mov_b32_e32 v24, v12
	v_mov_b32_e32 v25, v8
	v_mov_b32_e32 v48, v78
	v_mov_b32_e32 v49, v96
	v_mov_b32_dpp v12, v9 row_ror:2 row_mask:0xf bank_mask:0xf bound_ctrl:1
	v_pk_fma_f32 v[20:21], v[24:25], v[48:49], v[20:21]
	v_mov_b32_dpp v8, v9 row_ror:1 row_mask:0xf bank_mask:0xf bound_ctrl:1
	v_cndmask_b32_e64 v24, v41, v46, s[42:43]
	v_cndmask_b32_e64 v41, v55, v12, s[40:41]
	v_cndmask_b32_e64 v40, v40, v57, s[40:41]
	v_mov_b32_e32 v88, v17
	v_mov_b32_e32 v100, v85
	v_cndmask_b32_e64 v25, v72, v8, s[42:43]
	v_pk_fma_f32 v[16:17], v[88:89], v[40:41], v[100:101]
	v_mov_b32_e32 v92, v75
	v_pk_fma_f32 v[16:17], v[92:93], v[24:25], v[16:17]
	v_mov_b32_e32 v8, v13
	v_mov_b32_e32 v96, v79
	v_pk_fma_f32 v[16:17], v[8:9], v[96:97], v[16:17]
	v_mov_b32_dpp v8, v10 row_ror:1 row_mask:0xf bank_mask:0xf bound_ctrl:1
	v_mov_b32_dpp v12, v10 row_ror:2 row_mask:0xf bank_mask:0xf bound_ctrl:1
	v_cndmask_b32_e64 v9, v70, v8, s[42:43]
	v_cndmask_b32_e64 v8, v39, v59, s[42:43]
	v_cndmask_b32_e64 v13, v66, v12, s[40:41]
	v_cndmask_b32_e64 v12, v38, v61, s[40:41]
	v_mov_b32_e32 v24, v18
	v_mov_b32_e32 v25, v90
	v_mov_b32_e32 v38, v86
	v_mov_b32_e32 v39, v102
	v_pk_fma_f32 v[12:13], v[24:25], v[12:13], v[38:39]
	v_mov_b32_e32 v24, v76
	v_mov_b32_e32 v25, v94
	v_pk_fma_f32 v[8:9], v[24:25], v[8:9], v[12:13]
	v_mov_b32_e32 v12, v14
	v_mov_b32_e32 v13, v10
	v_mov_b32_e32 v24, v80
	v_mov_b32_e32 v25, v98
	v_mov_b32_dpp v10, v11 row_ror:2 row_mask:0xf bank_mask:0xf bound_ctrl:1
	v_pk_fma_f32 v[12:13], v[12:13], v[24:25], v[8:9]
	v_mov_b32_dpp v8, v11 row_ror:1 row_mask:0xf bank_mask:0xf bound_ctrl:1
	v_cndmask_b32_e64 v25, v67, v10, s[40:41]
	v_cndmask_b32_e64 v24, v36, v69, s[40:41]
	v_mov_b32_e32 v90, v19
	v_mov_b32_e32 v102, v87
	v_cndmask_b32_e64 v9, v68, v8, s[42:43]
	v_cndmask_b32_e64 v8, v37, v63, s[42:43]
	v_pk_fma_f32 v[18:19], v[90:91], v[24:25], v[102:103]
	v_mov_b32_e32 v94, v77
	v_pk_fma_f32 v[8:9], v[94:95], v[8:9], v[18:19]
	v_mov_b32_e32 v10, v15
	v_mov_b32_e32 v98, v81
	v_pk_fma_f32 v[8:9], v[10:11], v[98:99], v[8:9]
	v_mul_f32_e32 v10, 0xbfb8aa3b, v20
	v_exp_f32_e32 v10, v10
	s_nop 0
	v_add_f32_e32 v10, 1.0, v10
	s_nop 0
	v_rcp_f32_e32 v10, v10
	v_mul_f32_e32 v11, 0xbfb8aa3b, v16
	v_exp_f32_e32 v11, v11
	v_mul_f32_e32 v10, v20, v10
	v_mul_f32_e32 v10, v10, v21
	v_add_f32_e32 v11, 1.0, v11
	s_nop 0
	v_rcp_f32_e32 v11, v11
	s_nop 0
	v_mul_f32_e32 v11, v16, v11
	v_mul_f32_e32 v11, v11, v17
	v_cvt_pk_bf16_f32 v10, v10, v11
	v_mul_f32_e32 v11, 0xbfb8aa3b, v12
	v_exp_f32_e32 v11, v11
	s_nop 0
	v_add_f32_e32 v11, 1.0, v11
	s_nop 0
	v_rcp_f32_e32 v11, v11
	s_nop 0
	v_mul_f32_e32 v11, v12, v11
	v_mul_f32_e32 v12, 0xbfb8aa3b, v8
	v_exp_f32_e32 v12, v12
	v_mul_f32_e32 v11, v11, v13
	v_add_f32_e32 v12, 1.0, v12
	s_nop 0
	v_rcp_f32_e32 v12, v12
	s_nop 0
	v_mul_f32_e32 v8, v8, v12
	v_mul_f32_e32 v8, v8, v9
	v_cvt_pk_bf16_f32 v11, v11, v8
	v_mad_i64_i32 v[8:9], s[0:1], v23, s2, v[52:53]
	v_lshl_add_u64 v[8:9], v[8:9], 0, v[116:117]
	global_store_dwordx2 v[8:9], v[10:11], off offset:2048
	ds_read_b128 v[10:13], v172 offset:16
	ds_read_b128 v[14:17], v172 offset:1040
	ds_read_b128 v[18:21], v172 offset:2064
	ds_read_b128 v[36:39], v172 offset:3088
	v_mov_b32_dpp v23, v4 row_ror:1 row_mask:0xf bank_mask:0xf bound_ctrl:1
	v_mov_b32_dpp v40, v4 row_ror:2 row_mask:0xf bank_mask:0xf bound_ctrl:1
	v_mov_b32_dpp v46, v5 row_ror:1 row_mask:0xf bank_mask:0xf bound_ctrl:1
	v_mov_b32_dpp v48, v5 row_ror:2 row_mask:0xf bank_mask:0xf bound_ctrl:1
	v_mov_b32_dpp v49, v6 row_ror:1 row_mask:0xf bank_mask:0xf bound_ctrl:1
	v_mov_b32_dpp v57, v6 row_ror:2 row_mask:0xf bank_mask:0xf bound_ctrl:1
	v_mov_b32_dpp v59, v7 row_ror:1 row_mask:0xf bank_mask:0xf bound_ctrl:1
	v_mov_b32_dpp v61, v7 row_ror:2 row_mask:0xf bank_mask:0xf bound_ctrl:1
	ds_read_b128 v[52:55], v172 offset:528
	ds_read_b128 v[64:67], v172 offset:1552
	ds_read_b128 v[68:71], v172 offset:2576
	ds_read_b128 v[72:75], v172 offset:3600
	v_mov_b32_dpp v24, v0 row_ror:1 row_mask:0xf bank_mask:0xf bound_ctrl:1
	v_mov_b32_dpp v41, v0 row_ror:2 row_mask:0xf bank_mask:0xf bound_ctrl:1
	v_cndmask_b32_e64 v25, v62, v24, s[42:43]
	v_cndmask_b32_e64 v24, v44, v23, s[42:43]
	v_cndmask_b32_e64 v41, v47, v41, s[40:41]
	v_cndmask_b32_e64 v40, v42, v40, s[40:41]
	s_waitcnt lgkmcnt(7)
	v_mov_b32_e32 v42, v10
	s_waitcnt lgkmcnt(3)
	v_mov_b32_e32 v43, v52
	v_mov_b32_e32 v44, v36
	s_waitcnt lgkmcnt(0)
	v_mov_b32_e32 v45, v72
	v_pk_fma_f32 v[40:41], v[42:43], v[40:41], v[44:45]
	v_mov_b32_e32 v42, v14
	v_mov_b32_e32 v43, v64
	v_pk_fma_f32 v[24:25], v[42:43], v[24:25], v[40:41]
	v_mov_b32_e32 v40, v4
	v_mov_b32_e32 v41, v0
	v_mov_b32_e32 v42, v18
	v_mov_b32_e32 v43, v68
	v_mov_b32_dpp v4, v1 row_ror:2 row_mask:0xf bank_mask:0xf bound_ctrl:1
	v_pk_fma_f32 v[24:25], v[40:41], v[42:43], v[24:25]
	v_mov_b32_dpp v0, v1 row_ror:1 row_mask:0xf bank_mask:0xf bound_ctrl:1
	v_cndmask_b32_e64 v40, v35, v46, s[42:43]
	v_cndmask_b32_e64 v35, v50, v4, s[40:41]
	v_cndmask_b32_e64 v34, v34, v48, s[40:41]
	v_mov_b32_e32 v52, v11
	v_mov_b32_e32 v72, v37
	v_cndmask_b32_e64 v41, v60, v0, s[42:43]
	v_pk_fma_f32 v[10:11], v[52:53], v[34:35], v[72:73]
	v_mov_b32_e32 v64, v15
	v_pk_fma_f32 v[10:11], v[64:65], v[40:41], v[10:11]
	v_mov_b32_e32 v0, v5
	v_mov_b32_e32 v68, v19
	v_mov_b32_dpp v4, v2 row_ror:2 row_mask:0xf bank_mask:0xf bound_ctrl:1
	v_pk_fma_f32 v[10:11], v[0:1], v[68:69], v[10:11]
	v_mov_b32_dpp v0, v2 row_ror:1 row_mask:0xf bank_mask:0xf bound_ctrl:1
	v_cndmask_b32_e64 v5, v51, v4, s[40:41]
	v_cndmask_b32_e64 v4, v32, v57, s[40:41]
	v_mov_b32_e32 v14, v12
	v_mov_b32_e32 v15, v54
	v_mov_b32_e32 v18, v38
	v_mov_b32_e32 v19, v74
	v_cndmask_b32_e64 v1, v58, v0, s[42:43]
	v_cndmask_b32_e64 v0, v33, v49, s[42:43]
	v_pk_fma_f32 v[4:5], v[14:15], v[4:5], v[18:19]
	v_mov_b32_e32 v14, v16
	v_mov_b32_e32 v15, v66
	v_pk_fma_f32 v[0:1], v[14:15], v[0:1], v[4:5]
	v_mov_b32_e32 v4, v6
	v_mov_b32_e32 v5, v2
	v_mov_b32_e32 v14, v20
	v_mov_b32_e32 v15, v70
	v_mov_b32_dpp v2, v3 row_ror:2 row_mask:0xf bank_mask:0xf bound_ctrl:1
	v_pk_fma_f32 v[4:5], v[4:5], v[14:15], v[0:1]
	v_mov_b32_dpp v0, v3 row_ror:1 row_mask:0xf bank_mask:0xf bound_ctrl:1
	v_cndmask_b32_e64 v15, v22, v2, s[40:41]
	v_cndmask_b32_e64 v14, v26, v61, s[40:41]
	v_mov_b32_e32 v54, v13
	v_mov_b32_e32 v74, v39
	v_cndmask_b32_e64 v1, v56, v0, s[42:43]
	v_cndmask_b32_e64 v0, v27, v59, s[42:43]
	v_pk_fma_f32 v[12:13], v[54:55], v[14:15], v[74:75]
	v_mov_b32_e32 v66, v17
	v_pk_fma_f32 v[0:1], v[66:67], v[0:1], v[12:13]
	v_mov_b32_e32 v2, v7
	v_mov_b32_e32 v70, v21
	v_pk_fma_f32 v[0:1], v[2:3], v[70:71], v[0:1]
	v_mul_f32_e32 v2, 0xbfb8aa3b, v24
	v_exp_f32_e32 v2, v2
	s_nop 0
	v_add_f32_e32 v2, 1.0, v2
	s_nop 0
	v_rcp_f32_e32 v2, v2
	v_mul_f32_e32 v3, 0xbfb8aa3b, v10
	v_exp_f32_e32 v3, v3
	v_mul_f32_e32 v2, v24, v2
	v_mul_f32_e32 v2, v2, v25
	v_add_f32_e32 v3, 1.0, v3
	v_div_scale_f32 v6, s[0:1], v3, v3, 1.0
	v_rcp_f32_e32 v7, v6
	s_nop 0
	v_fma_f32 v12, -v6, v7, 1.0
	v_fmac_f32_e32 v7, v12, v7
	v_div_scale_f32 v12, vcc, 1.0, v3, 1.0
	v_mul_f32_e32 v13, v12, v7
	v_fma_f32 v14, -v6, v13, v12
	v_fmac_f32_e32 v13, v14, v7
	v_fma_f32 v6, -v6, v13, v12
	v_div_fmas_f32 v6, v6, v7, v13
	v_div_fixup_f32 v3, v6, v3, 1.0
	v_mul_f32_e32 v3, v10, v3
	v_mul_f32_e32 v3, v3, v11
	v_cvt_pk_bf16_f32 v2, v2, v3
	v_mul_f32_e32 v3, 0xbfb8aa3b, v4
	v_exp_f32_e32 v3, v3
	s_nop 0
	v_add_f32_e32 v3, 1.0, v3
	v_div_scale_f32 v6, s[0:1], v3, v3, 1.0
	v_rcp_f32_e32 v7, v6
	s_nop 0
	v_fma_f32 v10, -v6, v7, 1.0
	v_fmac_f32_e32 v7, v10, v7
	v_div_scale_f32 v10, vcc, 1.0, v3, 1.0
	v_mul_f32_e32 v11, v10, v7
	v_fma_f32 v12, -v6, v11, v10
	v_fmac_f32_e32 v11, v12, v7
	v_fma_f32 v6, -v6, v11, v10
	v_div_fmas_f32 v6, v6, v7, v11
	v_div_fixup_f32 v3, v6, v3, 1.0
	v_mul_f32_e32 v3, v4, v3
	v_mul_f32_e32 v4, 0xbfb8aa3b, v0
	v_exp_f32_e32 v4, v4
	v_mul_f32_e32 v3, v3, v5
	v_add_f32_e32 v4, 1.0, v4
	v_div_scale_f32 v5, s[0:1], v4, v4, 1.0
	v_rcp_f32_e32 v6, v5
	s_nop 0
	v_fma_f32 v7, -v5, v6, 1.0
	v_fmac_f32_e32 v6, v7, v6
	v_div_scale_f32 v7, vcc, 1.0, v4, 1.0
	v_mul_f32_e32 v10, v7, v6
	v_fma_f32 v11, -v5, v10, v7
	v_fmac_f32_e32 v10, v11, v6
	v_fma_f32 v5, -v5, v10, v7
	v_div_fmas_f32 v5, v5, v6, v10
	v_div_fixup_f32 v4, v5, v4, 1.0
	v_mul_f32_e32 v0, v0, v4
	v_mul_f32_e32 v0, v0, v1
	v_cvt_pk_bf16_f32 v3, v3, v0
	global_store_dwordx2 v[8:9], v[2:3], off offset:2056
	s_and_b64 vcc, exec, s[38:39]
	s_mov_b64 s[0:1], -1
	s_cbranch_vccnz .LBB0_217
	s_andn2_b64 vcc, exec, s[4:5]
	s_cbranch_vccnz .LBB0_216
	s_barrier
	s_branch .LBB0_216

.LBB0_281:
	s_waitcnt lgkmcnt(0)
	v_add_f32_e32 v30, v30, v92
	v_fmamk_f32 v30, v30, 0x3a800000, v188
	s_mov_b32 s0, 0xf800000
	v_mul_f32_e32 v36, 0x4f800000, v30
	v_cmp_gt_f32_e32 vcc, s0, v30
	s_nop 1
	v_cndmask_b32_e32 v30, v30, v36, vcc
	v_sqrt_f32_e32 v36, v30
	s_nop 0
	v_add_u32_e32 v37, -1, v36
	v_fma_f32 v39, -v37, v36, v30
	v_add_u32_e32 v38, 1, v36
	v_cmp_ge_f32_e64 s[0:1], 0, v39
	s_nop 1
	v_cndmask_b32_e64 v37, v36, v37, s[0:1]
	v_fma_f32 v36, -v38, v36, v30
	v_cmp_lt_f32_e64 s[0:1], 0, v36
	s_nop 1
	v_cndmask_b32_e64 v36, v37, v38, s[0:1]
	v_mul_f32_e32 v37, 0x37800000, v36
	v_cndmask_b32_e32 v36, v36, v37, vcc
	v_cmp_class_f32_e32 vcc, v30, v189
	s_nop 1
	v_cndmask_b32_e32 v30, v36, v30, vcc
	s_nop 0
	v_rcp_f32_e32 v30, v30
	s_nop 0
	v_pk_mul_f32 v[32:33], v[32:33], v[30:31] op_sel_hi:[1,0]
	v_pk_mul_f32 v[24:25], v[24:25], v[30:31] op_sel_hi:[1,0]
	v_pk_mul_f32 v[20:21], v[20:21], v[30:31] op_sel_hi:[1,0]
	v_pk_mul_f32 v[16:17], v[16:17], v[30:31] op_sel_hi:[1,0]
	v_mad_i64_i32 v[36:37], s[0:1], s8, v194, v[84:85]
	v_pk_mul_f32 v[34:35], v[34:35], v[30:31] op_sel_hi:[1,0]
	v_pk_mul_f32 v[32:33], v[0:1], v[32:33]
	v_pk_mul_f32 v[26:27], v[26:27], v[30:31] op_sel_hi:[1,0]
	v_pk_mul_f32 v[24:25], v[4:5], v[24:25]
	v_pk_mul_f32 v[22:23], v[22:23], v[30:31] op_sel_hi:[1,0]
	v_pk_mul_f32 v[20:21], v[8:9], v[20:21]
	v_pk_mul_f32 v[18:19], v[18:19], v[30:31] op_sel_hi:[1,0]
	v_pk_mul_f32 v[16:17], v[12:13], v[16:17]
	v_pk_mul_f32 v[34:35], v[2:3], v[34:35]
	v_cvt_pk_bf16_f32 v32, v32, v33
	v_pk_mul_f32 v[26:27], v[6:7], v[26:27]
	v_cvt_pk_bf16_f32 v33, v34, v35
	global_store_dwordx2 v[36:37], v[32:33], off
	v_cvt_pk_bf16_f32 v24, v24, v25
	v_cvt_pk_bf16_f32 v25, v26, v27
	global_store_dwordx2 v[36:37], v[24:25], off offset:512
	v_pk_mul_f32 v[22:23], v[10:11], v[22:23]
	v_cvt_pk_bf16_f32 v20, v20, v21
	v_pk_mul_f32 v[18:19], v[14:15], v[18:19]
	v_cvt_pk_bf16_f32 v21, v22, v23
	global_store_dwordx2 v[36:37], v[20:21], off offset:1024
	v_cvt_pk_bf16_f32 v16, v16, v17
	v_cvt_pk_bf16_f32 v17, v18, v19
	global_store_dwordx2 v[36:37], v[16:17], off offset:1536
	s_branch .LBB0_275

.LBB0_423:
	v_mul_f32_e32 v128, 0xbfb8aa3b, v128
	v_exp_f32_e32 v128, v128
	v_mul_f32_e32 v129, 0xbfb8aa3b, v129
	v_exp_f32_e32 v129, v129
	v_mul_f32_e32 v124, 0xbfb8aa3b, v124
	v_add_f32_e32 v128, 1.0, v128
	v_add_f32_e32 v129, 1.0, v129
	v_exp_f32_e32 v124, v124
	v_mul_f32_e32 v125, 0xbfb8aa3b, v125
	v_rcp_f32_e32 v128, v128
	v_add_f32_e32 v124, 1.0, v124
	v_exp_f32_e32 v125, v125
	v_mul_f32_e32 v120, 0xbfb8aa3b, v120
	v_rcp_f32_e32 v129, v129
	s_nop 0
	v_cvt_pk_bf16_f32 v128, v128, v129
	v_mul_f32_e32 v129, 0xbfb8aa3b, v130
	v_exp_f32_e32 v129, v129
	v_add_f32_e32 v125, 1.0, v125
	v_exp_f32_e32 v120, v120
	v_lshl_or_b32 v142, s24, 8, v164
	v_add_f32_e32 v129, 1.0, v129
	v_add_f32_e32 v120, 1.0, v120
	v_lshl_add_u32 v166, s25, 8, v146
	v_ashrrev_i32_e32 v143, 31, v142
	v_rcp_f32_e32 v129, v129
	v_mul_f32_e32 v130, 0xbfb8aa3b, v131
	v_exp_f32_e32 v130, v130
	v_mov_b64_e32 v[140:141], s[42:43]
	s_movk_i32 s2, 0x3080
	v_mad_i64_i32 v[144:145], s[0:1], v166, s2, v[140:141]
	v_add_f32_e32 v130, 1.0, v130
	v_lshlrev_b64 v[142:143], 1, v[142:143]
	v_mul_f32_e32 v121, 0xbfb8aa3b, v121
	v_lshl_add_u64 v[144:145], v[144:145], 0, v[142:143]
	v_rcp_f32_e32 v130, v130
	s_nop 0
	v_cvt_pk_bf16_f32 v129, v129, v130
	v_exp_f32_e32 v121, v121
	v_mul_f32_e32 v116, 0xbfb8aa3b, v116
	v_exp_f32_e32 v116, v116
	v_rcp_f32_e32 v124, v124
	v_add_f32_e32 v121, 1.0, v121
	v_add_f32_e32 v116, 1.0, v116
	v_mul_f32_e32 v117, 0xbfb8aa3b, v117
	v_rcp_f32_e32 v125, v125
	s_nop 0
	v_cvt_pk_bf16_f32 v130, v124, v125
	v_mul_f32_e32 v124, 0xbfb8aa3b, v126
	v_exp_f32_e32 v124, v124
	v_exp_f32_e32 v117, v117
	v_mul_f32_e32 v112, 0xbfb8aa3b, v112
	v_exp_f32_e32 v112, v112
	v_add_f32_e32 v124, 1.0, v124
	v_add_f32_e32 v117, 1.0, v117
	v_add_f32_e32 v112, 1.0, v112
	v_mul_f32_e32 v113, 0xbfb8aa3b, v113
	v_rcp_f32_e32 v124, v124
	v_mul_f32_e32 v125, 0xbfb8aa3b, v127
	v_exp_f32_e32 v125, v125
	v_exp_f32_e32 v113, v113
	v_mul_f32_e32 v108, 0xbfb8aa3b, v108
	v_exp_f32_e32 v108, v108
	v_add_f32_e32 v125, 1.0, v125
	v_add_f32_e32 v113, 1.0, v113
	v_add_f32_e32 v108, 1.0, v108
	v_mul_f32_e32 v109, 0xbfb8aa3b, v109
	v_rcp_f32_e32 v125, v125
	s_nop 0
	v_cvt_pk_bf16_f32 v131, v124, v125
	global_store_dwordx4 v[144:145], v[128:131], off
	v_exp_f32_e32 v109, v109
	v_mul_f32_e32 v104, 0xbfb8aa3b, v104
	v_rcp_f32_e32 v120, v120
	v_add_f32_e32 v109, 1.0, v109
	v_exp_f32_e32 v104, v104
	v_mul_f32_e32 v105, 0xbfb8aa3b, v105
	v_rcp_f32_e32 v121, v121
	s_nop 0
	v_cvt_pk_bf16_f32 v120, v120, v121
	v_mul_f32_e32 v121, 0xbfb8aa3b, v122
	v_exp_f32_e32 v121, v121
	v_add_f32_e32 v104, 1.0, v104
	v_exp_f32_e32 v105, v105
	v_mul_f32_e32 v100, 0xbfb8aa3b, v100
	v_add_f32_e32 v121, 1.0, v121
	v_add_f32_e32 v105, 1.0, v105
	v_exp_f32_e32 v100, v100
	v_mul_f32_e32 v101, 0xbfb8aa3b, v101
	v_rcp_f32_e32 v121, v121
	v_mul_f32_e32 v122, 0xbfb8aa3b, v123
	v_exp_f32_e32 v122, v122
	v_add_f32_e32 v100, 1.0, v100
	v_exp_f32_e32 v101, v101
	v_mul_f32_e32 v96, 0xbfb8aa3b, v96
	v_add_f32_e32 v122, 1.0, v122
	v_add_f32_e32 v101, 1.0, v101
	v_exp_f32_e32 v96, v96
	v_mul_f32_e32 v97, 0xbfb8aa3b, v97
	v_rcp_f32_e32 v122, v122
	s_nop 0
	v_cvt_pk_bf16_f32 v121, v121, v122
	v_add_f32_e32 v96, 1.0, v96
	v_exp_f32_e32 v97, v97
	v_mul_f32_e32 v92, 0xbfb8aa3b, v92
	v_rcp_f32_e32 v116, v116
	v_add_f32_e32 v97, 1.0, v97
	v_exp_f32_e32 v92, v92
	v_mul_f32_e32 v93, 0xbfb8aa3b, v93
	v_rcp_f32_e32 v117, v117
	s_nop 0
	v_cvt_pk_bf16_f32 v122, v116, v117
	v_mul_f32_e32 v116, 0xbfb8aa3b, v118
	v_exp_f32_e32 v116, v116
	v_add_f32_e32 v92, 1.0, v92
	v_exp_f32_e32 v93, v93
	v_mul_f32_e32 v88, 0xbfb8aa3b, v88
	v_add_f32_e32 v116, 1.0, v116
	v_add_f32_e32 v93, 1.0, v93
	v_exp_f32_e32 v88, v88
	v_mul_f32_e32 v89, 0xbfb8aa3b, v89
	v_rcp_f32_e32 v116, v116
	v_mul_f32_e32 v117, 0xbfb8aa3b, v119
	v_exp_f32_e32 v117, v117
	v_add_f32_e32 v88, 1.0, v88
	v_exp_f32_e32 v89, v89
	v_mul_f32_e32 v84, 0xbfb8aa3b, v84
	v_add_f32_e32 v117, 1.0, v117
	v_add_f32_e32 v89, 1.0, v89
	v_exp_f32_e32 v84, v84
	v_mul_f32_e32 v85, 0xbfb8aa3b, v85
	v_rcp_f32_e32 v117, v117
	s_nop 0
	v_cvt_pk_bf16_f32 v123, v116, v117
	global_store_dwordx4 v[144:145], v[120:123], off offset:256
	v_or_b32_e32 v116, 16, v166
	v_mad_i64_i32 v[116:117], s[0:1], v116, s2, v[140:141]
	v_rcp_f32_e32 v112, v112
	v_lshl_add_u64 v[116:117], v[116:117], 0, v[142:143]
	v_add_f32_e32 v84, 1.0, v84
	v_exp_f32_e32 v85, v85
	v_rcp_f32_e32 v113, v113
	s_nop 0
	v_cvt_pk_bf16_f32 v112, v112, v113
	v_mul_f32_e32 v113, 0xbfb8aa3b, v114
	v_exp_f32_e32 v113, v113
	v_add_f32_e32 v85, 1.0, v85
	v_mul_f32_e32 v80, 0xbfb8aa3b, v80
	v_exp_f32_e32 v80, v80
	v_add_f32_e32 v113, 1.0, v113
	v_add_f32_e32 v80, 1.0, v80
	v_mul_f32_e32 v81, 0xbfb8aa3b, v81
	v_exp_f32_e32 v81, v81
	v_rcp_f32_e32 v113, v113
	v_mul_f32_e32 v114, 0xbfb8aa3b, v115
	v_exp_f32_e32 v114, v114
	v_add_f32_e32 v81, 1.0, v81
	v_mul_f32_e32 v76, 0xbfb8aa3b, v76
	v_exp_f32_e32 v76, v76
	v_add_f32_e32 v114, 1.0, v114
	v_add_f32_e32 v76, 1.0, v76
	v_mul_f32_e32 v77, 0xbfb8aa3b, v77
	v_exp_f32_e32 v77, v77
	v_rcp_f32_e32 v114, v114
	s_nop 0
	v_cvt_pk_bf16_f32 v113, v113, v114
	v_add_f32_e32 v77, 1.0, v77
	v_mul_f32_e32 v72, 0xbfb8aa3b, v72
	v_exp_f32_e32 v72, v72
	v_rcp_f32_e32 v108, v108
	v_add_f32_e32 v72, 1.0, v72
	v_mul_f32_e32 v73, 0xbfb8aa3b, v73
	v_exp_f32_e32 v73, v73
	v_rcp_f32_e32 v109, v109
	s_nop 0
	v_cvt_pk_bf16_f32 v114, v108, v109
	v_mul_f32_e32 v108, 0xbfb8aa3b, v110
	v_exp_f32_e32 v108, v108
	v_add_f32_e32 v73, 1.0, v73
	v_mul_f32_e32 v68, 0xbfb8aa3b, v68
	v_exp_f32_e32 v68, v68
	v_add_f32_e32 v108, 1.0, v108
	v_add_f32_e32 v68, 1.0, v68
	v_mul_f32_e32 v69, 0xbfb8aa3b, v69
	v_exp_f32_e32 v69, v69
	v_rcp_f32_e32 v108, v108
	v_mul_f32_e32 v109, 0xbfb8aa3b, v111
	v_exp_f32_e32 v109, v109
	v_add_f32_e32 v69, 1.0, v69
	v_mul_f32_e32 v64, 0xbfb8aa3b, v64
	v_exp_f32_e32 v64, v64
	v_add_f32_e32 v109, 1.0, v109
	v_add_f32_e32 v64, 1.0, v64
	v_mul_f32_e32 v65, 0xbfb8aa3b, v65
	v_exp_f32_e32 v65, v65
	v_rcp_f32_e32 v109, v109
	s_nop 0
	v_cvt_pk_bf16_f32 v115, v108, v109
	global_store_dwordx4 v[116:117], v[112:115], off
	v_add_f32_e32 v65, 1.0, v65
	v_mul_f32_e32 v60, 0xbfb8aa3b, v60
	v_rcp_f32_e32 v104, v104
	v_exp_f32_e32 v60, v60
	v_mul_f32_e32 v61, 0xbfb8aa3b, v61
	v_exp_f32_e32 v61, v61
	v_rcp_f32_e32 v105, v105
	s_nop 0
	v_cvt_pk_bf16_f32 v104, v104, v105
	v_mul_f32_e32 v105, 0xbfb8aa3b, v106
	v_exp_f32_e32 v105, v105
	v_add_f32_e32 v60, 1.0, v60
	v_add_f32_e32 v61, 1.0, v61
	v_mul_f32_e32 v56, 0xbfb8aa3b, v56
	v_add_f32_e32 v105, 1.0, v105
	v_exp_f32_e32 v56, v56
	v_mul_f32_e32 v57, 0xbfb8aa3b, v57
	v_exp_f32_e32 v57, v57
	v_rcp_f32_e32 v105, v105
	v_mul_f32_e32 v106, 0xbfb8aa3b, v107
	v_exp_f32_e32 v106, v106
	v_add_f32_e32 v56, 1.0, v56
	v_add_f32_e32 v57, 1.0, v57
	v_mul_f32_e32 v52, 0xbfb8aa3b, v52
	v_add_f32_e32 v106, 1.0, v106
	v_exp_f32_e32 v52, v52
	v_mul_f32_e32 v53, 0xbfb8aa3b, v53
	v_exp_f32_e32 v53, v53
	v_rcp_f32_e32 v106, v106
	s_nop 0
	v_cvt_pk_bf16_f32 v105, v105, v106
	v_add_f32_e32 v52, 1.0, v52
	v_add_f32_e32 v53, 1.0, v53
	v_mul_f32_e32 v48, 0xbfb8aa3b, v48
	v_rcp_f32_e32 v100, v100
	v_exp_f32_e32 v48, v48
	v_mul_f32_e32 v49, 0xbfb8aa3b, v49
	v_exp_f32_e32 v49, v49
	v_rcp_f32_e32 v101, v101
	s_nop 0
	v_cvt_pk_bf16_f32 v106, v100, v101
	v_mul_f32_e32 v100, 0xbfb8aa3b, v102
	v_exp_f32_e32 v100, v100
	v_add_f32_e32 v48, 1.0, v48
	v_add_f32_e32 v49, 1.0, v49
	v_mul_f32_e32 v44, 0xbfb8aa3b, v44
	v_add_f32_e32 v100, 1.0, v100
	v_exp_f32_e32 v44, v44
	v_mul_f32_e32 v45, 0xbfb8aa3b, v45
	v_exp_f32_e32 v45, v45
	v_rcp_f32_e32 v100, v100
	v_mul_f32_e32 v101, 0xbfb8aa3b, v103
	v_exp_f32_e32 v101, v101
	v_add_f32_e32 v44, 1.0, v44
	v_add_f32_e32 v45, 1.0, v45
	v_mul_f32_e32 v40, 0xbfb8aa3b, v40
	v_add_f32_e32 v101, 1.0, v101
	v_exp_f32_e32 v40, v40
	v_mul_f32_e32 v41, 0xbfb8aa3b, v41
	v_exp_f32_e32 v41, v41
	v_rcp_f32_e32 v101, v101
	s_nop 0
	v_cvt_pk_bf16_f32 v107, v100, v101
	global_store_dwordx4 v[116:117], v[104:107], off offset:256
	v_or_b32_e32 v100, 32, v166
	v_mad_i64_i32 v[100:101], s[0:1], v100, s2, v[140:141]
	v_rcp_f32_e32 v96, v96
	v_lshl_add_u64 v[100:101], v[100:101], 0, v[142:143]
	v_add_f32_e32 v40, 1.0, v40
	v_add_f32_e32 v41, 1.0, v41
	v_rcp_f32_e32 v97, v97
	s_nop 0
	v_cvt_pk_bf16_f32 v96, v96, v97
	v_mul_f32_e32 v97, 0xbfb8aa3b, v98
	v_exp_f32_e32 v97, v97
	v_mul_f32_e32 v36, 0xbfb8aa3b, v36
	v_exp_f32_e32 v36, v36
	v_mul_f32_e32 v37, 0xbfb8aa3b, v37
	v_add_f32_e32 v97, 1.0, v97
	v_add_f32_e32 v36, 1.0, v36
	v_exp_f32_e32 v37, v37
	v_mul_f32_e32 v32, 0xbfb8aa3b, v32
	v_rcp_f32_e32 v97, v97
	v_mul_f32_e32 v98, 0xbfb8aa3b, v99
	v_exp_f32_e32 v98, v98
	v_add_f32_e32 v37, 1.0, v37
	v_exp_f32_e32 v32, v32
	v_mul_f32_e32 v33, 0xbfb8aa3b, v33
	v_add_f32_e32 v98, 1.0, v98
	v_add_f32_e32 v32, 1.0, v32
	v_exp_f32_e32 v33, v33
	v_mul_f32_e32 v24, 0xbfb8aa3b, v24
	v_rcp_f32_e32 v98, v98
	s_nop 0
	v_cvt_pk_bf16_f32 v97, v97, v98
	v_add_f32_e32 v33, 1.0, v33
	v_exp_f32_e32 v24, v24
	v_mul_f32_e32 v25, 0xbfb8aa3b, v25
	v_rcp_f32_e32 v92, v92
	v_add_f32_e32 v24, 1.0, v24
	v_exp_f32_e32 v25, v25
	v_mul_f32_e32 v20, 0xbfb8aa3b, v20
	v_rcp_f32_e32 v93, v93
	s_nop 0
	v_cvt_pk_bf16_f32 v98, v92, v93
	v_mul_f32_e32 v92, 0xbfb8aa3b, v94
	v_exp_f32_e32 v92, v92
	v_add_f32_e32 v25, 1.0, v25
	v_exp_f32_e32 v20, v20
	v_mul_f32_e32 v21, 0xbfb8aa3b, v21
	v_add_f32_e32 v92, 1.0, v92
	v_add_f32_e32 v20, 1.0, v20
	v_exp_f32_e32 v21, v21
	v_mul_f32_e32 v16, 0xbfb8aa3b, v16
	v_rcp_f32_e32 v92, v92
	v_mul_f32_e32 v93, 0xbfb8aa3b, v95
	v_exp_f32_e32 v93, v93
	v_add_f32_e32 v21, 1.0, v21
	v_exp_f32_e32 v16, v16
	v_mul_f32_e32 v17, 0xbfb8aa3b, v17
	v_add_f32_e32 v93, 1.0, v93
	v_div_scale_f32 v94, s[0:1], v93, v93, 1.0
	v_rcp_f32_e32 v95, v94
	v_add_f32_e32 v16, 1.0, v16
	v_exp_f32_e32 v17, v17
	v_mul_f32_e32 v12, 0xbfb8aa3b, v12
	v_fma_f32 v99, -v94, v95, 1.0
	v_fmac_f32_e32 v95, v99, v95
	v_div_scale_f32 v99, vcc, 1.0, v93, 1.0
	v_mul_f32_e32 v102, v99, v95
	v_fma_f32 v103, -v94, v102, v99
	v_fmac_f32_e32 v102, v103, v95
	v_fma_f32 v94, -v94, v102, v99
	v_div_fmas_f32 v94, v94, v95, v102
	v_div_fixup_f32 v93, v94, v93, 1.0
	v_cvt_pk_bf16_f32 v99, v92, v93
	global_store_dwordx4 v[100:101], v[96:99], off
	v_add_f32_e32 v17, 1.0, v17
	v_exp_f32_e32 v12, v12
	v_rcp_f32_e32 v88, v88
	v_add_f32_e32 v12, 1.0, v12
	v_mul_f32_e32 v13, 0xbfb8aa3b, v13
	v_exp_f32_e32 v13, v13
	v_rcp_f32_e32 v89, v89
	s_nop 0
	v_cvt_pk_bf16_f32 v88, v88, v89
	v_mul_f32_e32 v89, 0xbfb8aa3b, v90
	v_exp_f32_e32 v89, v89
	v_add_f32_e32 v13, 1.0, v13
	v_mul_f32_e32 v8, 0xbfb8aa3b, v8
	v_exp_f32_e32 v8, v8
	v_add_f32_e32 v89, 1.0, v89
	v_add_f32_e32 v8, 1.0, v8
	v_mul_f32_e32 v9, 0xbfb8aa3b, v9
	v_exp_f32_e32 v9, v9
	v_rcp_f32_e32 v89, v89
	v_mul_f32_e32 v90, 0xbfb8aa3b, v91
	v_exp_f32_e32 v90, v90
	v_add_f32_e32 v9, 1.0, v9
	v_mul_f32_e32 v4, 0xbfb8aa3b, v4
	v_exp_f32_e32 v4, v4
	v_add_f32_e32 v90, 1.0, v90
	v_add_f32_e32 v4, 1.0, v4
	v_mul_f32_e32 v5, 0xbfb8aa3b, v5
	v_exp_f32_e32 v5, v5
	v_rcp_f32_e32 v90, v90
	s_nop 0
	v_cvt_pk_bf16_f32 v89, v89, v90
	v_add_f32_e32 v5, 1.0, v5
	v_mul_f32_e32 v0, 0xbfb8aa3b, v0
	v_exp_f32_e32 v0, v0
	v_rcp_f32_e32 v84, v84
	v_add_f32_e32 v0, 1.0, v0
	v_mul_f32_e32 v1, 0xbfb8aa3b, v1
	v_exp_f32_e32 v1, v1
	v_rcp_f32_e32 v85, v85
	s_nop 0
	v_cvt_pk_bf16_f32 v90, v84, v85
	v_mul_f32_e32 v84, 0xbfb8aa3b, v86
	v_exp_f32_e32 v84, v84
	v_add_f32_e32 v1, 1.0, v1
	v_add_f32_e32 v84, 1.0, v84
	s_nop 0
	v_rcp_f32_e32 v84, v84
	v_mul_f32_e32 v85, 0xbfb8aa3b, v87
	v_exp_f32_e32 v85, v85
	s_nop 0
	v_add_f32_e32 v85, 1.0, v85
	s_nop 0
	v_rcp_f32_e32 v85, v85
	s_nop 0
	v_cvt_pk_bf16_f32 v91, v84, v85
	global_store_dwordx4 v[100:101], v[88:91], off offset:256
	v_or_b32_e32 v84, 48, v166
	v_mad_i64_i32 v[84:85], s[0:1], v84, s2, v[140:141]
	v_rcp_f32_e32 v80, v80
	v_lshl_add_u64 v[84:85], v[84:85], 0, v[142:143]
	v_rcp_f32_e32 v81, v81
	s_nop 0
	v_cvt_pk_bf16_f32 v80, v80, v81
	v_mul_f32_e32 v81, 0xbfb8aa3b, v82
	v_exp_f32_e32 v81, v81
	s_nop 0
	v_add_f32_e32 v81, 1.0, v81
	s_nop 0
	v_rcp_f32_e32 v81, v81
	v_mul_f32_e32 v82, 0xbfb8aa3b, v83
	v_exp_f32_e32 v82, v82
	s_nop 0
	v_add_f32_e32 v82, 1.0, v82
	s_nop 0
	v_rcp_f32_e32 v82, v82
	s_nop 0
	v_cvt_pk_bf16_f32 v81, v81, v82
	s_nop 0
	v_rcp_f32_e32 v76, v76
	s_nop 0
	v_rcp_f32_e32 v77, v77
	s_nop 0
	v_cvt_pk_bf16_f32 v82, v76, v77
	v_mul_f32_e32 v76, 0xbfb8aa3b, v78
	v_exp_f32_e32 v76, v76
	s_nop 0
	v_add_f32_e32 v76, 1.0, v76
	s_nop 0
	v_rcp_f32_e32 v76, v76
	v_mul_f32_e32 v77, 0xbfb8aa3b, v79
	v_exp_f32_e32 v77, v77
	s_nop 0
	v_add_f32_e32 v77, 1.0, v77
	s_nop 0
	v_rcp_f32_e32 v77, v77
	s_nop 0
	v_cvt_pk_bf16_f32 v83, v76, v77
	global_store_dwordx4 v[84:85], v[80:83], off
	v_rcp_f32_e32 v72, v72
	v_div_scale_f32 v76, s[0:1], v73, v73, 1.0
	v_rcp_f32_e32 v77, v76
	s_nop 0
	v_fma_f32 v78, -v76, v77, 1.0
	v_fmac_f32_e32 v77, v78, v77
	v_div_scale_f32 v78, vcc, 1.0, v73, 1.0
	v_mul_f32_e32 v79, v78, v77
	v_fma_f32 v80, -v76, v79, v78
	v_fmac_f32_e32 v79, v80, v77
	v_fma_f32 v76, -v76, v79, v78
	v_div_fmas_f32 v76, v76, v77, v79
	v_div_fixup_f32 v73, v76, v73, 1.0
	v_cvt_pk_bf16_f32 v72, v72, v73
	v_mul_f32_e32 v73, 0xbfb8aa3b, v74
	v_exp_f32_e32 v73, v73
	s_nop 0
	v_add_f32_e32 v73, 1.0, v73
	s_nop 0
	v_rcp_f32_e32 v73, v73
	v_mul_f32_e32 v74, 0xbfb8aa3b, v75
	v_exp_f32_e32 v74, v74
	s_nop 0
	v_add_f32_e32 v74, 1.0, v74
	v_div_scale_f32 v75, s[0:1], v74, v74, 1.0
	v_rcp_f32_e32 v76, v75
	s_nop 0
	v_fma_f32 v77, -v75, v76, 1.0
	v_fmac_f32_e32 v76, v77, v76
	v_div_scale_f32 v77, vcc, 1.0, v74, 1.0
	v_mul_f32_e32 v78, v77, v76
	v_fma_f32 v79, -v75, v78, v77
	v_fmac_f32_e32 v78, v79, v76
	v_fma_f32 v75, -v75, v78, v77
	v_div_fmas_f32 v75, v75, v76, v78
	v_div_fixup_f32 v74, v75, v74, 1.0
	v_cvt_pk_bf16_f32 v73, v73, v74
	s_nop 0
	v_rcp_f32_e32 v68, v68
	v_div_scale_f32 v74, s[0:1], v69, v69, 1.0
	v_rcp_f32_e32 v75, v74
	s_nop 0
	v_fma_f32 v76, -v74, v75, 1.0
	v_fmac_f32_e32 v75, v76, v75
	v_div_scale_f32 v76, vcc, 1.0, v69, 1.0
	v_mul_f32_e32 v77, v76, v75
	v_fma_f32 v78, -v74, v77, v76
	v_fmac_f32_e32 v77, v78, v75
	v_fma_f32 v74, -v74, v77, v76
	v_div_fmas_f32 v74, v74, v75, v77
	v_div_fixup_f32 v69, v74, v69, 1.0
	v_cvt_pk_bf16_f32 v74, v68, v69
	v_mul_f32_e32 v68, 0xbfb8aa3b, v70
	v_exp_f32_e32 v68, v68
	s_nop 0
	v_add_f32_e32 v68, 1.0, v68
	s_nop 0
	v_rcp_f32_e32 v68, v68
	v_mul_f32_e32 v69, 0xbfb8aa3b, v71
	v_exp_f32_e32 v69, v69
	s_nop 0
	v_add_f32_e32 v69, 1.0, v69
	v_div_scale_f32 v70, s[0:1], v69, v69, 1.0
	v_rcp_f32_e32 v71, v70
	s_nop 0
	v_fma_f32 v75, -v70, v71, 1.0
	v_fmac_f32_e32 v71, v75, v71
	v_div_scale_f32 v75, vcc, 1.0, v69, 1.0
	v_mul_f32_e32 v76, v75, v71
	v_fma_f32 v77, -v70, v76, v75
	v_fmac_f32_e32 v76, v77, v71
	v_fma_f32 v70, -v70, v76, v75
	v_div_fmas_f32 v70, v70, v71, v76
	v_div_fixup_f32 v69, v70, v69, 1.0
	v_cvt_pk_bf16_f32 v75, v68, v69
	global_store_dwordx4 v[84:85], v[72:75], off offset:256
	v_add_u32_e32 v68, 0x80, v166
	v_mad_i64_i32 v[68:69], s[0:1], v68, s2, v[140:141]
	v_rcp_f32_e32 v64, v64
	v_div_scale_f32 v70, s[0:1], v65, v65, 1.0
	v_rcp_f32_e32 v71, v70
	v_lshl_add_u64 v[68:69], v[68:69], 0, v[142:143]
	v_fma_f32 v72, -v70, v71, 1.0
	v_fmac_f32_e32 v71, v72, v71
	v_div_scale_f32 v72, vcc, 1.0, v65, 1.0
	v_mul_f32_e32 v73, v72, v71
	v_fma_f32 v74, -v70, v73, v72
	v_fmac_f32_e32 v73, v74, v71
	v_fma_f32 v70, -v70, v73, v72
	v_div_fmas_f32 v70, v70, v71, v73
	v_div_fixup_f32 v65, v70, v65, 1.0
	v_cvt_pk_bf16_f32 v64, v64, v65
	v_mul_f32_e32 v65, 0xbfb8aa3b, v66
	v_exp_f32_e32 v65, v65
	s_nop 0
	v_add_f32_e32 v65, 1.0, v65
	s_nop 0
	v_rcp_f32_e32 v65, v65
	v_mul_f32_e32 v66, 0xbfb8aa3b, v67
	v_exp_f32_e32 v66, v66
	s_nop 0
	v_add_f32_e32 v66, 1.0, v66
	v_div_scale_f32 v67, s[0:1], v66, v66, 1.0
	v_rcp_f32_e32 v70, v67
	s_nop 0
	v_fma_f32 v71, -v67, v70, 1.0
	v_fmac_f32_e32 v70, v71, v70
	v_div_scale_f32 v71, vcc, 1.0, v66, 1.0
	v_mul_f32_e32 v72, v71, v70
	v_fma_f32 v73, -v67, v72, v71
	v_fmac_f32_e32 v72, v73, v70
	v_fma_f32 v67, -v67, v72, v71
	v_div_fmas_f32 v67, v67, v70, v72
	v_div_fixup_f32 v66, v67, v66, 1.0
	v_cvt_pk_bf16_f32 v65, v65, v66
	s_nop 0
	v_rcp_f32_e32 v60, v60
	v_div_scale_f32 v66, s[0:1], v61, v61, 1.0
	v_rcp_f32_e32 v67, v66
	s_nop 0
	v_fma_f32 v70, -v66, v67, 1.0
	v_fmac_f32_e32 v67, v70, v67
	v_div_scale_f32 v70, vcc, 1.0, v61, 1.0
	v_mul_f32_e32 v71, v70, v67
	v_fma_f32 v72, -v66, v71, v70
	v_fmac_f32_e32 v71, v72, v67
	v_fma_f32 v66, -v66, v71, v70
	v_div_fmas_f32 v66, v66, v67, v71
	v_div_fixup_f32 v61, v66, v61, 1.0
	v_cvt_pk_bf16_f32 v66, v60, v61
	v_mul_f32_e32 v60, 0xbfb8aa3b, v62
	v_exp_f32_e32 v60, v60
	s_nop 0
	v_add_f32_e32 v60, 1.0, v60
	s_nop 0
	v_rcp_f32_e32 v60, v60
	v_mul_f32_e32 v61, 0xbfb8aa3b, v63
	v_exp_f32_e32 v61, v61
	s_nop 0
	v_add_f32_e32 v61, 1.0, v61
	v_div_scale_f32 v62, s[0:1], v61, v61, 1.0
	v_rcp_f32_e32 v63, v62
	s_nop 0
	v_fma_f32 v67, -v62, v63, 1.0
	v_fmac_f32_e32 v63, v67, v63
	v_div_scale_f32 v67, vcc, 1.0, v61, 1.0
	v_mul_f32_e32 v70, v67, v63
	v_fma_f32 v71, -v62, v70, v67
	v_fmac_f32_e32 v70, v71, v63
	v_fma_f32 v62, -v62, v70, v67
	v_div_fmas_f32 v62, v62, v63, v70
	v_div_fixup_f32 v61, v62, v61, 1.0
	v_cvt_pk_bf16_f32 v67, v60, v61
	global_store_dwordx4 v[68:69], v[64:67], off
	v_rcp_f32_e32 v56, v56
	s_nop 0
	v_rcp_f32_e32 v57, v57
	s_nop 0
	v_cvt_pk_bf16_f32 v56, v56, v57
	v_mul_f32_e32 v57, 0xbfb8aa3b, v58
	v_exp_f32_e32 v57, v57
	s_nop 0
	v_add_f32_e32 v57, 1.0, v57
	s_nop 0
	v_rcp_f32_e32 v57, v57
	v_mul_f32_e32 v58, 0xbfb8aa3b, v59
	v_exp_f32_e32 v58, v58
	s_nop 0
	v_add_f32_e32 v58, 1.0, v58
	s_nop 0
	v_rcp_f32_e32 v58, v58
	s_nop 0
	v_cvt_pk_bf16_f32 v57, v57, v58
	s_nop 0
	v_rcp_f32_e32 v52, v52
	s_nop 0
	v_rcp_f32_e32 v53, v53
	s_nop 0
	v_cvt_pk_bf16_f32 v58, v52, v53
	v_mul_f32_e32 v52, 0xbfb8aa3b, v54
	v_exp_f32_e32 v52, v52
	s_nop 0
	v_add_f32_e32 v52, 1.0, v52
	s_nop 0
	v_rcp_f32_e32 v52, v52
	v_mul_f32_e32 v53, 0xbfb8aa3b, v55
	v_exp_f32_e32 v53, v53
	s_nop 0
	v_add_f32_e32 v53, 1.0, v53
	s_nop 0
	v_rcp_f32_e32 v53, v53
	s_nop 0
	v_cvt_pk_bf16_f32 v59, v52, v53
	global_store_dwordx4 v[68:69], v[56:59], off offset:256
	v_add_u32_e32 v52, 0x90, v166
	v_mad_i64_i32 v[52:53], s[0:1], v52, s2, v[140:141]
	v_rcp_f32_e32 v48, v48
	v_lshl_add_u64 v[52:53], v[52:53], 0, v[142:143]
	v_rcp_f32_e32 v49, v49
	s_nop 0
	v_cvt_pk_bf16_f32 v48, v48, v49
	v_mul_f32_e32 v49, 0xbfb8aa3b, v50
	v_exp_f32_e32 v49, v49
	s_nop 0
	v_add_f32_e32 v49, 1.0, v49
	s_nop 0
	v_rcp_f32_e32 v49, v49
	v_mul_f32_e32 v50, 0xbfb8aa3b, v51
	v_exp_f32_e32 v50, v50
	s_nop 0
	v_add_f32_e32 v50, 1.0, v50
	v_div_scale_f32 v51, s[0:1], v50, v50, 1.0
	v_rcp_f32_e32 v54, v51
	s_nop 0
	v_fma_f32 v55, -v51, v54, 1.0
	v_fmac_f32_e32 v54, v55, v54
	v_div_scale_f32 v55, vcc, 1.0, v50, 1.0
	v_mul_f32_e32 v56, v55, v54
	v_fma_f32 v57, -v51, v56, v55
	v_fmac_f32_e32 v56, v57, v54
	v_fma_f32 v51, -v51, v56, v55
	v_div_fmas_f32 v51, v51, v54, v56
	v_div_fixup_f32 v50, v51, v50, 1.0
	v_cvt_pk_bf16_f32 v49, v49, v50
	s_nop 0
	v_rcp_f32_e32 v44, v44
	v_div_scale_f32 v50, s[0:1], v45, v45, 1.0
	v_rcp_f32_e32 v51, v50
	s_nop 0
	v_fma_f32 v54, -v50, v51, 1.0
	v_fmac_f32_e32 v51, v54, v51
	v_div_scale_f32 v54, vcc, 1.0, v45, 1.0
	v_mul_f32_e32 v55, v54, v51
	v_fma_f32 v56, -v50, v55, v54
	v_fmac_f32_e32 v55, v56, v51
	v_fma_f32 v50, -v50, v55, v54
	v_div_fmas_f32 v50, v50, v51, v55
	v_div_fixup_f32 v45, v50, v45, 1.0
	v_cvt_pk_bf16_f32 v50, v44, v45
	v_mul_f32_e32 v44, 0xbfb8aa3b, v46
	v_exp_f32_e32 v44, v44
	s_nop 0
	v_add_f32_e32 v44, 1.0, v44
	s_nop 0
	v_rcp_f32_e32 v44, v44
	v_mul_f32_e32 v45, 0xbfb8aa3b, v47
	v_exp_f32_e32 v45, v45
	s_nop 0
	v_add_f32_e32 v45, 1.0, v45
	s_nop 0
	v_rcp_f32_e32 v45, v45
	s_nop 0
	v_cvt_pk_bf16_f32 v51, v44, v45
	global_store_dwordx4 v[52:53], v[48:51], off
	v_rcp_f32_e32 v40, v40
	v_div_scale_f32 v44, s[0:1], v41, v41, 1.0
	v_rcp_f32_e32 v45, v44
	s_nop 0
	v_fma_f32 v46, -v44, v45, 1.0
	v_fmac_f32_e32 v45, v46, v45
	v_div_scale_f32 v46, vcc, 1.0, v41, 1.0
	v_mul_f32_e32 v47, v46, v45
	v_fma_f32 v48, -v44, v47, v46
	v_fmac_f32_e32 v47, v48, v45
	v_fma_f32 v44, -v44, v47, v46
	v_div_fmas_f32 v44, v44, v45, v47
	v_div_fixup_f32 v41, v44, v41, 1.0
	v_cvt_pk_bf16_f32 v40, v40, v41
	v_mul_f32_e32 v41, 0xbfb8aa3b, v42
	v_exp_f32_e32 v41, v41
	s_nop 0
	v_add_f32_e32 v41, 1.0, v41
	s_nop 0
	v_rcp_f32_e32 v41, v41
	v_mul_f32_e32 v42, 0xbfb8aa3b, v43
	v_exp_f32_e32 v42, v42
	s_nop 0
	v_add_f32_e32 v42, 1.0, v42
	s_nop 0
	v_rcp_f32_e32 v42, v42
	s_nop 0
	v_cvt_pk_bf16_f32 v41, v41, v42
	s_nop 0
	v_rcp_f32_e32 v36, v36
	s_nop 0
	v_rcp_f32_e32 v37, v37
	s_nop 0
	v_cvt_pk_bf16_f32 v42, v36, v37
	v_mul_f32_e32 v36, 0xbfb8aa3b, v38
	v_exp_f32_e32 v36, v36
	s_nop 0
	v_add_f32_e32 v36, 1.0, v36
	s_nop 0
	v_rcp_f32_e32 v36, v36
	v_mul_f32_e32 v37, 0xbfb8aa3b, v39
	v_exp_f32_e32 v37, v37
	s_nop 0
	v_add_f32_e32 v37, 1.0, v37
	s_nop 0
	v_rcp_f32_e32 v37, v37
	s_nop 0
	v_cvt_pk_bf16_f32 v43, v36, v37
	global_store_dwordx4 v[52:53], v[40:43], off offset:256
	v_add_u32_e32 v36, 0xa0, v166
	v_mad_i64_i32 v[36:37], s[0:1], v36, s2, v[140:141]
	v_rcp_f32_e32 v32, v32
	v_lshl_add_u64 v[36:37], v[36:37], 0, v[142:143]
	v_rcp_f32_e32 v33, v33
	s_nop 0
	v_cvt_pk_bf16_f32 v32, v32, v33
	v_mul_f32_e32 v33, 0xbfb8aa3b, v34
	v_exp_f32_e32 v33, v33
	s_nop 0
	v_add_f32_e32 v33, 1.0, v33
	s_nop 0
	v_rcp_f32_e32 v33, v33
	v_mul_f32_e32 v34, 0xbfb8aa3b, v35
	v_exp_f32_e32 v34, v34
	s_nop 0
	v_add_f32_e32 v34, 1.0, v34
	s_nop 0
	v_rcp_f32_e32 v34, v34
	s_nop 0
	v_cvt_pk_bf16_f32 v33, v33, v34
	s_nop 0
	v_rcp_f32_e32 v24, v24
	s_nop 0
	v_rcp_f32_e32 v25, v25
	s_nop 0
	v_cvt_pk_bf16_f32 v34, v24, v25
	v_mul_f32_e32 v24, 0xbfb8aa3b, v26
	v_exp_f32_e32 v24, v24
	s_nop 0
	v_add_f32_e32 v24, 1.0, v24
	s_nop 0
	v_rcp_f32_e32 v24, v24
	v_mul_f32_e32 v25, 0xbfb8aa3b, v27
	v_exp_f32_e32 v25, v25
	s_nop 0
	v_add_f32_e32 v25, 1.0, v25
	s_nop 0
	v_rcp_f32_e32 v25, v25
	s_nop 0
	v_cvt_pk_bf16_f32 v35, v24, v25
	global_store_dwordx4 v[36:37], v[32:35], off
	v_rcp_f32_e32 v20, v20
	s_nop 0
	v_rcp_f32_e32 v21, v21
	s_nop 0
	v_cvt_pk_bf16_f32 v20, v20, v21
	v_mul_f32_e32 v21, 0xbfb8aa3b, v22
	v_exp_f32_e32 v21, v21
	s_nop 0
	v_add_f32_e32 v21, 1.0, v21
	s_nop 0
	v_rcp_f32_e32 v21, v21
	v_mul_f32_e32 v22, 0xbfb8aa3b, v23
	v_exp_f32_e32 v22, v22
	s_nop 0
	v_add_f32_e32 v22, 1.0, v22
	s_nop 0
	v_rcp_f32_e32 v22, v22
	s_nop 0
	v_cvt_pk_bf16_f32 v21, v21, v22
	s_nop 0
	v_rcp_f32_e32 v16, v16
	s_nop 0
	v_rcp_f32_e32 v17, v17
	s_nop 0
	v_cvt_pk_bf16_f32 v22, v16, v17
	v_mul_f32_e32 v16, 0xbfb8aa3b, v18
	v_exp_f32_e32 v16, v16
	s_nop 0
	v_add_f32_e32 v16, 1.0, v16
	s_nop 0
	v_rcp_f32_e32 v16, v16
	v_mul_f32_e32 v17, 0xbfb8aa3b, v19
	v_exp_f32_e32 v17, v17
	s_nop 0
	v_add_f32_e32 v17, 1.0, v17
	s_nop 0
	v_rcp_f32_e32 v17, v17
	s_nop 0
	v_cvt_pk_bf16_f32 v23, v16, v17
	global_store_dwordx4 v[36:37], v[20:23], off offset:256
	v_add_u32_e32 v16, 0xb0, v166
	v_mad_i64_i32 v[16:17], s[0:1], v16, s2, v[140:141]
	v_rcp_f32_e32 v12, v12
	v_div_scale_f32 v18, s[0:1], v13, v13, 1.0
	v_rcp_f32_e32 v19, v18
	v_lshl_add_u64 v[16:17], v[16:17], 0, v[142:143]
	v_fma_f32 v20, -v18, v19, 1.0
	v_fmac_f32_e32 v19, v20, v19
	v_div_scale_f32 v20, vcc, 1.0, v13, 1.0
	v_mul_f32_e32 v21, v20, v19
	v_fma_f32 v22, -v18, v21, v20
	v_fmac_f32_e32 v21, v22, v19
	v_fma_f32 v18, -v18, v21, v20
	v_div_fmas_f32 v18, v18, v19, v21
	v_div_fixup_f32 v13, v18, v13, 1.0
	v_cvt_pk_bf16_f32 v12, v12, v13
	v_mul_f32_e32 v13, 0xbfb8aa3b, v14
	v_exp_f32_e32 v13, v13
	s_nop 0
	v_add_f32_e32 v13, 1.0, v13
	s_nop 0
	v_rcp_f32_e32 v13, v13
	v_mul_f32_e32 v14, 0xbfb8aa3b, v15
	v_exp_f32_e32 v14, v14
	s_nop 0
	v_add_f32_e32 v14, 1.0, v14
	v_div_scale_f32 v15, s[0:1], v14, v14, 1.0
	v_rcp_f32_e32 v18, v15
	s_nop 0
	v_fma_f32 v19, -v15, v18, 1.0
	v_fmac_f32_e32 v18, v19, v18
	v_div_scale_f32 v19, vcc, 1.0, v14, 1.0
	v_mul_f32_e32 v20, v19, v18
	v_fma_f32 v21, -v15, v20, v19
	v_fmac_f32_e32 v20, v21, v18
	v_fma_f32 v15, -v15, v20, v19
	v_div_fmas_f32 v15, v15, v18, v20
	v_div_fixup_f32 v14, v15, v14, 1.0
	v_cvt_pk_bf16_f32 v13, v13, v14
	s_nop 0
	v_rcp_f32_e32 v8, v8
	s_nop 0
	v_rcp_f32_e32 v9, v9
	s_nop 0
	v_cvt_pk_bf16_f32 v14, v8, v9
	v_mul_f32_e32 v8, 0xbfb8aa3b, v10
	v_exp_f32_e32 v8, v8
	s_nop 0
	v_add_f32_e32 v8, 1.0, v8
	s_nop 0
	v_rcp_f32_e32 v8, v8
	v_mul_f32_e32 v9, 0xbfb8aa3b, v11
	v_exp_f32_e32 v9, v9
	s_nop 0
	v_add_f32_e32 v9, 1.0, v9
	s_nop 0
	v_rcp_f32_e32 v9, v9
	s_nop 0
	v_cvt_pk_bf16_f32 v15, v8, v9
	global_store_dwordx4 v[16:17], v[12:15], off
	v_rcp_f32_e32 v4, v4
	v_div_scale_f32 v8, s[0:1], v5, v5, 1.0
	v_rcp_f32_e32 v9, v8
	s_nop 0
	v_fma_f32 v10, -v8, v9, 1.0
	v_fmac_f32_e32 v9, v10, v9
	v_div_scale_f32 v10, vcc, 1.0, v5, 1.0
	v_mul_f32_e32 v11, v10, v9
	v_fma_f32 v12, -v8, v11, v10
	v_fmac_f32_e32 v11, v12, v9
	v_fma_f32 v8, -v8, v11, v10
	v_div_fmas_f32 v8, v8, v9, v11
	v_div_fixup_f32 v5, v8, v5, 1.0
	v_cvt_pk_bf16_f32 v4, v4, v5
	v_mul_f32_e32 v5, 0xbfb8aa3b, v6
	v_exp_f32_e32 v5, v5
	s_nop 0
	v_add_f32_e32 v5, 1.0, v5
	s_nop 0
	v_rcp_f32_e32 v5, v5
	v_mul_f32_e32 v6, 0xbfb8aa3b, v7
	v_exp_f32_e32 v6, v6
	s_nop 0
	v_add_f32_e32 v6, 1.0, v6
	v_div_scale_f32 v7, s[0:1], v6, v6, 1.0
	v_rcp_f32_e32 v8, v7
	s_nop 0
	v_fma_f32 v9, -v7, v8, 1.0
	v_fmac_f32_e32 v8, v9, v8
	v_div_scale_f32 v9, vcc, 1.0, v6, 1.0
	v_mul_f32_e32 v10, v9, v8
	v_fma_f32 v11, -v7, v10, v9
	v_fmac_f32_e32 v10, v11, v8
	v_fma_f32 v7, -v7, v10, v9
	v_div_fmas_f32 v7, v7, v8, v10
	v_div_fixup_f32 v6, v7, v6, 1.0
	v_cvt_pk_bf16_f32 v5, v5, v6
	s_nop 0
	v_rcp_f32_e32 v0, v0
	v_div_scale_f32 v6, s[0:1], v1, v1, 1.0
	v_rcp_f32_e32 v7, v6
	s_nop 0
	v_fma_f32 v8, -v6, v7, 1.0
	v_fmac_f32_e32 v7, v8, v7
	v_div_scale_f32 v8, vcc, 1.0, v1, 1.0
	v_mul_f32_e32 v9, v8, v7
	v_fma_f32 v10, -v6, v9, v8
	v_fmac_f32_e32 v9, v10, v7
	v_fma_f32 v6, -v6, v9, v8
	v_div_fmas_f32 v6, v6, v7, v9
	v_div_fixup_f32 v1, v6, v1, 1.0
	v_cvt_pk_bf16_f32 v6, v0, v1
	v_mul_f32_e32 v0, 0xbfb8aa3b, v2
	v_exp_f32_e32 v0, v0
	s_nop 0
	v_add_f32_e32 v0, 1.0, v0
	s_nop 0
	v_rcp_f32_e32 v0, v0
	v_mul_f32_e32 v1, 0xbfb8aa3b, v3
	v_exp_f32_e32 v1, v1
	s_nop 0
	v_add_f32_e32 v1, 1.0, v1
	v_div_scale_f32 v2, s[0:1], v1, v1, 1.0
	v_rcp_f32_e32 v3, v2
	s_mov_b64 s[0:1], -1
	v_fma_f32 v7, -v2, v3, 1.0
	v_fmac_f32_e32 v3, v7, v3
	v_div_scale_f32 v7, vcc, 1.0, v1, 1.0
	v_mul_f32_e32 v8, v7, v3
	v_fma_f32 v9, -v2, v8, v7
	v_fmac_f32_e32 v8, v9, v3
	v_fma_f32 v2, -v2, v8, v7
	v_div_fmas_f32 v2, v2, v3, v8
	s_and_b64 vcc, exec, s[40:41]
	v_div_fixup_f32 v1, v2, v1, 1.0
	v_cvt_pk_bf16_f32 v7, v0, v1
	global_store_dwordx4 v[16:17], v[4:7], off offset:256
	s_cbranch_vccnz .LBB0_410
	s_andn2_b64 vcc, exec, s[48:49]
	s_cbranch_vccnz .LBB0_409
	s_barrier
	s_branch .LBB0_409

.LBB0_485:
	s_ashr_i32 s0, s4, 2
	s_mul_hi_i32 s1, s0, 0x3080
	s_mulk_i32 s0, 0x3080
	s_add_u32 s5, s34, s0
	s_addc_u32 s1, s35, s1
	s_and_b32 s0, s10, 0x180
	s_lshl_b32 s6, s0, 1
	s_add_u32 s6, s5, s6
	s_addc_u32 s7, s1, 0
	v_lshl_add_u64 v[0:1], s[6:7], 0, v[30:31]
	s_movk_i32 s14, 0x1000
	v_add_co_u32_e32 v4, vcc, s14, v0
	s_movk_i32 s15, 0x2000
	s_nop 0
	v_addc_co_u32_e32 v5, vcc, 0, v1, vcc
	global_load_dword v23, v[4:5], off offset:3584
	v_add_co_u32_e32 v0, vcc, s15, v0
	s_add_i32 s1, s12, s4
	s_nop 0
	v_addc_co_u32_e32 v1, vcc, 0, v1, vcc
	global_load_dword v32, v[0:1], off offset:512
	s_cmp_lt_i32 s1, 0x10000
	s_cselect_b32 s5, s1, s4
	s_ashr_i32 s6, s5, 2
	s_mul_hi_i32 s7, s6, 0x3080
	s_mulk_i32 s6, 0x3080
	s_add_u32 s6, s34, s6
	s_addc_u32 s7, s35, s7
	s_lshl_b32 s5, s5, 8
	s_and_b32 s5, s5, 0x300
	s_add_u32 s6, s6, s5
	s_addc_u32 s7, s7, 0
	s_add_i32 s5, s12, s1
	s_cmp_lt_i32 s5, 0x10000
	s_cselect_b64 s[8:9], -1, 0
	v_lshl_add_u64 v[8:9], s[6:7], 0, v[30:31]
	s_and_b64 s[6:7], s[8:9], exec
	s_cselect_b32 s6, s5, s4
	s_ashr_i32 s7, s6, 2
	s_mul_hi_i32 s11, s7, 0x3080
	s_mulk_i32 s7, 0x3080
	s_add_u32 s7, s34, s7
	s_addc_u32 s11, s35, s11
	s_lshl_b32 s6, s6, 8
	s_and_b32 s6, s6, 0x300
	s_add_u32 s6, s7, s6
	s_addc_u32 s7, s11, 0
	s_add_i32 s11, s12, s5
	s_cmp_lt_i32 s11, 0x10000
	s_waitcnt lgkmcnt(0)
	v_lshl_add_u64 v[6:7], s[6:7], 0, v[30:31]
	s_cselect_b64 s[6:7], -1, 0
	s_and_b64 s[12:13], s[6:7], exec
	s_cselect_b32 s4, s11, s4
	v_add_co_u32_e32 v2, vcc, s14, v8
	s_ashr_i32 s5, s4, 2
	s_nop 0
	v_addc_co_u32_e32 v3, vcc, 0, v9, vcc
	s_mul_hi_i32 s12, s5, 0x3080
	s_mulk_i32 s5, 0x3080
	v_add_co_u32_e32 v10, vcc, s15, v8
	s_add_u32 s5, s34, s5
	s_nop 0
	v_addc_co_u32_e32 v11, vcc, 0, v9, vcc
	s_addc_u32 s12, s35, s12
	s_lshl_b32 s4, s4, 8
	v_add_co_u32_e32 v20, vcc, s14, v6
	s_and_b32 s4, s4, 0x300
	s_nop 0
	v_addc_co_u32_e32 v21, vcc, 0, v7, vcc
	s_add_u32 s4, s5, s4
	v_add_co_u32_e32 v24, vcc, s15, v6
	s_addc_u32 s5, s12, 0
	s_nop 0
	v_addc_co_u32_e32 v25, vcc, 0, v7, vcc
	v_lshl_add_u64 v[0:1], s[4:5], 0, v[30:31]
	v_add_co_u32_e32 v26, vcc, s14, v0
	s_cmp_gt_i32 s1, 0xffff
	s_nop 0
	v_addc_co_u32_e32 v27, vcc, 0, v1, vcc
	v_add_co_u32_e32 v28, vcc, s15, v0
	s_nop 1
	v_addc_co_u32_e32 v29, vcc, 0, v1, vcc
	global_load_dword v33, v[2:3], off offset:3584
	s_nop 0
	global_load_dword v10, v[10:11], off offset:512
	s_nop 0
	global_load_dword v22, v[20:21], off offset:3584
	s_nop 0
	global_load_dword v21, v[24:25], off offset:512
	global_load_dword v20, v[26:27], off offset:3584
	global_load_dword v19, v[28:29], off offset:512
	v_or_b32_e32 v11, s0, v18
	s_mov_b32 s0, 0xf800000
	s_waitcnt vmcnt(0)
	v_lshlrev_b32_e32 v25, 16, v23
	v_and_b32_e32 v27, 0xffff0000, v23
	v_mov_b32_e32 v2, v25
	v_mov_b32_e32 v3, v27
	v_pk_mul_f32 v[2:3], v[2:3], v[2:3]
	v_and_b32_e32 v26, 0xffff0000, v32
	v_add_f32_e32 v2, v2, v3
	ds_bpermute_b32 v3, v12, v2
	v_mul_f32_e32 v29, 0xbfb8aa3b, v26
	v_exp_f32_e32 v29, v29
	v_lshlrev_b32_e32 v24, 16, v32
	s_waitcnt lgkmcnt(0)
	v_add_f32_e32 v23, v2, v3
	ds_bpermute_b32 v28, v13, v23
	v_lshlrev_b32_e32 v2, 2, v11
	global_load_dwordx2 v[2:3], v2, s[2:3]
	v_add_f32_e32 v29, 1.0, v29
	s_waitcnt lgkmcnt(0)
	v_add_f32_e32 v11, v23, v28
	ds_bpermute_b32 v23, v14, v11
	v_mul_f32_e32 v28, 0xbfb8aa3b, v24
	v_exp_f32_e32 v28, v28
	s_waitcnt lgkmcnt(0)
	v_add_f32_e32 v11, v11, v23
	ds_bpermute_b32 v23, v15, v11
	v_add_f32_e32 v35, 1.0, v28
	s_waitcnt lgkmcnt(0)
	v_add_f32_e32 v11, v11, v23
	ds_bpermute_b32 v23, v16, v11
	s_waitcnt lgkmcnt(0)
	v_add_f32_e32 v11, v11, v23
	ds_bpermute_b32 v23, v17, v11
	v_rcp_f32_e32 v28, v29
	s_waitcnt lgkmcnt(0)
	v_add_f32_e32 v11, v11, v23
	v_fmamk_f32 v11, v11, 0x3c000000, v188
	v_mul_f32_e32 v23, 0x4f800000, v11
	v_cmp_gt_f32_e64 s[0:1], s0, v11
	s_nop 1
	v_cndmask_b32_e64 v11, v11, v23, s[0:1]
	v_sqrt_f32_e32 v23, v11
	s_nop 0
	v_add_u32_e32 v32, -1, v23
	v_fma_f32 v37, -v32, v23, v11
	v_cmp_ge_f32_e64 s[4:5], 0, v37
	v_add_u32_e32 v37, 1, v23
	s_nop 0
	v_cndmask_b32_e64 v32, v23, v32, s[4:5]
	v_fma_f32 v23, -v37, v23, v11
	v_cmp_lt_f32_e64 s[4:5], 0, v23
	s_nop 1
	v_cndmask_b32_e64 v23, v32, v37, s[4:5]
	v_mul_f32_e32 v32, 0x37800000, v23
	v_cndmask_b32_e64 v23, v23, v32, s[0:1]
	v_cmp_class_f32_e64 s[0:1], v11, v189
	s_nop 1
	v_cndmask_b32_e64 v32, v23, v11, s[0:1]
	v_and_b32_e32 v23, 0xffff0000, v33
	v_lshlrev_b32_e32 v11, 16, v33
	v_mul_f32_e32 v34, v23, v23
	v_fmac_f32_e32 v34, v11, v11
	ds_bpermute_b32 v36, v12, v34
	v_rcp_f32_e32 v33, v32
	s_waitcnt lgkmcnt(0)
	v_add_f32_e32 v29, v34, v36
	ds_bpermute_b32 v32, v13, v29
	s_waitcnt lgkmcnt(0)
	v_add_f32_e32 v29, v29, v32
	ds_bpermute_b32 v32, v14, v29
	s_waitcnt lgkmcnt(0)
	v_add_f32_e32 v37, v29, v32
	ds_bpermute_b32 v39, v15, v37
	v_rcp_f32_e32 v32, v35
	v_mov_b32_e32 v29, v33
	v_pk_mul_f32 v[26:27], v[28:29], v[26:27]
	s_waitcnt lgkmcnt(0)
	v_add_f32_e32 v34, v37, v39
	ds_bpermute_b32 v35, v16, v34
	s_waitcnt vmcnt(0)
	v_mul_f32_e32 v27, v3, v27
	v_mul_f32_e32 v28, v26, v27
	v_pk_mul_f32 v[26:27], v[32:33], v[24:25]
	s_waitcnt lgkmcnt(0)
	v_add_f32_e32 v24, v34, v35
	ds_bpermute_b32 v25, v17, v24
	v_mul_f32_e32 v27, v2, v27
	v_mul_f32_e32 v26, v26, v27
	v_cvt_pk_bf16_f32 v26, v26, v28
	global_store_dword v[4:5], v26, off offset:3584
	s_cbranch_scc1 .LBB0_487
	v_and_b32_e32 v26, 0xffff0000, v10
	v_mul_f32_e32 v4, 0xbfb8aa3b, v26
	v_exp_f32_e32 v27, v4
	s_mov_b64 s[0:1], 0x1e00
	v_lshl_add_u64 v[4:5], v[8:9], 0, s[0:1]
	s_waitcnt lgkmcnt(0)
	v_add_f32_e32 v24, v24, v25
	v_add_f32_e32 v8, 1.0, v27
	v_fmamk_f32 v24, v24, 0x3c000000, v188
	s_mov_b32 s0, 0xf800000
	v_mul_f32_e32 v25, 0x4f800000, v24
	v_cmp_gt_f32_e32 vcc, s0, v24
	v_lshlrev_b32_e32 v10, 16, v10
	v_mul_f32_e32 v27, 0xbfb8aa3b, v10
	v_cndmask_b32_e32 v24, v24, v25, vcc
	v_sqrt_f32_e32 v25, v24
	v_rcp_f32_e32 v8, v8
	v_exp_f32_e32 v27, v27
	v_mul_f32_e32 v26, v8, v26
	v_add_u32_e32 v28, -1, v25
	v_fma_f32 v29, -v28, v25, v24
	v_cmp_ge_f32_e64 s[0:1], 0, v29
	v_add_u32_e32 v29, 1, v25
	v_add_f32_e32 v27, 1.0, v27
	v_cndmask_b32_e64 v28, v25, v28, s[0:1]
	v_fma_f32 v25, -v29, v25, v24
	v_cmp_lt_f32_e64 s[0:1], 0, v25
	s_nop 1
	v_cndmask_b32_e64 v25, v28, v29, s[0:1]
	v_mul_f32_e32 v28, 0x37800000, v25
	v_cndmask_b32_e32 v25, v25, v28, vcc
	v_cmp_class_f32_e32 vcc, v24, v189
	s_nop 1
	v_cndmask_b32_e32 v24, v25, v24, vcc
	s_nop 0
	v_rcp_f32_e32 v9, v24
	s_nop 0
	v_mul_f32_e32 v23, v9, v23
	v_rcp_f32_e32 v8, v27
	s_nop 0
	v_pk_mul_f32 v[8:9], v[8:9], v[10:11]
	v_mul_f32_e32 v23, v23, v3
	v_mul_f32_e32 v9, v9, v2
	v_mul_f32_e32 v8, v8, v9
	v_mul_f32_e32 v23, v26, v23
	v_cvt_pk_bf16_f32 v8, v8, v23
	global_store_dword v[4:5], v8, off
.LBB0_487:
	v_and_b32_e32 v8, 0xffff0000, v22
	v_lshlrev_b32_e32 v5, 16, v22
	v_mul_f32_e32 v4, v8, v8
	v_fmac_f32_e32 v4, v5, v5
	ds_bpermute_b32 v9, v12, v4
	s_andn2_b64 vcc, exec, s[8:9]
	s_waitcnt lgkmcnt(0)
	v_add_f32_e32 v4, v4, v9
	ds_bpermute_b32 v9, v13, v4
	s_waitcnt lgkmcnt(0)
	v_add_f32_e32 v4, v4, v9
	ds_bpermute_b32 v9, v14, v4
	s_waitcnt lgkmcnt(0)
	v_add_f32_e32 v4, v4, v9
	ds_bpermute_b32 v9, v15, v4
	s_waitcnt lgkmcnt(0)
	v_add_f32_e32 v4, v4, v9
	ds_bpermute_b32 v9, v16, v4
	s_waitcnt lgkmcnt(0)
	v_add_f32_e32 v4, v4, v9
	ds_bpermute_b32 v9, v17, v4
	s_cbranch_vccnz .LBB0_489
	v_and_b32_e32 v10, 0xffff0000, v21
	v_mul_f32_e32 v11, 0xbfb8aa3b, v10
	v_exp_f32_e32 v11, v11
	s_mov_b64 s[0:1], 0x1e00
	v_lshl_add_u64 v[6:7], v[6:7], 0, s[0:1]
	s_waitcnt lgkmcnt(0)
	v_add_f32_e32 v4, v4, v9
	v_add_f32_e32 v11, 1.0, v11
	v_fmamk_f32 v4, v4, 0x3c000000, v188
	s_mov_b32 s0, 0xf800000
	v_mul_f32_e32 v22, 0x4f800000, v4
	v_cmp_gt_f32_e32 vcc, s0, v4
	v_rcp_f32_e32 v9, v11
	s_nop 0
	v_mul_f32_e32 v9, v9, v10
	v_cndmask_b32_e32 v22, v4, v22, vcc
	v_sqrt_f32_e32 v23, v22
	v_lshlrev_b32_e32 v4, 16, v21
	v_mul_f32_e32 v21, 0xbfb8aa3b, v4
	v_exp_f32_e32 v21, v21
	v_add_u32_e32 v24, -1, v23
	v_fma_f32 v25, -v24, v23, v22
	v_cmp_ge_f32_e64 s[0:1], 0, v25
	v_add_u32_e32 v25, 1, v23
	v_add_f32_e32 v21, 1.0, v21
	v_cndmask_b32_e64 v24, v23, v24, s[0:1]
	v_fma_f32 v23, -v25, v23, v22
	v_cmp_lt_f32_e64 s[0:1], 0, v23
	s_nop 1
	v_cndmask_b32_e64 v23, v24, v25, s[0:1]
	v_mul_f32_e32 v24, 0x37800000, v23
	v_cndmask_b32_e32 v23, v23, v24, vcc
	v_cmp_class_f32_e32 vcc, v22, v189
	s_nop 1
	v_cndmask_b32_e32 v22, v23, v22, vcc
	s_nop 0
	v_div_scale_f32 v23, s[0:1], v21, v21, 1.0
	v_rcp_f32_e32 v25, v23
	v_rcp_f32_e32 v11, v22
	s_nop 0
	v_mul_f32_e32 v8, v11, v8
	v_fma_f32 v10, -v23, v25, 1.0
	v_fmac_f32_e32 v25, v10, v25
	v_div_scale_f32 v10, vcc, 1.0, v21, 1.0
	v_mul_f32_e32 v22, v10, v25
	v_fma_f32 v24, -v23, v22, v10
	v_fmac_f32_e32 v22, v24, v25
	v_fma_f32 v10, -v23, v22, v10
	v_div_fmas_f32 v10, v10, v25, v22
	v_div_fixup_f32 v10, v10, v21, 1.0
	v_pk_mul_f32 v[4:5], v[10:11], v[4:5]
	v_mul_f32_e32 v8, v8, v3
	v_mul_f32_e32 v5, v5, v2
	v_mul_f32_e32 v4, v4, v5
	v_mul_f32_e32 v8, v9, v8
	v_cvt_pk_bf16_f32 v4, v4, v8
	global_store_dword v[6:7], v4, off
.LBB0_489:
	v_and_b32_e32 v6, 0xffff0000, v20
	v_lshlrev_b32_e32 v5, 16, v20
	v_mul_f32_e32 v4, v6, v6
	v_fmac_f32_e32 v4, v5, v5
	ds_bpermute_b32 v7, v12, v4
	s_andn2_b64 vcc, exec, s[6:7]
	s_waitcnt lgkmcnt(0)
	v_add_f32_e32 v4, v4, v7
	ds_bpermute_b32 v7, v13, v4
	s_waitcnt lgkmcnt(0)
	v_add_f32_e32 v4, v4, v7
	ds_bpermute_b32 v7, v14, v4
	s_waitcnt lgkmcnt(0)
	v_add_f32_e32 v4, v4, v7
	ds_bpermute_b32 v7, v15, v4
	s_waitcnt lgkmcnt(0)
	v_add_f32_e32 v4, v4, v7
	ds_bpermute_b32 v7, v16, v4
	s_waitcnt lgkmcnt(0)
	v_add_f32_e32 v4, v4, v7
	ds_bpermute_b32 v7, v17, v4
	s_cbranch_vccnz .LBB0_484
	v_and_b32_e32 v8, 0xffff0000, v19
	v_mul_f32_e32 v9, 0xbfb8aa3b, v8
	v_exp_f32_e32 v9, v9
	s_mov_b64 s[0:1], 0x1e00
	v_lshl_add_u64 v[0:1], v[0:1], 0, s[0:1]
	s_waitcnt lgkmcnt(0)
	v_add_f32_e32 v4, v4, v7
	v_add_f32_e32 v9, 1.0, v9
	v_fmamk_f32 v4, v4, 0x3c000000, v188
	s_mov_b32 s0, 0xf800000
	v_mul_f32_e32 v10, 0x4f800000, v4
	v_cmp_gt_f32_e32 vcc, s0, v4
	v_rcp_f32_e32 v7, v9
	s_nop 0
	v_mul_f32_e32 v7, v7, v8
	v_cndmask_b32_e32 v10, v4, v10, vcc
	v_sqrt_f32_e32 v11, v10
	v_lshlrev_b32_e32 v4, 16, v19
	v_mul_f32_e32 v19, 0xbfb8aa3b, v4
	v_exp_f32_e32 v19, v19
	v_add_u32_e32 v20, -1, v11
	v_fma_f32 v21, -v20, v11, v10
	v_cmp_ge_f32_e64 s[0:1], 0, v21
	v_add_u32_e32 v21, 1, v11
	v_add_f32_e32 v19, 1.0, v19
	v_cndmask_b32_e64 v20, v11, v20, s[0:1]
	v_fma_f32 v11, -v21, v11, v10
	v_cmp_lt_f32_e64 s[0:1], 0, v11
	s_nop 1
	v_cndmask_b32_e64 v11, v20, v21, s[0:1]
	v_mul_f32_e32 v20, 0x37800000, v11
	v_cndmask_b32_e32 v11, v11, v20, vcc
	v_cmp_class_f32_e32 vcc, v10, v189
	s_nop 1
	v_cndmask_b32_e32 v10, v11, v10, vcc
	s_nop 0
	v_div_scale_f32 v11, s[0:1], v19, v19, 1.0
	v_rcp_f32_e32 v21, v11
	v_rcp_f32_e32 v9, v10
	s_nop 0
	v_mul_f32_e32 v6, v9, v6
	v_fma_f32 v8, -v11, v21, 1.0
	v_fmac_f32_e32 v21, v8, v21
	v_div_scale_f32 v8, vcc, 1.0, v19, 1.0
	v_mul_f32_e32 v10, v8, v21
	v_fma_f32 v20, -v11, v10, v8
	v_fmac_f32_e32 v10, v20, v21
	v_fma_f32 v8, -v11, v10, v8
	v_div_fmas_f32 v8, v8, v21, v10
	v_div_fixup_f32 v8, v8, v19, 1.0
	v_pk_mul_f32 v[4:5], v[8:9], v[4:5]
	v_mul_f32_e32 v3, v6, v3
	v_mul_f32_e32 v2, v5, v2
	v_mul_f32_e32 v2, v4, v2
	v_mul_f32_e32 v3, v7, v3
	v_cvt_pk_bf16_f32 v2, v2, v3
	global_store_dword v[0:1], v2, off
	s_branch .LBB0_484

.LBB0_507:
	v_mov_b32_e32 v52, v161
	s_cmp_gt_i32 s20, 63
	s_mov_b64 s[0:1], -1
	s_cbranch_scc0 .LBB0_571
	s_movk_i32 s0, 0x80
	s_bfe_u32 s2, s20, 0x20001
	v_cmp_gt_i32_e32 vcc, s0, v52
	s_and_saveexec_b64 s[0:1], vcc
	s_cbranch_execz .LBB0_512
	s_waitcnt vmcnt(0)
	v_mov_b32_e32 v0, 0
	s_andn2_b64 vcc, exec, s[6:7]
	s_cbranch_vccnz .LBB0_511
	v_lshl_add_u32 v0, s2, 7, v52
	v_readlane_b32 s40, v254, 26
	v_ashrrev_i32_e32 v1, 31, v0
	v_readlane_b32 s52, v254, 38
	v_readlane_b32 s53, v254, 39
	v_readlane_b32 s41, v254, 27
	v_readlane_b32 s42, v254, 28
	v_lshl_add_u64 v[0:1], v[0:1], 2, s[52:53]
	global_load_dword v2, v[0:1], off
	s_nop 0
	global_load_dword v0, v[0:1], off offset:2048
	v_readlane_b32 s43, v254, 29
	v_readlane_b32 s44, v254, 30
	v_readlane_b32 s45, v254, 31
	v_readlane_b32 s46, v254, 32
	v_readlane_b32 s47, v254, 33
	v_readlane_b32 s48, v254, 34
	v_readlane_b32 s49, v254, 35
	v_readlane_b32 s50, v254, 36
	v_readlane_b32 s51, v254, 37
	v_readlane_b32 s54, v254, 40
	v_readlane_b32 s55, v254, 41
	s_waitcnt vmcnt(0)
	v_sub_f32_e32 v0, v2, v0
	v_mul_f32_e32 v0, 0x3fb8aa3b, v0
	v_exp_f32_e32 v0, v0
	s_nop 0
	v_add_f32_e32 v0, 1.0, v0
	v_rcp_f32_e32 v0, v0

.LBB0_550:
	s_waitcnt vmcnt(0)
	v_lshlrev_b32_e32 v12, 16, v0
	v_and_b32_e32 v13, 0xffff0000, v0
	v_lshlrev_b32_e32 v14, 16, v1
	v_and_b32_e32 v15, 0xffff0000, v1
	v_lshlrev_b32_e32 v18, 16, v2
	v_and_b32_e32 v19, 0xffff0000, v2
	v_lshlrev_b32_e32 v20, 16, v3
	v_and_b32_e32 v21, 0xffff0000, v3
	s_and_saveexec_b64 s[8:9], s[54:55]
	s_xor_b64 s[8:9], exec, s[8:9]
	s_or_saveexec_b64 s[8:9], s[8:9]
	v_mov_b32_e32 v16, v64
	s_xor_b64 exec, exec, s[8:9]
	s_cbranch_execz .LBB0_552
	v_mul_f32_e32 v12, 0xbfb8aa3b, v12
	v_exp_f32_e32 v56, v12
	v_mul_f32_e32 v12, 0xbfb8aa3b, v13
	v_exp_f32_e32 v57, v12
	v_mul_f32_e32 v12, 0xbfb8aa3b, v14
	v_exp_f32_e32 v70, v12
	v_mul_f32_e32 v12, 0xbfb8aa3b, v15
	v_pk_add_f32 v[56:57], v[56:57], 1.0 op_sel_hi:[1,0]
	v_exp_f32_e32 v71, v12
	s_nop 0
	v_pk_add_f32 v[70:71], v[70:71], 1.0 op_sel_hi:[1,0]
	v_mul_f32_e32 v12, 0xbfb8aa3b, v18
	v_exp_f32_e32 v72, v12
	v_rcp_f32_e32 v57, v57
	v_mul_f32_e32 v12, 0xbfb8aa3b, v19
	v_exp_f32_e32 v73, v12
	v_mul_f32_e32 v20, 0xbfb8aa3b, v20
	v_rcp_f32_e32 v56, v56
	v_pk_add_f32 v[72:73], v[72:73], 1.0 op_sel_hi:[1,0]
	v_mul_f32_e32 v21, 0xbfb8aa3b, v21
	v_exp_f32_e32 v20, v20
	v_rcp_f32_e32 v71, v71
	v_exp_f32_e32 v21, v21
	ds_read_b128 v[12:15], v58 offset:49152
	ds_read_b128 v[16:19], v58 offset:49168
	v_rcp_f32_e32 v70, v70
	v_pk_add_f32 v[20:21], v[20:21], 1.0 op_sel_hi:[1,0]
	s_waitcnt lgkmcnt(0)
	v_sub_f32_e32 v79, 1.0, v17
	v_sub_f32_e32 v81, 1.0, v19
	v_rcp_f32_e32 v73, v73
	v_sub_f32_e32 v80, 1.0, v18
	v_rcp_f32_e32 v72, v72
	s_nop 0
	v_rcp_f32_e32 v21, v21
	s_nop 0
	v_rcp_f32_e32 v20, v20
	v_sub_f32_e32 v75, 1.0, v13
	v_sub_f32_e32 v74, 1.0, v12
	v_sub_f32_e32 v77, 1.0, v15
	v_sub_f32_e32 v76, 1.0, v14
	v_sub_f32_e32 v78, 1.0, v16
	v_pk_fma_f32 v[20:21], v[20:21], v[80:81], v[18:19]
	v_pk_fma_f32 v[18:19], v[72:73], v[78:79], v[16:17]
	v_pk_fma_f32 v[14:15], v[70:71], v[76:77], v[14:15]
	v_pk_fma_f32 v[12:13], v[56:57], v[74:75], v[12:13]
	v_mov_b32_e32 v16, v59

.LBB0_553:
	s_waitcnt vmcnt(0)
	v_lshlrev_b32_e32 v12, 16, v4
	v_and_b32_e32 v13, 0xffff0000, v4
	v_lshlrev_b32_e32 v14, 16, v5
	v_and_b32_e32 v15, 0xffff0000, v5
	v_lshlrev_b32_e32 v18, 16, v6
	v_and_b32_e32 v19, 0xffff0000, v6
	v_lshlrev_b32_e32 v20, 16, v7
	v_and_b32_e32 v21, 0xffff0000, v7
	s_and_saveexec_b64 s[8:9], s[56:57]
	s_xor_b64 s[8:9], exec, s[8:9]
	s_or_saveexec_b64 s[8:9], s[8:9]
	v_mov_b32_e32 v16, v65
	s_xor_b64 exec, exec, s[8:9]
	s_cbranch_execz .LBB0_555
	v_mul_f32_e32 v12, 0xbfb8aa3b, v12
	v_exp_f32_e32 v56, v12
	v_mul_f32_e32 v12, 0xbfb8aa3b, v13
	v_exp_f32_e32 v57, v12
	v_mul_f32_e32 v12, 0xbfb8aa3b, v14
	v_exp_f32_e32 v70, v12
	v_mul_f32_e32 v12, 0xbfb8aa3b, v15
	v_pk_add_f32 v[56:57], v[56:57], 1.0 op_sel_hi:[1,0]
	v_exp_f32_e32 v71, v12
	s_nop 0
	v_pk_add_f32 v[70:71], v[70:71], 1.0 op_sel_hi:[1,0]
	v_mul_f32_e32 v12, 0xbfb8aa3b, v18
	v_exp_f32_e32 v72, v12
	v_rcp_f32_e32 v57, v57
	v_mul_f32_e32 v12, 0xbfb8aa3b, v19
	v_exp_f32_e32 v73, v12
	v_mul_f32_e32 v20, 0xbfb8aa3b, v20
	v_rcp_f32_e32 v56, v56
	v_pk_add_f32 v[72:73], v[72:73], 1.0 op_sel_hi:[1,0]
	v_mul_f32_e32 v21, 0xbfb8aa3b, v21
	v_exp_f32_e32 v20, v20
	v_rcp_f32_e32 v71, v71
	v_exp_f32_e32 v21, v21
	ds_read_b128 v[12:15], v60 offset:49152
	ds_read_b128 v[16:19], v60 offset:49168
	v_rcp_f32_e32 v70, v70
	v_pk_add_f32 v[20:21], v[20:21], 1.0 op_sel_hi:[1,0]
	s_waitcnt lgkmcnt(0)
	v_sub_f32_e32 v79, 1.0, v17
	v_sub_f32_e32 v81, 1.0, v19
	v_rcp_f32_e32 v73, v73
	v_sub_f32_e32 v80, 1.0, v18
	v_rcp_f32_e32 v72, v72
	s_nop 0
	v_rcp_f32_e32 v21, v21
	s_nop 0
	v_rcp_f32_e32 v20, v20
	v_sub_f32_e32 v75, 1.0, v13
	v_sub_f32_e32 v74, 1.0, v12
	v_sub_f32_e32 v77, 1.0, v15
	v_sub_f32_e32 v76, 1.0, v14
	v_sub_f32_e32 v78, 1.0, v16
	v_pk_fma_f32 v[20:21], v[20:21], v[80:81], v[18:19]
	v_pk_fma_f32 v[18:19], v[72:73], v[78:79], v[16:17]
	v_pk_fma_f32 v[14:15], v[70:71], v[76:77], v[14:15]
	v_pk_fma_f32 v[12:13], v[56:57], v[74:75], v[12:13]
	v_mov_b32_e32 v16, v61

.LBB0_556:
	s_waitcnt vmcnt(0)
	v_lshlrev_b32_e32 v12, 16, v8
	v_and_b32_e32 v13, 0xffff0000, v8
	v_lshlrev_b32_e32 v14, 16, v9
	v_and_b32_e32 v15, 0xffff0000, v9
	v_lshlrev_b32_e32 v18, 16, v10
	v_and_b32_e32 v19, 0xffff0000, v10
	v_lshlrev_b32_e32 v20, 16, v11
	v_and_b32_e32 v21, 0xffff0000, v11
	s_and_saveexec_b64 s[8:9], s[58:59]
	s_xor_b64 s[8:9], exec, s[8:9]
	s_or_saveexec_b64 s[8:9], s[8:9]
	v_mov_b32_e32 v16, v66
	s_xor_b64 exec, exec, s[8:9]
	s_cbranch_execz .LBB0_558
	v_mul_f32_e32 v12, 0xbfb8aa3b, v12
	v_exp_f32_e32 v56, v12
	v_mul_f32_e32 v12, 0xbfb8aa3b, v13
	v_exp_f32_e32 v57, v12
	v_mul_f32_e32 v12, 0xbfb8aa3b, v14
	v_exp_f32_e32 v70, v12
	v_mul_f32_e32 v12, 0xbfb8aa3b, v15
	v_pk_add_f32 v[56:57], v[56:57], 1.0 op_sel_hi:[1,0]
	v_exp_f32_e32 v71, v12
	s_nop 0
	v_pk_add_f32 v[70:71], v[70:71], 1.0 op_sel_hi:[1,0]
	v_mul_f32_e32 v12, 0xbfb8aa3b, v18
	v_exp_f32_e32 v72, v12
	v_rcp_f32_e32 v57, v57
	v_mul_f32_e32 v12, 0xbfb8aa3b, v19
	v_exp_f32_e32 v73, v12
	v_mul_f32_e32 v20, 0xbfb8aa3b, v20
	v_rcp_f32_e32 v56, v56
	v_pk_add_f32 v[72:73], v[72:73], 1.0 op_sel_hi:[1,0]
	v_mul_f32_e32 v21, 0xbfb8aa3b, v21
	v_exp_f32_e32 v20, v20
	v_rcp_f32_e32 v71, v71
	v_exp_f32_e32 v21, v21
	ds_read_b128 v[12:15], v62 offset:49152
	ds_read_b128 v[16:19], v62 offset:49168
	v_rcp_f32_e32 v70, v70
	v_pk_add_f32 v[20:21], v[20:21], 1.0 op_sel_hi:[1,0]
	s_waitcnt lgkmcnt(0)
	v_sub_f32_e32 v79, 1.0, v17
	v_sub_f32_e32 v81, 1.0, v19
	v_rcp_f32_e32 v73, v73
	v_sub_f32_e32 v80, 1.0, v18
	v_rcp_f32_e32 v72, v72
	s_nop 0
	v_rcp_f32_e32 v21, v21
	s_nop 0
	v_rcp_f32_e32 v20, v20
	v_sub_f32_e32 v75, 1.0, v13
	v_sub_f32_e32 v74, 1.0, v12
	v_sub_f32_e32 v77, 1.0, v15
	v_sub_f32_e32 v76, 1.0, v14
	v_sub_f32_e32 v78, 1.0, v16
	v_pk_fma_f32 v[20:21], v[20:21], v[80:81], v[18:19]
	v_pk_fma_f32 v[18:19], v[72:73], v[78:79], v[16:17]
	v_pk_fma_f32 v[14:15], v[70:71], v[76:77], v[14:15]
	v_pk_fma_f32 v[12:13], v[56:57], v[74:75], v[12:13]
	v_mov_b32_e32 v16, v63

.LBB0_1022:
	s_waitcnt vmcnt(3)
	v_and_b32_e32 v37, 64, v193
	v_xor_b32_e32 v36, 16, v193
	v_add_u32_e32 v37, 64, v37
	v_cmp_lt_i32_e32 vcc, v36, v37
	v_xor_b32_e32 v38, 32, v193
	s_mov_b32 s2, 1
	v_cndmask_b32_e32 v36, v193, v36, vcc
	s_waitcnt vmcnt(2)
	v_lshlrev_b32_e32 v40, 2, v36
	ds_bpermute_b32 v36, v40, v128
	v_cmp_lt_i32_e32 vcc, v38, v37
	s_waitcnt lgkmcnt(0)
	v_add_f32_e32 v36, v128, v36
	v_cndmask_b32_e32 v37, v193, v38, vcc
	v_lshlrev_b32_e32 v37, 2, v37
	ds_bpermute_b32 v38, v37, v36
	s_waitcnt lgkmcnt(0)
	v_add_f32_e32 v36, v36, v38
	v_rcp_f32_e32 v36, v36
	v_lshlrev_b32_e32 v38, 1, v104
	v_mov_b32_e32 v39, v31
	v_lshl_add_u64 v[38:39], v[102:103], 0, v[38:39]
	v_pk_mul_f32 v[32:33], v[32:33], v[36:37] op_sel_hi:[1,0]
	v_pk_mul_f32 v[26:27], v[26:27], v[36:37] op_sel_hi:[1,0]
	v_pk_mul_f32 v[24:25], v[24:25], v[36:37] op_sel_hi:[1,0]
	v_pk_mul_f32 v[34:35], v[34:35], v[36:37] op_sel_hi:[1,0]
	v_cvt_pk_bf16_f32 v32, v32, v33
	v_pk_mul_f32 v[18:19], v[18:19], v[36:37] op_sel_hi:[1,0]
	v_cvt_pk_bf16_f32 v33, v34, v35
	global_store_dwordx2 v[38:39], v[32:33], off
	v_cvt_pk_bf16_f32 v24, v24, v25
	v_cvt_pk_bf16_f32 v25, v26, v27
	ds_bpermute_b32 v26, v40, v127
	global_store_dwordx2 v[38:39], v[24:25], off offset:32
	v_pk_mul_f32 v[16:17], v[16:17], v[36:37] op_sel_hi:[1,0]
	s_waitcnt lgkmcnt(0)
	v_add_f32_e32 v24, v127, v26
	ds_bpermute_b32 v25, v37, v24
	v_cvt_pk_bf16_f32 v16, v16, v17
	v_cvt_pk_bf16_f32 v17, v18, v19
	v_pk_mul_f32 v[18:19], v[20:21], v[36:37] op_sel_hi:[1,0]
	global_store_dwordx2 v[38:39], v[16:17], off offset:64
	s_waitcnt lgkmcnt(0)
	v_add_f32_e32 v20, v24, v25
	v_div_scale_f32 v21, s[0:1], v20, v20, 1.0
	v_pk_mul_f32 v[16:17], v[22:23], v[36:37] op_sel_hi:[1,0]
	v_rcp_f32_e32 v22, v21
	v_cvt_pk_bf16_f32 v18, v18, v19
	v_cvt_pk_bf16_f32 v19, v16, v17
	global_store_dwordx2 v[38:39], v[18:19], off offset:96
	v_fma_f32 v16, -v21, v22, 1.0
	v_fmac_f32_e32 v22, v16, v22
	v_div_scale_f32 v16, vcc, 1.0, v20, 1.0
	v_mul_f32_e32 v17, v16, v22
	v_fma_f32 v18, -v21, v17, v16
	v_fmac_f32_e32 v17, v18, v22
	v_fma_f32 v16, -v21, v17, v16
	v_div_fmas_f32 v16, v16, v22, v17
	v_div_fixup_f32 v16, v16, v20, 1.0
	v_pk_mul_f32 v[10:11], v[10:11], v[16:17] op_sel_hi:[1,0]
	v_pk_mul_f32 v[8:9], v[8:9], v[16:17] op_sel_hi:[1,0]
	v_pk_mul_f32 v[4:5], v[4:5], v[16:17] op_sel_hi:[1,0]
	v_cvt_pk_bf16_f32 v8, v8, v9
	v_cvt_pk_bf16_f32 v9, v10, v11
	v_pk_mul_f32 v[10:11], v[12:13], v[16:17] op_sel_hi:[1,0]
	v_pk_mul_f32 v[0:1], v[0:1], v[16:17] op_sel_hi:[1,0]
	s_mov_b64 s[0:1], 0
	s_and_b64 vcc, exec, s[8:9]
	global_store_dwordx2 v[38:39], v[8:9], off offset:256
	v_pk_mul_f32 v[8:9], v[14:15], v[16:17] op_sel_hi:[1,0]
	v_cvt_pk_bf16_f32 v10, v10, v11
	v_pk_mul_f32 v[6:7], v[6:7], v[16:17] op_sel_hi:[1,0]
	v_cvt_pk_bf16_f32 v11, v8, v9
	global_store_dwordx2 v[38:39], v[10:11], off offset:288
	v_cvt_pk_bf16_f32 v4, v4, v5
	v_cvt_pk_bf16_f32 v5, v6, v7
	global_store_dwordx2 v[38:39], v[4:5], off offset:320
	v_pk_mul_f32 v[2:3], v[2:3], v[16:17] op_sel_hi:[1,0]
	v_cvt_pk_bf16_f32 v0, v0, v1
	s_nop 0
	v_cvt_pk_bf16_f32 v1, v2, v3
	global_store_dwordx2 v[38:39], v[0:1], off offset:352
	s_cbranch_vccnz .LBB0_630

.LBB0_1049:
	v_mul_f32_e32 v128, 0xbfb8aa3b, v128
	v_exp_f32_e32 v128, v128
	v_lshl_add_u32 v142, s21, 8, v146
	v_ashrrev_i32_e32 v143, 31, v142
	v_lshlrev_b64 v[144:145], 12, v[142:143]
	v_add_f32_e32 v128, 1.0, v128
	v_lshl_or_b32 v140, s20, 8, v164
	v_readlane_b32 s8, v250, 1
	v_ashrrev_i32_e32 v141, 31, v140
	v_readlane_b32 s9, v250, 2
	s_nop 1
	v_lshl_add_u64 v[166:167], s[8:9], 0, v[144:145]
	v_lshlrev_b64 v[144:145], 1, v[140:141]
	v_mul_f32_e32 v129, 0xbfb8aa3b, v129
	v_lshl_add_u64 v[140:141], v[166:167], 0, v[144:145]
	v_exp_f32_e32 v129, v129
	s_nop 0
	v_add_f32_e32 v129, 1.0, v129
	v_rcp_f32_e32 v128, v128
	v_mul_f32_e32 v124, 0xbfb8aa3b, v124
	v_exp_f32_e32 v124, v124
	v_mul_f32_e32 v125, 0xbfb8aa3b, v125
	v_rcp_f32_e32 v129, v129
	s_nop 0
	v_cvt_pk_bf16_f32 v128, v128, v129
	v_mul_f32_e32 v129, 0xbfb8aa3b, v130
	v_exp_f32_e32 v129, v129
	v_add_f32_e32 v124, 1.0, v124
	v_exp_f32_e32 v125, v125
	v_mul_f32_e32 v120, 0xbfb8aa3b, v120
	v_add_f32_e32 v129, 1.0, v129
	v_add_f32_e32 v125, 1.0, v125
	v_exp_f32_e32 v120, v120
	v_mul_f32_e32 v121, 0xbfb8aa3b, v121
	v_rcp_f32_e32 v129, v129
	v_mul_f32_e32 v130, 0xbfb8aa3b, v131
	v_exp_f32_e32 v130, v130
	v_add_f32_e32 v120, 1.0, v120
	v_exp_f32_e32 v121, v121
	v_mul_f32_e32 v116, 0xbfb8aa3b, v116
	v_add_f32_e32 v130, 1.0, v130
	v_add_f32_e32 v121, 1.0, v121
	v_exp_f32_e32 v116, v116
	v_mul_f32_e32 v117, 0xbfb8aa3b, v117
	v_rcp_f32_e32 v130, v130
	s_nop 0
	v_cvt_pk_bf16_f32 v129, v129, v130
	v_add_f32_e32 v116, 1.0, v116
	v_exp_f32_e32 v117, v117
	v_mul_f32_e32 v112, 0xbfb8aa3b, v112
	v_rcp_f32_e32 v124, v124
	v_add_f32_e32 v117, 1.0, v117
	v_exp_f32_e32 v112, v112
	v_mul_f32_e32 v113, 0xbfb8aa3b, v113
	v_rcp_f32_e32 v125, v125
	s_nop 0
	v_cvt_pk_bf16_f32 v130, v124, v125
	v_mul_f32_e32 v124, 0xbfb8aa3b, v126
	v_exp_f32_e32 v124, v124
	v_add_f32_e32 v112, 1.0, v112
	v_exp_f32_e32 v113, v113
	v_mul_f32_e32 v108, 0xbfb8aa3b, v108
	v_add_f32_e32 v124, 1.0, v124
	v_add_f32_e32 v113, 1.0, v113
	v_exp_f32_e32 v108, v108
	v_mul_f32_e32 v109, 0xbfb8aa3b, v109
	v_rcp_f32_e32 v124, v124
	v_mul_f32_e32 v125, 0xbfb8aa3b, v127
	v_exp_f32_e32 v125, v125
	v_add_f32_e32 v108, 1.0, v108
	v_exp_f32_e32 v109, v109
	v_mul_f32_e32 v104, 0xbfb8aa3b, v104
	v_add_f32_e32 v125, 1.0, v125
	v_add_f32_e32 v109, 1.0, v109
	v_exp_f32_e32 v104, v104
	v_mul_f32_e32 v105, 0xbfb8aa3b, v105
	v_rcp_f32_e32 v125, v125
	s_nop 0
	v_cvt_pk_bf16_f32 v131, v124, v125
	global_store_dwordx4 v[140:141], v[128:131], off offset:2048
	v_add_f32_e32 v104, 1.0, v104
	v_exp_f32_e32 v105, v105
	v_rcp_f32_e32 v120, v120
	v_add_f32_e32 v105, 1.0, v105
	v_mul_f32_e32 v100, 0xbfb8aa3b, v100
	v_exp_f32_e32 v100, v100
	v_rcp_f32_e32 v121, v121
	s_nop 0
	v_cvt_pk_bf16_f32 v120, v120, v121
	v_mul_f32_e32 v121, 0xbfb8aa3b, v122
	v_exp_f32_e32 v121, v121
	v_add_f32_e32 v100, 1.0, v100
	v_mul_f32_e32 v101, 0xbfb8aa3b, v101
	v_exp_f32_e32 v101, v101
	v_add_f32_e32 v121, 1.0, v121
	v_add_f32_e32 v101, 1.0, v101
	v_mul_f32_e32 v96, 0xbfb8aa3b, v96
	v_exp_f32_e32 v96, v96
	v_rcp_f32_e32 v121, v121
	v_mul_f32_e32 v122, 0xbfb8aa3b, v123
	v_exp_f32_e32 v122, v122
	v_add_f32_e32 v96, 1.0, v96
	v_mul_f32_e32 v97, 0xbfb8aa3b, v97
	v_exp_f32_e32 v97, v97
	v_add_f32_e32 v122, 1.0, v122
	v_add_f32_e32 v97, 1.0, v97
	v_mul_f32_e32 v92, 0xbfb8aa3b, v92
	v_exp_f32_e32 v92, v92
	v_rcp_f32_e32 v122, v122
	s_nop 0
	v_cvt_pk_bf16_f32 v121, v121, v122
	v_add_f32_e32 v92, 1.0, v92
	v_mul_f32_e32 v93, 0xbfb8aa3b, v93
	v_exp_f32_e32 v93, v93
	v_rcp_f32_e32 v116, v116
	v_add_f32_e32 v93, 1.0, v93
	v_mul_f32_e32 v88, 0xbfb8aa3b, v88
	v_exp_f32_e32 v88, v88
	v_rcp_f32_e32 v117, v117
	s_nop 0
	v_cvt_pk_bf16_f32 v122, v116, v117
	v_mul_f32_e32 v116, 0xbfb8aa3b, v118
	v_exp_f32_e32 v116, v116
	v_add_f32_e32 v88, 1.0, v88
	v_mul_f32_e32 v89, 0xbfb8aa3b, v89
	v_exp_f32_e32 v89, v89
	v_add_f32_e32 v116, 1.0, v116
	v_add_f32_e32 v89, 1.0, v89
	v_mul_f32_e32 v84, 0xbfb8aa3b, v84
	v_exp_f32_e32 v84, v84
	v_rcp_f32_e32 v116, v116
	v_mul_f32_e32 v117, 0xbfb8aa3b, v119
	v_exp_f32_e32 v117, v117
	v_add_f32_e32 v84, 1.0, v84
	v_mul_f32_e32 v85, 0xbfb8aa3b, v85
	v_exp_f32_e32 v85, v85
	v_add_f32_e32 v117, 1.0, v117
	v_add_f32_e32 v85, 1.0, v85
	v_mul_f32_e32 v80, 0xbfb8aa3b, v80
	v_exp_f32_e32 v80, v80
	v_rcp_f32_e32 v117, v117
	s_nop 0
	v_cvt_pk_bf16_f32 v123, v116, v117
	global_store_dwordx4 v[140:141], v[120:123], off offset:2304
	v_or_b32_e32 v116, 16, v142
	v_ashrrev_i32_e32 v117, 31, v116
	v_rcp_f32_e32 v112, v112
	v_lshlrev_b64 v[116:117], 12, v[116:117]
	v_lshl_add_u64 v[116:117], s[8:9], 0, v[116:117]
	v_lshl_add_u64 v[116:117], v[116:117], 0, v[144:145]
	v_rcp_f32_e32 v113, v113
	s_nop 0
	v_cvt_pk_bf16_f32 v112, v112, v113
	v_mul_f32_e32 v113, 0xbfb8aa3b, v114
	v_exp_f32_e32 v113, v113
	v_add_f32_e32 v80, 1.0, v80
	v_mul_f32_e32 v81, 0xbfb8aa3b, v81
	v_exp_f32_e32 v81, v81
	v_add_f32_e32 v113, 1.0, v113
	v_add_f32_e32 v81, 1.0, v81
	v_mul_f32_e32 v76, 0xbfb8aa3b, v76
	v_exp_f32_e32 v76, v76
	v_rcp_f32_e32 v113, v113
	v_mul_f32_e32 v114, 0xbfb8aa3b, v115
	v_exp_f32_e32 v114, v114
	v_add_f32_e32 v76, 1.0, v76
	v_mul_f32_e32 v77, 0xbfb8aa3b, v77
	v_exp_f32_e32 v77, v77
	v_add_f32_e32 v114, 1.0, v114
	v_add_f32_e32 v77, 1.0, v77
	v_mul_f32_e32 v72, 0xbfb8aa3b, v72
	v_exp_f32_e32 v72, v72
	v_rcp_f32_e32 v114, v114
	s_nop 0
	v_cvt_pk_bf16_f32 v113, v113, v114
	v_add_f32_e32 v72, 1.0, v72
	v_mul_f32_e32 v73, 0xbfb8aa3b, v73
	v_exp_f32_e32 v73, v73
	v_rcp_f32_e32 v108, v108
	v_add_f32_e32 v73, 1.0, v73
	v_mul_f32_e32 v68, 0xbfb8aa3b, v68
	v_exp_f32_e32 v68, v68
	v_rcp_f32_e32 v109, v109
	s_nop 0
	v_cvt_pk_bf16_f32 v114, v108, v109
	v_mul_f32_e32 v108, 0xbfb8aa3b, v110
	v_exp_f32_e32 v108, v108
	v_add_f32_e32 v68, 1.0, v68
	v_mul_f32_e32 v69, 0xbfb8aa3b, v69
	v_exp_f32_e32 v69, v69
	v_add_f32_e32 v108, 1.0, v108
	v_add_f32_e32 v69, 1.0, v69
	v_mul_f32_e32 v64, 0xbfb8aa3b, v64
	v_exp_f32_e32 v64, v64
	v_rcp_f32_e32 v108, v108
	v_mul_f32_e32 v109, 0xbfb8aa3b, v111
	v_exp_f32_e32 v109, v109
	v_add_f32_e32 v64, 1.0, v64
	v_mul_f32_e32 v65, 0xbfb8aa3b, v65
	v_exp_f32_e32 v65, v65
	v_add_f32_e32 v109, 1.0, v109
	v_add_f32_e32 v65, 1.0, v65
	v_mul_f32_e32 v60, 0xbfb8aa3b, v60
	v_exp_f32_e32 v60, v60
	v_rcp_f32_e32 v109, v109
	s_nop 0
	v_cvt_pk_bf16_f32 v115, v108, v109
	global_store_dwordx4 v[116:117], v[112:115], off offset:2048
	v_add_f32_e32 v60, 1.0, v60
	v_mul_f32_e32 v61, 0xbfb8aa3b, v61
	v_rcp_f32_e32 v104, v104
	v_exp_f32_e32 v61, v61
	v_mul_f32_e32 v56, 0xbfb8aa3b, v56
	v_exp_f32_e32 v56, v56
	v_rcp_f32_e32 v105, v105
	s_nop 0
	v_cvt_pk_bf16_f32 v104, v104, v105
	v_mul_f32_e32 v105, 0xbfb8aa3b, v106
	v_exp_f32_e32 v105, v105
	v_add_f32_e32 v61, 1.0, v61
	v_add_f32_e32 v56, 1.0, v56
	v_mul_f32_e32 v57, 0xbfb8aa3b, v57
	v_add_f32_e32 v105, 1.0, v105
	v_exp_f32_e32 v57, v57
	v_mul_f32_e32 v52, 0xbfb8aa3b, v52
	v_exp_f32_e32 v52, v52
	v_rcp_f32_e32 v105, v105
	v_mul_f32_e32 v106, 0xbfb8aa3b, v107
	v_exp_f32_e32 v106, v106
	v_add_f32_e32 v57, 1.0, v57
	v_add_f32_e32 v52, 1.0, v52
	v_mul_f32_e32 v53, 0xbfb8aa3b, v53
	v_add_f32_e32 v106, 1.0, v106
	v_exp_f32_e32 v53, v53
	v_mul_f32_e32 v48, 0xbfb8aa3b, v48
	v_exp_f32_e32 v48, v48
	v_rcp_f32_e32 v106, v106
	s_nop 0
	v_cvt_pk_bf16_f32 v105, v105, v106
	v_add_f32_e32 v53, 1.0, v53
	v_add_f32_e32 v48, 1.0, v48
	v_mul_f32_e32 v49, 0xbfb8aa3b, v49
	v_rcp_f32_e32 v100, v100
	v_exp_f32_e32 v49, v49
	v_mul_f32_e32 v44, 0xbfb8aa3b, v44
	v_exp_f32_e32 v44, v44
	v_rcp_f32_e32 v101, v101
	s_nop 0
	v_cvt_pk_bf16_f32 v106, v100, v101
	v_mul_f32_e32 v100, 0xbfb8aa3b, v102
	v_exp_f32_e32 v100, v100
	v_add_f32_e32 v49, 1.0, v49
	v_add_f32_e32 v44, 1.0, v44
	v_mul_f32_e32 v45, 0xbfb8aa3b, v45
	v_add_f32_e32 v100, 1.0, v100
	v_exp_f32_e32 v45, v45
	v_mul_f32_e32 v40, 0xbfb8aa3b, v40
	v_exp_f32_e32 v40, v40
	v_rcp_f32_e32 v100, v100
	v_mul_f32_e32 v101, 0xbfb8aa3b, v103
	v_exp_f32_e32 v101, v101
	v_add_f32_e32 v45, 1.0, v45
	v_add_f32_e32 v40, 1.0, v40
	v_mul_f32_e32 v41, 0xbfb8aa3b, v41
	v_add_f32_e32 v101, 1.0, v101
	v_exp_f32_e32 v41, v41
	v_mul_f32_e32 v36, 0xbfb8aa3b, v36
	v_exp_f32_e32 v36, v36
	v_rcp_f32_e32 v101, v101
	s_nop 0
	v_cvt_pk_bf16_f32 v107, v100, v101
	global_store_dwordx4 v[116:117], v[104:107], off offset:2304
	v_or_b32_e32 v100, 32, v142
	v_ashrrev_i32_e32 v101, 31, v100
	v_rcp_f32_e32 v96, v96
	v_lshlrev_b64 v[100:101], 12, v[100:101]
	v_lshl_add_u64 v[100:101], s[8:9], 0, v[100:101]
	v_lshl_add_u64 v[100:101], v[100:101], 0, v[144:145]
	v_rcp_f32_e32 v97, v97
	s_nop 0
	v_cvt_pk_bf16_f32 v96, v96, v97
	v_mul_f32_e32 v97, 0xbfb8aa3b, v98
	v_exp_f32_e32 v97, v97
	v_add_f32_e32 v41, 1.0, v41
	v_add_f32_e32 v36, 1.0, v36
	v_mul_f32_e32 v37, 0xbfb8aa3b, v37
	v_add_f32_e32 v97, 1.0, v97
	v_exp_f32_e32 v37, v37
	v_mul_f32_e32 v32, 0xbfb8aa3b, v32
	v_exp_f32_e32 v32, v32
	v_rcp_f32_e32 v97, v97
	v_mul_f32_e32 v98, 0xbfb8aa3b, v99
	v_exp_f32_e32 v98, v98
	v_add_f32_e32 v37, 1.0, v37
	v_add_f32_e32 v32, 1.0, v32
	v_mul_f32_e32 v33, 0xbfb8aa3b, v33
	v_add_f32_e32 v98, 1.0, v98
	v_exp_f32_e32 v33, v33
	v_mul_f32_e32 v24, 0xbfb8aa3b, v24
	v_exp_f32_e32 v24, v24
	v_rcp_f32_e32 v98, v98
	s_nop 0
	v_cvt_pk_bf16_f32 v97, v97, v98
	v_add_f32_e32 v33, 1.0, v33
	v_add_f32_e32 v24, 1.0, v24
	v_mul_f32_e32 v25, 0xbfb8aa3b, v25
	v_rcp_f32_e32 v92, v92
	v_exp_f32_e32 v25, v25
	v_mul_f32_e32 v20, 0xbfb8aa3b, v20
	v_exp_f32_e32 v20, v20
	v_rcp_f32_e32 v93, v93
	s_nop 0
	v_cvt_pk_bf16_f32 v98, v92, v93
	v_mul_f32_e32 v92, 0xbfb8aa3b, v94
	v_exp_f32_e32 v92, v92
	v_add_f32_e32 v25, 1.0, v25
	v_add_f32_e32 v20, 1.0, v20
	v_mul_f32_e32 v21, 0xbfb8aa3b, v21
	v_add_f32_e32 v92, 1.0, v92
	v_exp_f32_e32 v21, v21
	v_mul_f32_e32 v16, 0xbfb8aa3b, v16
	v_exp_f32_e32 v16, v16
	v_rcp_f32_e32 v92, v92
	v_mul_f32_e32 v93, 0xbfb8aa3b, v95
	v_exp_f32_e32 v93, v93
	v_add_f32_e32 v21, 1.0, v21
	v_add_f32_e32 v16, 1.0, v16
	v_mul_f32_e32 v17, 0xbfb8aa3b, v17
	v_add_f32_e32 v93, 1.0, v93
	v_div_scale_f32 v94, s[0:1], v93, v93, 1.0
	v_rcp_f32_e32 v95, v94
	v_exp_f32_e32 v17, v17
	v_mul_f32_e32 v12, 0xbfb8aa3b, v12
	v_exp_f32_e32 v12, v12
	v_fma_f32 v99, -v94, v95, 1.0
	v_fmac_f32_e32 v95, v99, v95
	v_div_scale_f32 v99, vcc, 1.0, v93, 1.0
	v_mul_f32_e32 v102, v99, v95
	v_fma_f32 v103, -v94, v102, v99
	v_fmac_f32_e32 v102, v103, v95
	v_fma_f32 v94, -v94, v102, v99
	v_div_fmas_f32 v94, v94, v95, v102
	v_div_fixup_f32 v93, v94, v93, 1.0
	v_cvt_pk_bf16_f32 v99, v92, v93
	global_store_dwordx4 v[100:101], v[96:99], off offset:2048
	v_add_f32_e32 v17, 1.0, v17
	v_add_f32_e32 v12, 1.0, v12
	v_rcp_f32_e32 v88, v88
	v_mul_f32_e32 v13, 0xbfb8aa3b, v13
	v_exp_f32_e32 v13, v13
	v_mul_f32_e32 v8, 0xbfb8aa3b, v8
	v_rcp_f32_e32 v89, v89
	s_nop 0
	v_cvt_pk_bf16_f32 v88, v88, v89
	v_mul_f32_e32 v89, 0xbfb8aa3b, v90
	v_exp_f32_e32 v89, v89
	v_add_f32_e32 v13, 1.0, v13
	v_exp_f32_e32 v8, v8
	v_mul_f32_e32 v9, 0xbfb8aa3b, v9
	v_add_f32_e32 v89, 1.0, v89
	v_add_f32_e32 v8, 1.0, v8
	v_exp_f32_e32 v9, v9
	v_mul_f32_e32 v4, 0xbfb8aa3b, v4
	v_rcp_f32_e32 v89, v89
	v_mul_f32_e32 v90, 0xbfb8aa3b, v91
	v_exp_f32_e32 v90, v90
	v_add_f32_e32 v9, 1.0, v9
	v_exp_f32_e32 v4, v4
	v_mul_f32_e32 v5, 0xbfb8aa3b, v5
	v_add_f32_e32 v90, 1.0, v90
	v_add_f32_e32 v4, 1.0, v4
	v_exp_f32_e32 v5, v5
	v_mul_f32_e32 v0, 0xbfb8aa3b, v0
	v_rcp_f32_e32 v90, v90
	s_nop 0
	v_cvt_pk_bf16_f32 v89, v89, v90
	v_add_f32_e32 v5, 1.0, v5
	v_exp_f32_e32 v0, v0
	v_mul_f32_e32 v1, 0xbfb8aa3b, v1
	v_rcp_f32_e32 v84, v84
	v_add_f32_e32 v0, 1.0, v0
	v_exp_f32_e32 v1, v1
	v_readlane_b32 s10, v250, 3
	v_rcp_f32_e32 v85, v85
	s_nop 0
	v_cvt_pk_bf16_f32 v90, v84, v85
	v_mul_f32_e32 v84, 0xbfb8aa3b, v86
	v_exp_f32_e32 v84, v84
	v_add_f32_e32 v1, 1.0, v1
	v_readlane_b32 s11, v250, 4
	v_add_f32_e32 v84, 1.0, v84
	s_nop 0
	v_rcp_f32_e32 v84, v84
	v_mul_f32_e32 v85, 0xbfb8aa3b, v87
	v_exp_f32_e32 v85, v85
	s_nop 0
	v_add_f32_e32 v85, 1.0, v85
	s_nop 0
	v_rcp_f32_e32 v85, v85
	s_nop 0
	v_cvt_pk_bf16_f32 v91, v84, v85
	global_store_dwordx4 v[100:101], v[88:91], off offset:2304
	v_or_b32_e32 v84, 48, v142
	v_ashrrev_i32_e32 v85, 31, v84
	v_rcp_f32_e32 v80, v80
	v_lshlrev_b64 v[84:85], 12, v[84:85]
	v_lshl_add_u64 v[84:85], s[8:9], 0, v[84:85]
	v_lshl_add_u64 v[84:85], v[84:85], 0, v[144:145]
	v_rcp_f32_e32 v81, v81
	s_nop 0
	v_cvt_pk_bf16_f32 v80, v80, v81
	v_mul_f32_e32 v81, 0xbfb8aa3b, v82
	v_exp_f32_e32 v81, v81
	s_nop 0
	v_add_f32_e32 v81, 1.0, v81
	s_nop 0
	v_rcp_f32_e32 v81, v81
	v_mul_f32_e32 v82, 0xbfb8aa3b, v83
	v_exp_f32_e32 v82, v82
	s_nop 0
	v_add_f32_e32 v82, 1.0, v82
	s_nop 0
	v_rcp_f32_e32 v82, v82
	s_nop 0
	v_cvt_pk_bf16_f32 v81, v81, v82
	s_nop 0
	v_rcp_f32_e32 v76, v76
	s_nop 0
	v_rcp_f32_e32 v77, v77
	s_nop 0
	v_cvt_pk_bf16_f32 v82, v76, v77
	v_mul_f32_e32 v76, 0xbfb8aa3b, v78
	v_exp_f32_e32 v76, v76
	s_nop 0
	v_add_f32_e32 v76, 1.0, v76
	s_nop 0
	v_rcp_f32_e32 v76, v76
	v_mul_f32_e32 v77, 0xbfb8aa3b, v79
	v_exp_f32_e32 v77, v77
	s_nop 0
	v_add_f32_e32 v77, 1.0, v77
	s_nop 0
	v_rcp_f32_e32 v77, v77
	s_nop 0
	v_cvt_pk_bf16_f32 v83, v76, v77
	global_store_dwordx4 v[84:85], v[80:83], off offset:2048
	v_rcp_f32_e32 v72, v72
	v_div_scale_f32 v76, s[0:1], v73, v73, 1.0
	v_rcp_f32_e32 v77, v76
	s_nop 0
	v_fma_f32 v78, -v76, v77, 1.0
	v_fmac_f32_e32 v77, v78, v77
	v_div_scale_f32 v78, vcc, 1.0, v73, 1.0
	v_mul_f32_e32 v79, v78, v77
	v_fma_f32 v80, -v76, v79, v78
	v_fmac_f32_e32 v79, v80, v77
	v_fma_f32 v76, -v76, v79, v78
	v_div_fmas_f32 v76, v76, v77, v79
	v_div_fixup_f32 v73, v76, v73, 1.0
	v_cvt_pk_bf16_f32 v72, v72, v73
	v_mul_f32_e32 v73, 0xbfb8aa3b, v74
	v_exp_f32_e32 v73, v73
	s_nop 0
	v_add_f32_e32 v73, 1.0, v73
	s_nop 0
	v_rcp_f32_e32 v73, v73
	v_mul_f32_e32 v74, 0xbfb8aa3b, v75
	v_exp_f32_e32 v74, v74
	s_nop 0
	v_add_f32_e32 v74, 1.0, v74
	v_div_scale_f32 v75, s[0:1], v74, v74, 1.0
	v_rcp_f32_e32 v76, v75
	s_nop 0
	v_fma_f32 v77, -v75, v76, 1.0
	v_fmac_f32_e32 v76, v77, v76
	v_div_scale_f32 v77, vcc, 1.0, v74, 1.0
	v_mul_f32_e32 v78, v77, v76
	v_fma_f32 v79, -v75, v78, v77
	v_fmac_f32_e32 v78, v79, v76
	v_fma_f32 v75, -v75, v78, v77
	v_div_fmas_f32 v75, v75, v76, v78
	v_div_fixup_f32 v74, v75, v74, 1.0
	v_cvt_pk_bf16_f32 v73, v73, v74
	s_nop 0
	v_rcp_f32_e32 v68, v68
	v_div_scale_f32 v74, s[0:1], v69, v69, 1.0
	v_rcp_f32_e32 v75, v74
	s_nop 0
	v_fma_f32 v76, -v74, v75, 1.0
	v_fmac_f32_e32 v75, v76, v75
	v_div_scale_f32 v76, vcc, 1.0, v69, 1.0
	v_mul_f32_e32 v77, v76, v75
	v_fma_f32 v78, -v74, v77, v76
	v_fmac_f32_e32 v77, v78, v75
	v_fma_f32 v74, -v74, v77, v76
	v_div_fmas_f32 v74, v74, v75, v77
	v_div_fixup_f32 v69, v74, v69, 1.0
	v_cvt_pk_bf16_f32 v74, v68, v69
	v_mul_f32_e32 v68, 0xbfb8aa3b, v70
	v_exp_f32_e32 v68, v68
	s_nop 0
	v_add_f32_e32 v68, 1.0, v68
	s_nop 0
	v_rcp_f32_e32 v68, v68
	v_mul_f32_e32 v69, 0xbfb8aa3b, v71
	v_exp_f32_e32 v69, v69
	s_nop 0
	v_add_f32_e32 v69, 1.0, v69
	v_div_scale_f32 v70, s[0:1], v69, v69, 1.0
	v_rcp_f32_e32 v71, v70
	s_mov_b64 s[0:1], 0x80000
	v_fma_f32 v75, -v70, v71, 1.0
	v_fmac_f32_e32 v71, v75, v71
	v_div_scale_f32 v75, vcc, 1.0, v69, 1.0
	v_mul_f32_e32 v76, v75, v71
	v_fma_f32 v77, -v70, v76, v75
	v_fmac_f32_e32 v76, v77, v71
	v_fma_f32 v70, -v70, v76, v75
	v_div_fmas_f32 v70, v70, v71, v76
	v_div_fixup_f32 v69, v70, v69, 1.0
	v_cvt_pk_bf16_f32 v75, v68, v69
	v_lshl_add_u64 v[68:69], v[140:141], 0, s[0:1]
	global_store_dwordx4 v[84:85], v[72:75], off offset:2304
	s_nop 1
	v_rcp_f32_e32 v64, v64
	v_div_scale_f32 v70, s[0:1], v65, v65, 1.0
	v_rcp_f32_e32 v71, v70
	s_nop 0
	v_fma_f32 v72, -v70, v71, 1.0
	v_fmac_f32_e32 v71, v72, v71
	v_div_scale_f32 v72, vcc, 1.0, v65, 1.0
	v_mul_f32_e32 v73, v72, v71
	v_fma_f32 v74, -v70, v73, v72
	v_fmac_f32_e32 v73, v74, v71
	v_fma_f32 v70, -v70, v73, v72
	v_div_fmas_f32 v70, v70, v71, v73
	v_div_fixup_f32 v65, v70, v65, 1.0
	v_cvt_pk_bf16_f32 v64, v64, v65
	v_mul_f32_e32 v65, 0xbfb8aa3b, v66
	v_exp_f32_e32 v65, v65
	s_nop 0
	v_add_f32_e32 v65, 1.0, v65
	s_nop 0
	v_rcp_f32_e32 v65, v65
	v_mul_f32_e32 v66, 0xbfb8aa3b, v67
	v_exp_f32_e32 v66, v66
	s_nop 0
	v_add_f32_e32 v66, 1.0, v66
	v_div_scale_f32 v67, s[0:1], v66, v66, 1.0
	v_rcp_f32_e32 v70, v67
	s_nop 0
	v_fma_f32 v71, -v67, v70, 1.0
	v_fmac_f32_e32 v70, v71, v70
	v_div_scale_f32 v71, vcc, 1.0, v66, 1.0
	v_mul_f32_e32 v72, v71, v70
	v_fma_f32 v73, -v67, v72, v71
	v_fmac_f32_e32 v72, v73, v70
	v_fma_f32 v67, -v67, v72, v71
	v_div_fmas_f32 v67, v67, v70, v72
	v_div_fixup_f32 v66, v67, v66, 1.0
	v_cvt_pk_bf16_f32 v65, v65, v66
	s_nop 0
	v_rcp_f32_e32 v60, v60
	v_div_scale_f32 v66, s[0:1], v61, v61, 1.0
	v_rcp_f32_e32 v67, v66
	s_nop 0
	v_fma_f32 v70, -v66, v67, 1.0
	v_fmac_f32_e32 v67, v70, v67
	v_div_scale_f32 v70, vcc, 1.0, v61, 1.0
	v_mul_f32_e32 v71, v70, v67
	v_fma_f32 v72, -v66, v71, v70
	v_fmac_f32_e32 v71, v72, v67
	v_fma_f32 v66, -v66, v71, v70
	v_div_fmas_f32 v66, v66, v67, v71
	v_div_fixup_f32 v61, v66, v61, 1.0
	v_cvt_pk_bf16_f32 v66, v60, v61
	v_mul_f32_e32 v60, 0xbfb8aa3b, v62
	v_exp_f32_e32 v60, v60
	s_nop 0
	v_add_f32_e32 v60, 1.0, v60
	s_nop 0
	v_rcp_f32_e32 v60, v60
	v_mul_f32_e32 v61, 0xbfb8aa3b, v63
	v_exp_f32_e32 v61, v61
	s_nop 0
	v_add_f32_e32 v61, 1.0, v61
	v_div_scale_f32 v62, s[0:1], v61, v61, 1.0
	v_rcp_f32_e32 v63, v62
	s_nop 0
	v_fma_f32 v67, -v62, v63, 1.0
	v_fmac_f32_e32 v63, v67, v63
	v_div_scale_f32 v67, vcc, 1.0, v61, 1.0
	v_mul_f32_e32 v70, v67, v63
	v_fma_f32 v71, -v62, v70, v67
	v_fmac_f32_e32 v70, v71, v63
	v_fma_f32 v62, -v62, v70, v67
	v_div_fmas_f32 v62, v62, v63, v70
	v_div_fixup_f32 v61, v62, v61, 1.0
	v_cvt_pk_bf16_f32 v67, v60, v61
	global_store_dwordx4 v[68:69], v[64:67], off offset:2048
	v_rcp_f32_e32 v56, v56
	s_nop 0
	v_rcp_f32_e32 v57, v57
	s_nop 0
	v_cvt_pk_bf16_f32 v56, v56, v57
	v_mul_f32_e32 v57, 0xbfb8aa3b, v58
	v_exp_f32_e32 v57, v57
	s_nop 0
	v_add_f32_e32 v57, 1.0, v57
	s_nop 0
	v_rcp_f32_e32 v57, v57
	v_mul_f32_e32 v58, 0xbfb8aa3b, v59
	v_exp_f32_e32 v58, v58
	s_nop 0
	v_add_f32_e32 v58, 1.0, v58
	s_nop 0
	v_rcp_f32_e32 v58, v58
	s_nop 0
	v_cvt_pk_bf16_f32 v57, v57, v58
	s_nop 0
	v_rcp_f32_e32 v52, v52
	s_nop 0
	v_rcp_f32_e32 v53, v53
	s_nop 0
	v_cvt_pk_bf16_f32 v58, v52, v53
	v_mul_f32_e32 v52, 0xbfb8aa3b, v54
	v_exp_f32_e32 v52, v52
	s_nop 0
	v_add_f32_e32 v52, 1.0, v52
	s_nop 0
	v_rcp_f32_e32 v52, v52
	v_mul_f32_e32 v53, 0xbfb8aa3b, v55
	v_exp_f32_e32 v53, v53
	s_nop 0
	v_add_f32_e32 v53, 1.0, v53
	s_mov_b64 s[0:1], 0x90000
	v_rcp_f32_e32 v53, v53
	s_nop 0
	v_cvt_pk_bf16_f32 v59, v52, v53
	v_lshl_add_u64 v[52:53], v[140:141], 0, s[0:1]
	global_store_dwordx4 v[68:69], v[56:59], off offset:2304
	s_nop 1
	v_rcp_f32_e32 v48, v48
	s_nop 0
	v_rcp_f32_e32 v49, v49
	s_nop 0
	v_cvt_pk_bf16_f32 v48, v48, v49
	v_mul_f32_e32 v49, 0xbfb8aa3b, v50
	v_exp_f32_e32 v49, v49
	s_nop 0
	v_add_f32_e32 v49, 1.0, v49
	s_nop 0
	v_rcp_f32_e32 v49, v49
	v_mul_f32_e32 v50, 0xbfb8aa3b, v51
	v_exp_f32_e32 v50, v50
	s_nop 0
	v_add_f32_e32 v50, 1.0, v50
	v_div_scale_f32 v51, s[0:1], v50, v50, 1.0
	v_rcp_f32_e32 v54, v51
	s_nop 0
	v_fma_f32 v55, -v51, v54, 1.0
	v_fmac_f32_e32 v54, v55, v54
	v_div_scale_f32 v55, vcc, 1.0, v50, 1.0
	v_mul_f32_e32 v56, v55, v54
	v_fma_f32 v57, -v51, v56, v55
	v_fmac_f32_e32 v56, v57, v54
	v_fma_f32 v51, -v51, v56, v55
	v_div_fmas_f32 v51, v51, v54, v56
	v_div_fixup_f32 v50, v51, v50, 1.0
	v_cvt_pk_bf16_f32 v49, v49, v50
	s_nop 0
	v_rcp_f32_e32 v44, v44
	v_div_scale_f32 v50, s[0:1], v45, v45, 1.0
	v_rcp_f32_e32 v51, v50
	s_nop 0
	v_fma_f32 v54, -v50, v51, 1.0
	v_fmac_f32_e32 v51, v54, v51
	v_div_scale_f32 v54, vcc, 1.0, v45, 1.0
	v_mul_f32_e32 v55, v54, v51
	v_fma_f32 v56, -v50, v55, v54
	v_fmac_f32_e32 v55, v56, v51
	v_fma_f32 v50, -v50, v55, v54
	v_div_fmas_f32 v50, v50, v51, v55
	v_div_fixup_f32 v45, v50, v45, 1.0
	v_cvt_pk_bf16_f32 v50, v44, v45
	v_mul_f32_e32 v44, 0xbfb8aa3b, v46
	v_exp_f32_e32 v44, v44
	s_nop 0
	v_add_f32_e32 v44, 1.0, v44
	s_nop 0
	v_rcp_f32_e32 v44, v44
	v_mul_f32_e32 v45, 0xbfb8aa3b, v47
	v_exp_f32_e32 v45, v45
	s_nop 0
	v_add_f32_e32 v45, 1.0, v45
	s_nop 0
	v_rcp_f32_e32 v45, v45
	s_nop 0
	v_cvt_pk_bf16_f32 v51, v44, v45
	global_store_dwordx4 v[52:53], v[48:51], off offset:2048
	v_rcp_f32_e32 v40, v40
	v_div_scale_f32 v44, s[0:1], v41, v41, 1.0
	v_rcp_f32_e32 v45, v44
	s_nop 0
	v_fma_f32 v46, -v44, v45, 1.0
	v_fmac_f32_e32 v45, v46, v45
	v_div_scale_f32 v46, vcc, 1.0, v41, 1.0
	v_mul_f32_e32 v47, v46, v45
	v_fma_f32 v48, -v44, v47, v46
	v_fmac_f32_e32 v47, v48, v45
	v_fma_f32 v44, -v44, v47, v46
	v_div_fmas_f32 v44, v44, v45, v47
	v_div_fixup_f32 v41, v44, v41, 1.0
	v_cvt_pk_bf16_f32 v40, v40, v41
	v_mul_f32_e32 v41, 0xbfb8aa3b, v42
	v_exp_f32_e32 v41, v41
	s_nop 0
	v_add_f32_e32 v41, 1.0, v41
	s_nop 0
	v_rcp_f32_e32 v41, v41
	v_mul_f32_e32 v42, 0xbfb8aa3b, v43
	v_exp_f32_e32 v42, v42
	s_nop 0
	v_add_f32_e32 v42, 1.0, v42
	s_nop 0
	v_rcp_f32_e32 v42, v42
	s_nop 0
	v_cvt_pk_bf16_f32 v41, v41, v42
	s_nop 0
	v_rcp_f32_e32 v36, v36
	s_nop 0
	v_rcp_f32_e32 v37, v37
	s_nop 0
	v_cvt_pk_bf16_f32 v42, v36, v37
	v_mul_f32_e32 v36, 0xbfb8aa3b, v38
	v_exp_f32_e32 v36, v36
	s_nop 0
	v_add_f32_e32 v36, 1.0, v36
	s_nop 0
	v_rcp_f32_e32 v36, v36
	v_mul_f32_e32 v37, 0xbfb8aa3b, v39
	v_exp_f32_e32 v37, v37
	s_nop 0
	v_add_f32_e32 v37, 1.0, v37
	s_mov_b64 s[0:1], 0xa0000
	v_rcp_f32_e32 v37, v37
	s_nop 0
	v_cvt_pk_bf16_f32 v43, v36, v37
	v_lshl_add_u64 v[36:37], v[140:141], 0, s[0:1]
	global_store_dwordx4 v[52:53], v[40:43], off offset:2304
	s_nop 1
	v_rcp_f32_e32 v32, v32
	s_nop 0
	v_rcp_f32_e32 v33, v33
	s_nop 0
	v_cvt_pk_bf16_f32 v32, v32, v33
	v_mul_f32_e32 v33, 0xbfb8aa3b, v34
	v_exp_f32_e32 v33, v33
	s_nop 0
	v_add_f32_e32 v33, 1.0, v33
	s_nop 0
	v_rcp_f32_e32 v33, v33
	v_mul_f32_e32 v34, 0xbfb8aa3b, v35
	v_exp_f32_e32 v34, v34
	s_nop 0
	v_add_f32_e32 v34, 1.0, v34
	s_nop 0
	v_rcp_f32_e32 v34, v34
	s_nop 0
	v_cvt_pk_bf16_f32 v33, v33, v34
	s_nop 0
	v_rcp_f32_e32 v24, v24
	s_nop 0
	v_rcp_f32_e32 v25, v25
	s_nop 0
	v_cvt_pk_bf16_f32 v34, v24, v25
	v_mul_f32_e32 v24, 0xbfb8aa3b, v26
	v_exp_f32_e32 v24, v24
	s_nop 0
	v_add_f32_e32 v24, 1.0, v24
	s_nop 0
	v_rcp_f32_e32 v24, v24
	v_mul_f32_e32 v25, 0xbfb8aa3b, v27
	v_exp_f32_e32 v25, v25
	s_nop 0
	v_add_f32_e32 v25, 1.0, v25
	s_nop 0
	v_rcp_f32_e32 v25, v25
	s_nop 0
	v_cvt_pk_bf16_f32 v35, v24, v25
	global_store_dwordx4 v[36:37], v[32:35], off offset:2048
	v_rcp_f32_e32 v20, v20
	s_nop 0
	v_rcp_f32_e32 v21, v21
	s_nop 0
	v_cvt_pk_bf16_f32 v20, v20, v21
	v_mul_f32_e32 v21, 0xbfb8aa3b, v22
	v_exp_f32_e32 v21, v21
	s_nop 0
	v_add_f32_e32 v21, 1.0, v21
	s_nop 0
	v_rcp_f32_e32 v21, v21
	v_mul_f32_e32 v22, 0xbfb8aa3b, v23
	v_exp_f32_e32 v22, v22
	s_nop 0
	v_add_f32_e32 v22, 1.0, v22
	s_nop 0
	v_rcp_f32_e32 v22, v22
	s_nop 0
	v_cvt_pk_bf16_f32 v21, v21, v22
	s_nop 0
	v_rcp_f32_e32 v16, v16
	s_nop 0
	v_rcp_f32_e32 v17, v17
	s_nop 0
	v_cvt_pk_bf16_f32 v22, v16, v17
	v_mul_f32_e32 v16, 0xbfb8aa3b, v18
	v_exp_f32_e32 v16, v16
	s_nop 0
	v_add_f32_e32 v16, 1.0, v16
	s_nop 0
	v_rcp_f32_e32 v16, v16
	v_mul_f32_e32 v17, 0xbfb8aa3b, v19
	v_exp_f32_e32 v17, v17
	s_nop 0
	v_add_f32_e32 v17, 1.0, v17
	s_mov_b64 s[0:1], 0xb0000
	v_rcp_f32_e32 v17, v17
	s_nop 0
	v_cvt_pk_bf16_f32 v23, v16, v17
	v_lshl_add_u64 v[16:17], v[140:141], 0, s[0:1]
	global_store_dwordx4 v[36:37], v[20:23], off offset:2304
	s_nop 1
	v_rcp_f32_e32 v12, v12
	v_div_scale_f32 v18, s[0:1], v13, v13, 1.0
	v_rcp_f32_e32 v19, v18
	s_nop 0
	v_fma_f32 v20, -v18, v19, 1.0
	v_fmac_f32_e32 v19, v20, v19
	v_div_scale_f32 v20, vcc, 1.0, v13, 1.0
	v_mul_f32_e32 v21, v20, v19
	v_fma_f32 v22, -v18, v21, v20
	v_fmac_f32_e32 v21, v22, v19
	v_fma_f32 v18, -v18, v21, v20
	v_div_fmas_f32 v18, v18, v19, v21
	v_div_fixup_f32 v13, v18, v13, 1.0
	v_cvt_pk_bf16_f32 v12, v12, v13
	v_mul_f32_e32 v13, 0xbfb8aa3b, v14
	v_exp_f32_e32 v13, v13
	s_nop 0
	v_add_f32_e32 v13, 1.0, v13
	s_nop 0
	v_rcp_f32_e32 v13, v13
	v_mul_f32_e32 v14, 0xbfb8aa3b, v15
	v_exp_f32_e32 v14, v14
	s_nop 0
	v_add_f32_e32 v14, 1.0, v14
	v_div_scale_f32 v15, s[0:1], v14, v14, 1.0
	v_rcp_f32_e32 v18, v15
	s_nop 0
	v_fma_f32 v19, -v15, v18, 1.0
	v_fmac_f32_e32 v18, v19, v18
	v_div_scale_f32 v19, vcc, 1.0, v14, 1.0
	v_mul_f32_e32 v20, v19, v18
	v_fma_f32 v21, -v15, v20, v19
	v_fmac_f32_e32 v20, v21, v18
	v_fma_f32 v15, -v15, v20, v19
	v_div_fmas_f32 v15, v15, v18, v20
	v_div_fixup_f32 v14, v15, v14, 1.0
	v_cvt_pk_bf16_f32 v13, v13, v14
	s_nop 0
	v_rcp_f32_e32 v8, v8
	s_nop 0
	v_rcp_f32_e32 v9, v9
	s_nop 0
	v_cvt_pk_bf16_f32 v14, v8, v9
	v_mul_f32_e32 v8, 0xbfb8aa3b, v10
	v_exp_f32_e32 v8, v8
	s_nop 0
	v_add_f32_e32 v8, 1.0, v8
	s_nop 0
	v_rcp_f32_e32 v8, v8
	v_mul_f32_e32 v9, 0xbfb8aa3b, v11
	v_exp_f32_e32 v9, v9
	s_nop 0
	v_add_f32_e32 v9, 1.0, v9
	s_nop 0
	v_rcp_f32_e32 v9, v9
	s_nop 0
	v_cvt_pk_bf16_f32 v15, v8, v9
	global_store_dwordx4 v[16:17], v[12:15], off offset:2048
	v_rcp_f32_e32 v4, v4
	v_div_scale_f32 v8, s[0:1], v5, v5, 1.0
	v_rcp_f32_e32 v9, v8
	s_nop 0
	v_fma_f32 v10, -v8, v9, 1.0
	v_fmac_f32_e32 v9, v10, v9
	v_div_scale_f32 v10, vcc, 1.0, v5, 1.0
	v_mul_f32_e32 v11, v10, v9
	v_fma_f32 v12, -v8, v11, v10
	v_fmac_f32_e32 v11, v12, v9
	v_fma_f32 v8, -v8, v11, v10
	v_div_fmas_f32 v8, v8, v9, v11
	v_div_fixup_f32 v5, v8, v5, 1.0
	v_cvt_pk_bf16_f32 v4, v4, v5
	v_mul_f32_e32 v5, 0xbfb8aa3b, v6
	v_exp_f32_e32 v5, v5
	s_nop 0
	v_add_f32_e32 v5, 1.0, v5
	s_nop 0
	v_rcp_f32_e32 v5, v5
	v_mul_f32_e32 v6, 0xbfb8aa3b, v7
	v_exp_f32_e32 v6, v6
	s_nop 0
	v_add_f32_e32 v6, 1.0, v6
	v_div_scale_f32 v7, s[0:1], v6, v6, 1.0
	v_rcp_f32_e32 v8, v7
	s_nop 0
	v_fma_f32 v9, -v7, v8, 1.0
	v_fmac_f32_e32 v8, v9, v8
	v_div_scale_f32 v9, vcc, 1.0, v6, 1.0
	v_mul_f32_e32 v10, v9, v8
	v_fma_f32 v11, -v7, v10, v9
	v_fmac_f32_e32 v10, v11, v8
	v_fma_f32 v7, -v7, v10, v9
	v_div_fmas_f32 v7, v7, v8, v10
	v_div_fixup_f32 v6, v7, v6, 1.0
	v_cvt_pk_bf16_f32 v5, v5, v6
	s_nop 0
	v_rcp_f32_e32 v0, v0
	v_div_scale_f32 v6, s[0:1], v1, v1, 1.0
	v_rcp_f32_e32 v7, v6
	s_nop 0
	v_fma_f32 v8, -v6, v7, 1.0
	v_fmac_f32_e32 v7, v8, v7
	v_div_scale_f32 v8, vcc, 1.0, v1, 1.0
	v_mul_f32_e32 v9, v8, v7
	v_fma_f32 v10, -v6, v9, v8
	v_fmac_f32_e32 v9, v10, v7
	v_fma_f32 v6, -v6, v9, v8
	v_div_fmas_f32 v6, v6, v7, v9
	v_div_fixup_f32 v1, v6, v1, 1.0
	v_cvt_pk_bf16_f32 v6, v0, v1
	v_mul_f32_e32 v0, 0xbfb8aa3b, v2
	v_exp_f32_e32 v0, v0
	s_nop 0
	v_add_f32_e32 v0, 1.0, v0
	s_nop 0
	v_rcp_f32_e32 v0, v0
	v_mul_f32_e32 v1, 0xbfb8aa3b, v3
	v_exp_f32_e32 v1, v1
	s_nop 0
	v_add_f32_e32 v1, 1.0, v1
	v_div_scale_f32 v2, s[0:1], v1, v1, 1.0
	v_rcp_f32_e32 v3, v2
	s_mov_b64 s[0:1], -1
	v_fma_f32 v7, -v2, v3, 1.0
	v_fmac_f32_e32 v3, v7, v3
	v_div_scale_f32 v7, vcc, 1.0, v1, 1.0
	v_mul_f32_e32 v8, v7, v3
	v_fma_f32 v9, -v2, v8, v7
	v_fmac_f32_e32 v8, v9, v3
	v_fma_f32 v2, -v2, v8, v7
	v_div_fmas_f32 v2, v2, v3, v8
	s_and_b64 vcc, exec, s[38:39]
	v_div_fixup_f32 v1, v2, v1, 1.0
	v_cvt_pk_bf16_f32 v7, v0, v1
	global_store_dwordx4 v[16:17], v[4:7], off offset:2304
	s_cbranch_vccnz .LBB0_1040
	s_andn2_b64 vcc, exec, s[4:5]
	s_cbranch_vccnz .LBB0_1039
	s_barrier
	s_branch .LBB0_1039

.LBB0_1135:
	ds_read_b128 v[48:51], v91
	ds_read_b128 v[108:111], v91 offset:16
	s_waitcnt vmcnt(0)
	v_lshlrev_b32_e32 v28, 16, v8
	v_and_b32_e32 v29, 0xffff0000, v8
	v_lshlrev_b32_e32 v52, 16, v24
	v_and_b32_e32 v53, 0xffff0000, v24
	v_pk_add_f32 v[52:53], v[52:53], v[28:29] neg_lo:[0,1] neg_hi:[0,1]
	v_lshlrev_b32_e32 v54, 16, v27
	s_waitcnt lgkmcnt(1)
	v_pk_fma_f32 v[48:49], v[52:53], v[48:49], v[28:29]
	v_lshlrev_b32_e32 v28, 16, v9
	v_and_b32_e32 v29, 0xffff0000, v9
	v_lshlrev_b32_e32 v52, 16, v25
	v_and_b32_e32 v53, 0xffff0000, v25
	v_pk_add_f32 v[52:53], v[52:53], v[28:29] neg_lo:[0,1] neg_hi:[0,1]
	v_and_b32_e32 v55, 0xffff0000, v27
	v_pk_fma_f32 v[52:53], v[52:53], v[50:51], v[28:29]
	v_lshlrev_b32_e32 v28, 16, v10
	v_and_b32_e32 v29, 0xffff0000, v10
	v_lshlrev_b32_e32 v50, 16, v26
	v_and_b32_e32 v51, 0xffff0000, v26
	v_pk_add_f32 v[50:51], v[50:51], v[28:29] neg_lo:[0,1] neg_hi:[0,1]
	s_waitcnt lgkmcnt(0)
	v_pk_fma_f32 v[50:51], v[50:51], v[108:109], v[28:29]
	v_lshlrev_b32_e32 v28, 16, v11
	v_and_b32_e32 v29, 0xffff0000, v11
	v_pk_add_f32 v[54:55], v[54:55], v[28:29] neg_lo:[0,1] neg_hi:[0,1]
	s_nop 0
	v_pk_fma_f32 v[28:29], v[54:55], v[110:111], v[28:29]
	s_and_saveexec_b64 s[2:3], s[86:87]
	s_xor_b64 s[2:3], exec, s[2:3]
	s_cbranch_execz .LBB0_1139
	v_mov_b32_e32 v30, v92
	s_and_saveexec_b64 s[6:7], s[88:89]
	s_cbranch_execz .LBB0_1138
	v_add_f32_e32 v30, v48, v48
	v_mul_f32_e32 v30, 0x3fb8aa3b, v30
	v_exp_f32_e32 v48, v30
	v_add_f32_e32 v30, v49, v49
	v_mul_f32_e32 v30, 0x3fb8aa3b, v30
	v_exp_f32_e32 v49, v30
	v_add_f32_e32 v30, v52, v52
	v_mul_f32_e32 v30, 0x3fb8aa3b, v30
	v_exp_f32_e32 v52, v30
	v_add_f32_e32 v30, v53, v53
	v_mul_f32_e32 v30, 0x3fb8aa3b, v30
	v_exp_f32_e32 v53, v30
	v_add_f32_e32 v30, v50, v50
	v_mul_f32_e32 v30, 0x3fb8aa3b, v30
	v_exp_f32_e32 v50, v30
	v_add_f32_e32 v30, v51, v51
	v_mul_f32_e32 v30, 0x3fb8aa3b, v30
	v_pk_add_f32 v[48:49], v[48:49], 1.0 op_sel_hi:[1,0]
	v_exp_f32_e32 v51, v30
	v_pk_add_f32 v[52:53], v[52:53], 1.0 op_sel_hi:[1,0]
	v_pk_add_f32 v[50:51], v[50:51], 1.0 op_sel_hi:[1,0]
	v_add_f32_e32 v28, v28, v28
	v_rcp_f32_e32 v30, v49
	s_nop 0
	v_mul_f32_e32 v49, -2.0, v30
	v_add_f32_e32 v29, v29, v29
	v_mul_f32_e32 v28, 0x3fb8aa3b, v28
	v_mul_f32_e32 v29, 0x3fb8aa3b, v29
	v_rcp_f32_e32 v30, v48
	s_nop 0
	v_mul_f32_e32 v48, -2.0, v30
	v_exp_f32_e32 v28, v28
	v_exp_f32_e32 v29, v29
	v_pk_add_f32 v[48:49], v[48:49], 1.0 op_sel_hi:[1,0]
	v_rcp_f32_e32 v30, v53
	s_nop 0
	v_mul_f32_e32 v53, -2.0, v30
	v_pk_add_f32 v[28:29], v[28:29], 1.0 op_sel_hi:[1,0]
	v_rcp_f32_e32 v30, v52
	s_nop 0
	v_mul_f32_e32 v52, -2.0, v30
	v_pk_add_f32 v[52:53], v[52:53], 1.0 op_sel_hi:[1,0]
	v_rcp_f32_e32 v30, v51
	s_nop 0
	v_mul_f32_e32 v51, -2.0, v30
	s_nop 0
	v_rcp_f32_e32 v30, v50
	s_nop 0
	v_mul_f32_e32 v50, -2.0, v30
	v_pk_add_f32 v[50:51], v[50:51], 1.0 op_sel_hi:[1,0]
	v_rcp_f32_e32 v30, v29
	s_nop 0
	v_mul_f32_e32 v29, -2.0, v30
	s_nop 0
	v_rcp_f32_e32 v30, v28
	s_nop 0
	v_mul_f32_e32 v28, -2.0, v30
	v_pk_add_f32 v[28:29], v[28:29], 1.0 op_sel_hi:[1,0]
	v_mov_b32_e32 v30, v93

.LBB0_1141:
	s_or_b64 exec, exec, s[0:1]
	s_and_saveexec_b64 s[0:1], s[66:67]
	s_cbranch_execz .LBB0_1148
	ds_read_b128 v[48:51], v95
	ds_read_b128 v[108:111], v95 offset:16
	s_waitcnt vmcnt(0)
	v_lshlrev_b32_e32 v28, 16, v32
	v_and_b32_e32 v29, 0xffff0000, v32
	v_lshlrev_b32_e32 v52, 16, v36
	v_and_b32_e32 v53, 0xffff0000, v36
	v_pk_add_f32 v[52:53], v[52:53], v[28:29] neg_lo:[0,1] neg_hi:[0,1]
	v_lshlrev_b32_e32 v54, 16, v39
	s_waitcnt lgkmcnt(1)
	v_pk_fma_f32 v[48:49], v[52:53], v[48:49], v[28:29]
	v_lshlrev_b32_e32 v28, 16, v33
	v_and_b32_e32 v29, 0xffff0000, v33
	v_lshlrev_b32_e32 v52, 16, v37
	v_and_b32_e32 v53, 0xffff0000, v37
	v_pk_add_f32 v[52:53], v[52:53], v[28:29] neg_lo:[0,1] neg_hi:[0,1]
	v_and_b32_e32 v55, 0xffff0000, v39
	v_pk_fma_f32 v[52:53], v[52:53], v[50:51], v[28:29]
	v_lshlrev_b32_e32 v28, 16, v34
	v_and_b32_e32 v29, 0xffff0000, v34
	v_lshlrev_b32_e32 v50, 16, v38
	v_and_b32_e32 v51, 0xffff0000, v38
	v_pk_add_f32 v[50:51], v[50:51], v[28:29] neg_lo:[0,1] neg_hi:[0,1]
	s_waitcnt lgkmcnt(0)
	v_pk_fma_f32 v[50:51], v[50:51], v[108:109], v[28:29]
	v_lshlrev_b32_e32 v28, 16, v35
	v_and_b32_e32 v29, 0xffff0000, v35
	v_pk_add_f32 v[54:55], v[54:55], v[28:29] neg_lo:[0,1] neg_hi:[0,1]
	s_nop 0
	v_pk_fma_f32 v[28:29], v[54:55], v[110:111], v[28:29]
	s_and_saveexec_b64 s[2:3], s[90:91]
	s_xor_b64 s[2:3], exec, s[2:3]
	s_cbranch_execz .LBB0_1146
	v_mov_b32_e32 v30, v96
	s_and_saveexec_b64 s[6:7], s[92:93]
	s_cbranch_execz .LBB0_1145
	v_add_f32_e32 v30, v48, v48
	v_mul_f32_e32 v30, 0x3fb8aa3b, v30
	v_exp_f32_e32 v48, v30
	v_add_f32_e32 v30, v49, v49
	v_mul_f32_e32 v30, 0x3fb8aa3b, v30
	v_exp_f32_e32 v49, v30
	v_add_f32_e32 v30, v52, v52
	v_mul_f32_e32 v30, 0x3fb8aa3b, v30
	v_exp_f32_e32 v52, v30
	v_add_f32_e32 v30, v53, v53
	v_mul_f32_e32 v30, 0x3fb8aa3b, v30
	v_exp_f32_e32 v53, v30
	v_add_f32_e32 v30, v50, v50
	v_mul_f32_e32 v30, 0x3fb8aa3b, v30
	v_exp_f32_e32 v50, v30
	v_add_f32_e32 v30, v51, v51
	v_mul_f32_e32 v30, 0x3fb8aa3b, v30
	v_pk_add_f32 v[48:49], v[48:49], 1.0 op_sel_hi:[1,0]
	v_exp_f32_e32 v51, v30
	v_pk_add_f32 v[52:53], v[52:53], 1.0 op_sel_hi:[1,0]
	v_pk_add_f32 v[50:51], v[50:51], 1.0 op_sel_hi:[1,0]
	v_add_f32_e32 v28, v28, v28
	v_rcp_f32_e32 v30, v49
	s_nop 0
	v_mul_f32_e32 v49, -2.0, v30
	v_add_f32_e32 v29, v29, v29
	v_mul_f32_e32 v28, 0x3fb8aa3b, v28
	v_mul_f32_e32 v29, 0x3fb8aa3b, v29
	v_rcp_f32_e32 v30, v48
	s_nop 0
	v_mul_f32_e32 v48, -2.0, v30
	v_exp_f32_e32 v28, v28
	v_exp_f32_e32 v29, v29
	v_pk_add_f32 v[48:49], v[48:49], 1.0 op_sel_hi:[1,0]
	v_rcp_f32_e32 v30, v53
	s_nop 0
	v_mul_f32_e32 v53, -2.0, v30
	v_pk_add_f32 v[28:29], v[28:29], 1.0 op_sel_hi:[1,0]
	v_rcp_f32_e32 v30, v52
	s_nop 0
	v_mul_f32_e32 v52, -2.0, v30
	v_pk_add_f32 v[52:53], v[52:53], 1.0 op_sel_hi:[1,0]
	v_rcp_f32_e32 v30, v51
	s_nop 0
	v_mul_f32_e32 v51, -2.0, v30
	s_nop 0
	v_rcp_f32_e32 v30, v50
	s_nop 0
	v_mul_f32_e32 v50, -2.0, v30
	v_pk_add_f32 v[50:51], v[50:51], 1.0 op_sel_hi:[1,0]
	v_rcp_f32_e32 v30, v29
	s_nop 0
	v_mul_f32_e32 v29, -2.0, v30
	s_nop 0
	v_rcp_f32_e32 v30, v28
	s_nop 0
	v_mul_f32_e32 v28, -2.0, v30
	v_pk_add_f32 v[28:29], v[28:29], 1.0 op_sel_hi:[1,0]
	v_mov_b32_e32 v30, v97

.LBB0_1148:
	s_or_b64 exec, exec, s[0:1]
	s_and_saveexec_b64 s[0:1], s[76:77]
	s_cbranch_execz .LBB0_1155
	ds_read_b128 v[48:51], v99
	ds_read_b128 v[108:111], v99 offset:16
	s_waitcnt vmcnt(0)
	v_lshlrev_b32_e32 v28, 16, v40
	v_and_b32_e32 v29, 0xffff0000, v40
	v_lshlrev_b32_e32 v52, 16, v44
	v_and_b32_e32 v53, 0xffff0000, v44
	v_pk_add_f32 v[52:53], v[52:53], v[28:29] neg_lo:[0,1] neg_hi:[0,1]
	v_lshlrev_b32_e32 v54, 16, v47
	s_waitcnt lgkmcnt(1)
	v_pk_fma_f32 v[48:49], v[52:53], v[48:49], v[28:29]
	v_lshlrev_b32_e32 v28, 16, v41
	v_and_b32_e32 v29, 0xffff0000, v41
	v_lshlrev_b32_e32 v52, 16, v45
	v_and_b32_e32 v53, 0xffff0000, v45
	v_pk_add_f32 v[52:53], v[52:53], v[28:29] neg_lo:[0,1] neg_hi:[0,1]
	v_and_b32_e32 v55, 0xffff0000, v47
	v_pk_fma_f32 v[52:53], v[52:53], v[50:51], v[28:29]
	v_lshlrev_b32_e32 v28, 16, v42
	v_and_b32_e32 v29, 0xffff0000, v42
	v_lshlrev_b32_e32 v50, 16, v46
	v_and_b32_e32 v51, 0xffff0000, v46
	v_pk_add_f32 v[50:51], v[50:51], v[28:29] neg_lo:[0,1] neg_hi:[0,1]
	s_waitcnt lgkmcnt(0)
	v_pk_fma_f32 v[50:51], v[50:51], v[108:109], v[28:29]
	v_lshlrev_b32_e32 v28, 16, v43
	v_and_b32_e32 v29, 0xffff0000, v43
	v_pk_add_f32 v[54:55], v[54:55], v[28:29] neg_lo:[0,1] neg_hi:[0,1]
	s_nop 0
	v_pk_fma_f32 v[28:29], v[54:55], v[110:111], v[28:29]
	s_and_saveexec_b64 s[2:3], s[94:95]
	s_xor_b64 s[2:3], exec, s[2:3]
	s_cbranch_execz .LBB0_1153
	v_mov_b32_e32 v30, v100
	s_and_saveexec_b64 s[6:7], s[96:97]
	s_cbranch_execz .LBB0_1152
	v_add_f32_e32 v30, v48, v48
	v_mul_f32_e32 v30, 0x3fb8aa3b, v30
	v_exp_f32_e32 v48, v30
	v_add_f32_e32 v30, v49, v49
	v_mul_f32_e32 v30, 0x3fb8aa3b, v30
	v_exp_f32_e32 v49, v30
	v_add_f32_e32 v30, v52, v52
	v_mul_f32_e32 v30, 0x3fb8aa3b, v30
	v_exp_f32_e32 v52, v30
	v_add_f32_e32 v30, v53, v53
	v_mul_f32_e32 v30, 0x3fb8aa3b, v30
	v_exp_f32_e32 v53, v30
	v_add_f32_e32 v30, v50, v50
	v_mul_f32_e32 v30, 0x3fb8aa3b, v30
	v_exp_f32_e32 v50, v30
	v_add_f32_e32 v30, v51, v51
	v_mul_f32_e32 v30, 0x3fb8aa3b, v30
	v_pk_add_f32 v[48:49], v[48:49], 1.0 op_sel_hi:[1,0]
	v_exp_f32_e32 v51, v30
	v_pk_add_f32 v[52:53], v[52:53], 1.0 op_sel_hi:[1,0]
	v_pk_add_f32 v[50:51], v[50:51], 1.0 op_sel_hi:[1,0]
	v_add_f32_e32 v28, v28, v28
	v_rcp_f32_e32 v30, v49
	s_nop 0
	v_mul_f32_e32 v49, -2.0, v30
	v_add_f32_e32 v29, v29, v29
	v_mul_f32_e32 v28, 0x3fb8aa3b, v28
	v_mul_f32_e32 v29, 0x3fb8aa3b, v29
	v_rcp_f32_e32 v30, v48
	s_nop 0
	v_mul_f32_e32 v48, -2.0, v30
	v_exp_f32_e32 v28, v28
	v_exp_f32_e32 v29, v29
	v_pk_add_f32 v[48:49], v[48:49], 1.0 op_sel_hi:[1,0]
	v_rcp_f32_e32 v30, v53
	s_nop 0
	v_mul_f32_e32 v53, -2.0, v30
	v_pk_add_f32 v[28:29], v[28:29], 1.0 op_sel_hi:[1,0]
	v_rcp_f32_e32 v30, v52
	s_nop 0
	v_mul_f32_e32 v52, -2.0, v30
	v_pk_add_f32 v[52:53], v[52:53], 1.0 op_sel_hi:[1,0]
	v_rcp_f32_e32 v30, v51
	s_nop 0
	v_mul_f32_e32 v51, -2.0, v30
	s_nop 0
	v_rcp_f32_e32 v30, v50
	s_nop 0
	v_mul_f32_e32 v50, -2.0, v30
	v_pk_add_f32 v[50:51], v[50:51], 1.0 op_sel_hi:[1,0]
	v_rcp_f32_e32 v30, v29
	s_nop 0
	v_mul_f32_e32 v29, -2.0, v30
	s_nop 0
	v_rcp_f32_e32 v30, v28
	s_nop 0
	v_mul_f32_e32 v28, -2.0, v30
	v_pk_add_f32 v[28:29], v[28:29], 1.0 op_sel_hi:[1,0]
	v_mov_b32_e32 v30, v101

.LBB0_1155:
	s_or_b64 exec, exec, s[0:1]
	s_and_saveexec_b64 s[0:1], s[42:43]
	s_cbranch_execz .LBB0_1157
	v_lshl_or_b32 v28, s21, 4, v81
	v_lshlrev_b32_e32 v29, 2, v28
	global_load_dwordx4 v[48:51], v29, s[26:27] offset:16
	global_load_dwordx4 v[52:55], v29, s[26:27]
	s_waitcnt vmcnt(2)
	v_lshlrev_b32_e32 v29, 16, v4
	v_lshlrev_b32_e32 v30, 16, v0
	v_sub_f32_e32 v29, v29, v30
	s_ashr_i32 s5, s4, 31
	s_waitcnt vmcnt(0)
	v_fmac_f32_e32 v30, v29, v52
	v_mul_f32_e32 v29, 0xbfb8aa3b, v30
	v_exp_f32_e32 v29, v29
	s_nop 0
	v_add_f32_e32 v29, 1.0, v29
	s_nop 0
	v_rcp_f32_e32 v29, v29
	v_and_b32_e32 v30, 0xffff0000, v0
	v_and_b32_e32 v52, 0xffff0000, v4
	v_sub_f32_e32 v52, v52, v30
	v_fmac_f32_e32 v30, v52, v53
	v_mul_f32_e32 v30, 0xbfb8aa3b, v30
	v_exp_f32_e32 v30, v30
	s_nop 0
	v_add_f32_e32 v30, 1.0, v30
	s_nop 0
	v_rcp_f32_e32 v30, v30
	v_lshlrev_b32_e32 v52, 16, v5
	v_lshlrev_b32_e32 v53, 16, v1
	v_sub_f32_e32 v52, v52, v53
	v_fmac_f32_e32 v53, v52, v54
	v_mul_f32_e32 v52, 0xbfb8aa3b, v53
	v_exp_f32_e32 v52, v52
	s_nop 0
	v_add_f32_e32 v52, 1.0, v52
	s_nop 0
	v_rcp_f32_e32 v52, v52
	v_and_b32_e32 v53, 0xffff0000, v1
	v_and_b32_e32 v54, 0xffff0000, v5
	v_sub_f32_e32 v54, v54, v53
	v_fmac_f32_e32 v53, v54, v55
	v_mul_f32_e32 v53, 0xbfb8aa3b, v53
	v_exp_f32_e32 v53, v53
	s_nop 0
	v_add_f32_e32 v53, 1.0, v53
	s_nop 0
	v_rcp_f32_e32 v53, v53
	v_lshlrev_b32_e32 v54, 16, v6
	v_lshlrev_b32_e32 v55, 16, v2
	v_sub_f32_e32 v54, v54, v55
	v_fmac_f32_e32 v55, v54, v48
	v_mul_f32_e32 v48, 0xbfb8aa3b, v55
	v_exp_f32_e32 v48, v48
	s_nop 0
	v_add_f32_e32 v48, 1.0, v48
	s_nop 0
	v_rcp_f32_e32 v48, v48
	v_and_b32_e32 v54, 0xffff0000, v2
	v_and_b32_e32 v55, 0xffff0000, v6
	v_sub_f32_e32 v55, v55, v54
	v_fmac_f32_e32 v54, v55, v49
	v_mul_f32_e32 v49, 0xbfb8aa3b, v54
	v_exp_f32_e32 v49, v49
	s_nop 0
	v_add_f32_e32 v49, 1.0, v49
	s_nop 0
	v_rcp_f32_e32 v49, v49
	v_lshlrev_b32_e32 v54, 16, v7
	v_lshlrev_b32_e32 v55, 16, v3
	v_sub_f32_e32 v54, v54, v55
	v_fmac_f32_e32 v55, v54, v50
	v_mul_f32_e32 v50, 0xbfb8aa3b, v55
	v_exp_f32_e32 v50, v50
	s_nop 0
	v_add_f32_e32 v50, 1.0, v50
	s_nop 0
	v_rcp_f32_e32 v54, v50
	v_and_b32_e32 v50, 0xffff0000, v3
	v_and_b32_e32 v55, 0xffff0000, v7
	v_sub_f32_e32 v55, v55, v50
	v_fmac_f32_e32 v50, v55, v51
	v_mul_f32_e32 v50, 0xbfb8aa3b, v50
	v_exp_f32_e32 v50, v50
	s_nop 0
	v_add_f32_e32 v50, 1.0, v50
	s_lshl_b64 s[2:3], s[4:5], 5
	s_movk_i32 s5, 0x3080
	v_rcp_f32_e32 v55, v50
	v_cvt_pk_bf16_f32 v51, v52, v53
	v_cvt_pk_bf16_f32 v52, v48, v49
	v_cvt_pk_bf16_f32 v53, v54, v55
	v_lshl_add_u64 v[48:49], s[2:3], 0, v[62:63]
	v_mov_b64_e32 v[54:55], s[34:35]
	v_mad_u64_u32 v[54:55], s[2:3], v48, s5, v[54:55]
	v_cvt_pk_bf16_f32 v50, v29, v30
	v_mad_i32_i24 v55, v49, s5, v55
	v_lshlrev_b32_e32 v30, 1, v28
	v_lshl_add_u64 v[28:29], v[54:55], 0, v[30:31]
	v_add_co_u32_e32 v28, vcc, 0x2000, v28
	s_nop 1
	v_addc_co_u32_e32 v29, vcc, 0, v29, vcc
	global_store_dwordx4 v[28:29], v[50:53], off offset:3728

.LBB0_1217:
	s_waitcnt lgkmcnt(0)
	s_barrier
	ds_read_b128 v[48:51], v103 offset:40960
	ds_read_b128 v[52:55], v104 offset:50176
	s_mov_b32 s2, 0xbfb8aa3b
	s_mov_b32 s5, 0x800000
	s_waitcnt lgkmcnt(0)
	v_mfma_f32_16x16x32_bf16 v[48:51], v[48:51], v[52:55], 0
	ds_read_b128 v[52:55], v103 offset:45568
	ds_read_b128 v[108:111], v104 offset:59392
	s_mov_b32 s10, 0x3f317217
	s_mov_b32 s11, 0x7f800000
	s_waitcnt lgkmcnt(0)
	v_mfma_f32_16x16x32_bf16 v[108:111], v[52:55], v[108:111], 0
	ds_read_b128 v[52:55], v103 offset:41024
	ds_read_b128 v[112:115], v104 offset:50240
	s_mov_b32 s13, 0xbf317218
	s_mov_b32 s14, 0x43000000
	s_waitcnt lgkmcnt(0)
	v_mfma_f32_16x16x32_bf16 v[52:55], v[52:55], v[112:115], v[48:51]
	s_nop 2
	ds_read_b128 v[48:51], v103 offset:45632
	ds_read_b128 v[112:115], v104 offset:59456
	s_mov_b32 s15, 0xc2b17217
	s_mov_b32 s16, 0x41880000
	s_waitcnt vmcnt(1)
	v_add_f32_e32 v28, v106, v52
	v_max_f32_e64 v29, -v28, 0
	v_mul_f32_e64 v28, |v28|, s2
	v_exp_f32_e32 v28, v28
	s_waitcnt lgkmcnt(0)
	v_mfma_f32_16x16x32_bf16 v[48:51], v[48:51], v[112:115], v[108:111]
	s_movk_i32 s3, 0x7fff
	v_add_f32_e32 v28, 1.0, v28
	v_cmp_gt_f32_e32 vcc, s5, v28
	s_nop 1
	v_cndmask_b32_e64 v30, 0, 32, vcc
	v_ldexp_f32 v28, v28, v30
	v_log_f32_e32 v28, v28
	s_nop 0
	v_mul_f32_e32 v30, 0x3f317217, v28
	v_fma_f32 v30, v28, s10, -v30
	v_fmac_f32_e32 v30, 0x3377d1cf, v28
	v_fmac_f32_e32 v30, 0x3f317217, v28
	v_cmp_lt_f32_e64 s[0:1], |v28|, s11
	s_nop 1
	v_cndmask_b32_e64 v28, v28, v30, s[0:1]
	v_cndmask_b32_e32 v30, 0, v196, vcc
	v_sub_f32_e32 v28, v28, v30
	v_add_f32_e32 v28, v29, v28
	v_sub_f32_e32 v28, -0.5, v28
	v_mul_f32_e32 v28, 0x3fb8aa3b, v28
	v_exp_f32_e32 v28, v28
	s_nop 0
	v_mul_f32_e32 v29, 0xbfb8aa3b, v28
	v_rndne_f32_e32 v29, v29
	v_fma_f32 v30, v29, s13, -v28
	v_fmac_f32_e32 v30, 0x3102e308, v29
	v_fmamk_f32 v52, v30, 0x395133b1, v191
	v_cmp_eq_f32_e32 vcc, s14, v29
	v_cvt_i32_f32_e32 v29, v29
	v_fmaak_f32 v52, v30, v52, 0x3c0887f9
	v_fmaak_f32 v52, v30, v52, 0x3d2aaa81
	v_fmaak_f32 v52, v30, v52, 0x3e2aaaab
	v_fma_f32 v52, v30, v52, 0.5
	v_ldexp_f32 v29, 1.0, v29
	v_mul_f32_e32 v52, v30, v52
	v_cndmask_b32_e32 v29, v29, v197, vcc
	v_fmac_f32_e32 v30, v30, v52
	v_add_f32_e32 v52, -1.0, v29
	v_fmac_f32_e32 v52, v29, v30
	v_add_f32_e32 v29, v52, v52
	v_cndmask_b32_e32 v29, v52, v29, vcc
	v_cmp_ngt_f32_e32 vcc, s15, v28
	s_nop 1
	v_cndmask_b32_e64 v29, v195, -v29, vcc
	v_cmp_nlt_f32_e32 vcc, s16, v28
	s_nop 1
	v_cndmask_b32_e32 v28, 1.0, v29, vcc
	v_bfe_u32 v29, v28, 16, 1
	v_add3_u32 v28, v28, v29, s3
	s_waitcnt vmcnt(0)
	v_add_f32_e32 v29, v107, v48
	v_mul_f32_e32 v29, 0xbfb8aa3b, v29
	v_exp_f32_e32 v29, v29
	v_and_b32_e32 v28, 0xffff0000, v28
	v_add_f32_e32 v29, 1.0, v29
	s_nop 0
	v_rcp_f32_e32 v29, v29
	s_nop 0
	v_bfe_u32 v30, v29, 16, 1
	v_add3_u32 v29, v29, v30, s3
	v_add_f32_e32 v30, v106, v53
	v_max_f32_e64 v48, -v30, 0
	v_mul_f32_e64 v30, |v30|, s2
	v_exp_f32_e32 v30, v30
	v_and_b32_e32 v29, 0xffff0000, v29
	v_add_f32_e32 v30, 1.0, v30
	v_cmp_gt_f32_e32 vcc, s5, v30
	s_nop 1
	v_cndmask_b32_e64 v52, 0, 32, vcc
	v_ldexp_f32 v30, v30, v52
	v_log_f32_e32 v30, v30
	s_nop 0
	v_mul_f32_e32 v52, 0x3f317217, v30
	v_fma_f32 v52, v30, s10, -v52
	v_fmac_f32_e32 v52, 0x3377d1cf, v30
	v_fmac_f32_e32 v52, 0x3f317217, v30
	v_cmp_lt_f32_e64 s[0:1], |v30|, s11
	s_nop 1
	v_cndmask_b32_e64 v30, v30, v52, s[0:1]
	v_cndmask_b32_e32 v52, 0, v196, vcc
	v_sub_f32_e32 v30, v30, v52
	v_add_f32_e32 v30, v48, v30
	v_sub_f32_e32 v30, -0.5, v30
	v_mul_f32_e32 v30, 0x3fb8aa3b, v30
	v_exp_f32_e32 v30, v30
	s_nop 0
	v_mul_f32_e32 v48, 0xbfb8aa3b, v30
	v_rndne_f32_e32 v48, v48
	v_fma_f32 v52, v48, s13, -v30
	v_fmac_f32_e32 v52, 0x3102e308, v48
	v_fmamk_f32 v53, v52, 0x395133b1, v191
	v_cmp_eq_f32_e32 vcc, s14, v48
	v_cvt_i32_f32_e32 v48, v48
	v_fmaak_f32 v53, v52, v53, 0x3c0887f9
	v_fmaak_f32 v53, v52, v53, 0x3d2aaa81
	v_fmaak_f32 v53, v52, v53, 0x3e2aaaab
	v_fma_f32 v53, v52, v53, 0.5
	v_ldexp_f32 v48, 1.0, v48
	v_mul_f32_e32 v53, v52, v53
	v_cndmask_b32_e32 v48, v48, v197, vcc
	v_fmac_f32_e32 v52, v52, v53
	v_add_f32_e32 v53, -1.0, v48
	v_fmac_f32_e32 v53, v48, v52
	v_add_f32_e32 v48, v53, v53
	v_cndmask_b32_e32 v48, v53, v48, vcc
	v_cmp_ngt_f32_e32 vcc, s15, v30
	s_nop 1
	v_cndmask_b32_e64 v48, v195, -v48, vcc
	v_cmp_nlt_f32_e32 vcc, s16, v30
	s_nop 1
	v_cndmask_b32_e32 v30, 1.0, v48, vcc
	v_bfe_u32 v48, v30, 16, 1
	v_add3_u32 v30, v30, v48, s3
	v_and_b32_e32 v30, 0xffff0000, v30
	ds_write2st64_b32 v105, v28, v30 offset0:96 offset1:97
	v_add_f32_e32 v28, v107, v49
	v_mul_f32_e32 v28, 0xbfb8aa3b, v28
	v_exp_f32_e32 v28, v28
	s_nop 0
	v_add_f32_e32 v28, 1.0, v28
	s_nop 0
	v_rcp_f32_e32 v28, v28
	s_nop 0
	v_bfe_u32 v30, v28, 16, 1
	v_add3_u32 v28, v28, v30, s3
	v_and_b32_e32 v28, 0xffff0000, v28
	ds_write2st64_b32 v105, v29, v28 offset0:128 offset1:129
	v_add_f32_e32 v28, v106, v54
	v_max_f32_e64 v29, -v28, 0
	v_mul_f32_e64 v28, |v28|, s2
	v_exp_f32_e32 v28, v28
	s_nop 0
	v_add_f32_e32 v28, 1.0, v28
	v_cmp_gt_f32_e32 vcc, s5, v28
	s_nop 1
	v_cndmask_b32_e64 v30, 0, 32, vcc
	v_ldexp_f32 v28, v28, v30
	v_log_f32_e32 v28, v28
	s_nop 0
	v_mul_f32_e32 v30, 0x3f317217, v28
	v_fma_f32 v30, v28, s10, -v30
	v_fmac_f32_e32 v30, 0x3377d1cf, v28
	v_fmac_f32_e32 v30, 0x3f317217, v28
	v_cmp_lt_f32_e64 s[0:1], |v28|, s11
	s_nop 1
	v_cndmask_b32_e64 v28, v28, v30, s[0:1]
	v_cndmask_b32_e32 v30, 0, v196, vcc
	v_sub_f32_e32 v28, v28, v30
	v_add_f32_e32 v28, v29, v28
	v_sub_f32_e32 v28, -0.5, v28
	v_mul_f32_e32 v28, 0x3fb8aa3b, v28
	v_exp_f32_e32 v28, v28
	s_nop 0
	v_mul_f32_e32 v29, 0xbfb8aa3b, v28
	v_rndne_f32_e32 v29, v29
	v_fma_f32 v30, v29, s13, -v28
	v_fmac_f32_e32 v30, 0x3102e308, v29
	v_fmamk_f32 v48, v30, 0x395133b1, v191
	v_cmp_eq_f32_e32 vcc, s14, v29
	v_cvt_i32_f32_e32 v29, v29
	v_fmaak_f32 v48, v30, v48, 0x3c0887f9
	v_fmaak_f32 v48, v30, v48, 0x3d2aaa81
	v_fmaak_f32 v48, v30, v48, 0x3e2aaaab
	v_fma_f32 v48, v30, v48, 0.5
	v_ldexp_f32 v29, 1.0, v29
	v_mul_f32_e32 v48, v30, v48
	v_cndmask_b32_e32 v29, v29, v197, vcc
	v_fmac_f32_e32 v30, v30, v48
	v_add_f32_e32 v48, -1.0, v29
	v_fmac_f32_e32 v48, v29, v30
	v_add_f32_e32 v29, v48, v48
	v_cndmask_b32_e32 v29, v48, v29, vcc
	v_cmp_ngt_f32_e32 vcc, s15, v28
	s_nop 1
	v_cndmask_b32_e64 v29, v195, -v29, vcc
	v_cmp_nlt_f32_e32 vcc, s16, v28
	s_nop 1
	v_cndmask_b32_e32 v28, 1.0, v29, vcc
	v_bfe_u32 v29, v28, 16, 1
	v_add3_u32 v28, v28, v29, s3
	v_add_f32_e32 v29, v107, v50
	v_mul_f32_e32 v29, 0xbfb8aa3b, v29
	v_exp_f32_e32 v29, v29
	v_and_b32_e32 v28, 0xffff0000, v28
	v_add_f32_e32 v29, 1.0, v29
	s_nop 0
	v_rcp_f32_e32 v29, v29
	s_nop 0
	v_bfe_u32 v30, v29, 16, 1
	v_add3_u32 v29, v29, v30, s3
	v_add_f32_e32 v30, v106, v55
	v_max_f32_e64 v48, -v30, 0
	v_mul_f32_e64 v30, |v30|, s2
	v_exp_f32_e32 v30, v30
	v_and_b32_e32 v29, 0xffff0000, v29
	s_movk_i32 s2, 0x3080
	v_add_f32_e32 v30, 1.0, v30
	v_cmp_gt_f32_e32 vcc, s5, v30
	s_ashr_i32 s5, s4, 31
	s_nop 0
	v_cndmask_b32_e64 v49, 0, 32, vcc
	v_ldexp_f32 v30, v30, v49
	v_log_f32_e32 v30, v30
	s_nop 0
	v_mul_f32_e32 v49, 0x3f317217, v30
	v_fma_f32 v49, v30, s10, -v49
	v_fmac_f32_e32 v49, 0x3377d1cf, v30
	v_fmac_f32_e32 v49, 0x3f317217, v30
	v_cmp_lt_f32_e64 s[0:1], |v30|, s11
	s_nop 1
	v_cndmask_b32_e64 v30, v30, v49, s[0:1]
	v_cndmask_b32_e32 v49, 0, v196, vcc
	v_sub_f32_e32 v30, v30, v49
	v_add_f32_e32 v30, v48, v30
	v_sub_f32_e32 v30, -0.5, v30
	v_mul_f32_e32 v30, 0x3fb8aa3b, v30
	v_exp_f32_e32 v30, v30
	s_nop 0
	v_mul_f32_e32 v48, 0xbfb8aa3b, v30
	v_rndne_f32_e32 v48, v48
	v_fma_f32 v49, v48, s13, -v30
	v_fmac_f32_e32 v49, 0x3102e308, v48
	v_fmamk_f32 v50, v49, 0x395133b1, v191
	v_cmp_eq_f32_e32 vcc, s14, v48
	v_cvt_i32_f32_e32 v48, v48
	v_fmaak_f32 v50, v49, v50, 0x3c0887f9
	v_fmaak_f32 v50, v49, v50, 0x3d2aaa81
	v_fmaak_f32 v50, v49, v50, 0x3e2aaaab
	v_fma_f32 v50, v49, v50, 0.5
	v_ldexp_f32 v48, 1.0, v48
	v_mul_f32_e32 v50, v49, v50
	v_cndmask_b32_e32 v48, v48, v197, vcc
	v_fmac_f32_e32 v49, v49, v50
	v_add_f32_e32 v50, -1.0, v48
	v_fmac_f32_e32 v50, v48, v49
	v_add_f32_e32 v48, v50, v50
	v_cndmask_b32_e32 v48, v50, v48, vcc
	v_cmp_ngt_f32_e32 vcc, s15, v30
	s_nop 1
	v_cndmask_b32_e64 v48, v195, -v48, vcc
	v_cmp_nlt_f32_e32 vcc, s16, v30
	s_nop 1
	v_cndmask_b32_e32 v30, 1.0, v48, vcc
	v_bfe_u32 v48, v30, 16, 1
	v_add3_u32 v30, v30, v48, s3
	v_and_b32_e32 v30, 0xffff0000, v30
	ds_write2st64_b32 v105, v28, v30 offset0:98 offset1:99
	v_add_f32_e32 v28, v107, v51
	v_mul_f32_e32 v28, 0xbfb8aa3b, v28
	v_exp_f32_e32 v28, v28
	s_nop 0
	v_add_f32_e32 v28, 1.0, v28
	s_lshl_b64 s[0:1], s[4:5], 5
	v_rcp_f32_e32 v28, v28
	s_nop 0
	v_bfe_u32 v30, v28, 16, 1
	v_add3_u32 v28, v28, v30, s3
	v_and_b32_e32 v28, 0xffff0000, v28
	ds_write2st64_b32 v105, v29, v28 offset0:130 offset1:131
	s_waitcnt lgkmcnt(0)
	s_barrier
	ds_read_b128 v[108:111], v83 offset:24576
	ds_read_b128 v[48:51], v83 offset:32768
	ds_read_b128 v[112:115], v83 offset:8192
	ds_read_b128 v[116:119], v83
	ds_read_b128 v[120:123], v83 offset:16384
	v_lshl_add_u64 v[28:29], s[0:1], 0, v[64:65]
	s_mov_b32 s0, 0xf800000
	s_waitcnt lgkmcnt(2)
	v_pk_mul_f32 v[54:55], v[14:15], v[114:115]
	v_pk_mul_f32 v[74:75], v[12:13], v[112:113]
	v_pk_mul_f32 v[52:53], v[54:55], v[54:55]
	v_pk_mul_f32 v[124:125], v[74:75], v[74:75]
	v_cvt_pk_bf16_f32 v108, v108, v109
	v_cvt_pk_bf16_f32 v109, v110, v111
	s_nop 0
	v_pk_mov_b32 v[126:127], v[124:125], v[52:53] op_sel:[1,0]
	v_mov_b32_e32 v125, v53
	v_pk_add_f32 v[52:53], v[126:127], v[124:125]
	v_pk_add_f32 v[126:127], v[48:49], -1.0 op_sel_hi:[1,0]
	v_add_f32_e32 v30, v52, v53
	v_pk_fma_f32 v[126:127], v[16:17], v[126:127], 1.0 op_sel_hi:[1,1,0]
	s_nop 0
	v_add_f32_dpp v30, v30, v30 quad_perm:[1,0,3,2] row_mask:0xf bank_mask:0xf bound_ctrl:1
	v_pk_mul_f32 v[126:127], v[112:113], v[126:127]
	v_cvt_pk_bf16_f32 v112, v112, v113
	v_cvt_pk_bf16_f32 v113, v114, v115
	s_nop 0
	v_add_f32_dpp v30, v30, v30 quad_perm:[2,3,0,1] row_mask:0xf bank_mask:0xf bound_ctrl:1
	s_waitcnt lgkmcnt(1)
	v_pk_mul_f32 v[126:127], v[116:117], v[126:127]
	v_add_f32_dpp v30, v30, v30 row_half_mirror row_mask:0xf bank_mask:0xf bound_ctrl:1
	v_pk_mul_f32 v[130:131], v[20:21], v[126:127]
	v_mov_b32_e32 v133, v126
	v_add_f32_dpp v30, v30, v30 row_mirror row_mask:0xf bank_mask:0xf bound_ctrl:1
	v_max_f32_e32 v30, 0x179abe15, v30
	v_cmp_gt_f32_e32 vcc, s0, v30
	v_mul_f32_e32 v52, 0x4f800000, v30
	s_nop 0
	v_cndmask_b32_e32 v30, v30, v52, vcc
	v_sqrt_f32_e32 v52, v30
	s_nop 0
	v_add_u32_e32 v53, -1, v52
	v_fma_f32 v73, -v53, v52, v30
	v_cmp_ge_f32_e64 s[0:1], 0, v73
	v_add_u32_e32 v73, 1, v52
	s_nop 0
	v_cndmask_b32_e64 v53, v52, v53, s[0:1]
	v_fma_f32 v52, -v73, v52, v30
	v_cmp_lt_f32_e64 s[0:1], 0, v52
	s_nop 1
	v_cndmask_b32_e64 v52, v53, v73, s[0:1]
	v_mul_f32_e32 v53, 0x37800000, v52
	v_cndmask_b32_e32 v52, v52, v53, vcc
	v_cmp_class_f32_e32 vcc, v30, v189
	s_nop 1
	v_cndmask_b32_e32 v30, v52, v30, vcc
	v_div_scale_f32 v52, s[0:1], v30, v30, 1.0
	v_rcp_f32_e32 v53, v52
	s_nop 0
	v_fma_f32 v73, -v52, v53, 1.0
	v_fmac_f32_e32 v53, v73, v53
	v_div_scale_f32 v73, vcc, 1.0, v30, 1.0
	v_mul_f32_e32 v124, v73, v53
	v_fma_f32 v125, -v52, v124, v73
	v_fmac_f32_e32 v124, v125, v53
	v_fma_f32 v52, -v52, v124, v73
	v_div_fmas_f32 v52, v52, v53, v124
	v_div_fixup_f32 v52, v52, v30, 1.0
	v_pk_mul_f32 v[74:75], v[74:75], v[52:53] op_sel_hi:[1,0]
	v_pk_add_f32 v[124:125], v[50:51], -1.0 op_sel_hi:[1,0]
	v_pk_mul_f32 v[54:55], v[54:55], v[52:53] op_sel_hi:[1,0]
	v_pk_fma_f32 v[124:125], v[18:19], v[124:125], 1.0 op_sel_hi:[1,1,0]
	v_pk_mul_f32 v[74:75], v[48:49], v[74:75]
	v_pk_mul_f32 v[124:125], v[114:115], v[124:125]
	v_pk_mul_f32 v[54:55], v[50:51], v[54:55]
	v_pk_mul_f32 v[74:75], v[116:117], v[74:75]
	v_pk_mul_f32 v[54:55], v[118:119], v[54:55]
	v_pk_mul_f32 v[124:125], v[118:119], v[124:125]
	v_mov_b32_e32 v132, v74
	v_mov_b32_e32 v126, v75
	v_pk_mul_f32 v[128:129], v[22:23], v[124:125]
	v_pk_add_f32 v[74:75], v[132:133], v[126:127]
	v_mov_b32_e32 v126, v54
	v_mov_b32_e32 v127, v124
	v_mov_b32_e32 v124, v55
	v_pk_add_f32 v[54:55], v[126:127], v[124:125]
	v_mov_b64_e32 v[124:125], s[34:35]
	v_mad_u64_u32 v[124:125], s[0:1], v28, s2, v[124:125]
	v_readlane_b32 s0, v254, 22
	v_readlane_b32 s1, v254, 23
	s_mov_b32 s13, s0
	v_mad_i32_i24 v125, v29, s2, v125
	s_lshl_b64 s[0:1], s[12:13], 1
	v_cvt_pk_bf16_f32 v116, v116, v117
	v_cvt_pk_bf16_f32 v117, v118, v119
	v_lshl_add_u64 v[118:119], v[124:125], 0, s[0:1]
	v_mov_b32_e32 v73, v31
	v_pk_add_f32 v[54:55], v[74:75], v[54:55]
	v_lshl_add_u64 v[118:119], v[118:119], 0, v[72:73]
	s_movk_i32 s2, 0x1000
	v_mov_b32_dpp v74, v54 quad_perm:[1,0,3,2] row_mask:0xf bank_mask:0xf bound_ctrl:1
	v_mov_b32_dpp v75, v55 quad_perm:[1,0,3,2] row_mask:0xf bank_mask:0xf bound_ctrl:1
	v_add_co_u32_e32 v114, vcc, s2, v118
	v_pk_add_f32 v[54:55], v[54:55], v[74:75]
	v_add_f32_e32 v30, v130, v131
	v_add_f32_e32 v53, v128, v129
	global_store_dwordx2 v[118:119], v[112:113], off offset:3072
	s_waitcnt lgkmcnt(0)
	v_cvt_pk_bf16_f32 v112, v120, v121
	v_cvt_pk_bf16_f32 v113, v122, v123
	v_addc_co_u32_e32 v115, vcc, 0, v119, vcc
	v_readlane_b32 s12, v250, 1
	v_mov_b32_dpp v74, v54 quad_perm:[2,3,0,1] row_mask:0xf bank_mask:0xf bound_ctrl:1
	v_mov_b32_dpp v75, v55 quad_perm:[2,3,0,1] row_mask:0xf bank_mask:0xf bound_ctrl:1
	v_add_f32_e32 v30, v30, v53
	global_store_dwordx2 v[114:115], v[112:113], off
	v_lshlrev_b64 v[112:113], 12, v[28:29]
	v_readlane_b32 s13, v250, 2
	v_pk_add_f32 v[54:55], v[54:55], v[74:75]
	v_add_f32_dpp v30, v30, v30 quad_perm:[1,0,3,2] row_mask:0xf bank_mask:0xf bound_ctrl:1
	v_lshl_add_u64 v[112:113], s[12:13], 0, v[112:113]
	v_mov_b32_dpp v74, v54 row_half_mirror row_mask:0xf bank_mask:0xf bound_ctrl:1
	v_mov_b32_dpp v75, v55 row_half_mirror row_mask:0xf bank_mask:0xf bound_ctrl:1
	v_add_f32_dpp v30, v30, v30 quad_perm:[2,3,0,1] row_mask:0xf bank_mask:0xf bound_ctrl:1
	v_cndmask_b32_e64 v112, v124, v112, s[52:53]
	v_cndmask_b32_e64 v113, v125, v113, s[52:53]
	v_pk_add_f32 v[54:55], v[54:55], v[74:75]
	v_add_f32_dpp v30, v30, v30 row_half_mirror row_mask:0xf bank_mask:0xf bound_ctrl:1
	v_lshl_add_u64 v[110:111], v[112:113], 0, s[0:1]
	v_mov_b32_dpp v74, v54 row_mirror row_mask:0xf bank_mask:0xf bound_ctrl:1
	v_mov_b32_dpp v75, v55 row_mirror row_mask:0xf bank_mask:0xf bound_ctrl:1
	v_mov_b32_dpp v53, v30 row_mirror row_mask:0xf bank_mask:0xf bound_ctrl:1
	v_lshl_add_u64 v[110:111], v[110:111], 0, v[72:73]
	global_store_dwordx2 v[118:119], v[116:117], off offset:2048
	v_readlane_b32 s14, v250, 3
	v_readlane_b32 s15, v250, 4
	global_store_dwordx2 v[110:111], v[108:109], off
	v_cvt_pk_bf16_f32 v48, v48, v49
	v_cvt_pk_bf16_f32 v49, v50, v51
	global_store_dwordx2 v[110:111], v[48:49], off offset:1024
	s_and_saveexec_b64 s[0:1], s[54:55]
	s_cbranch_execz .LBB0_1058
	v_readlane_b32 s2, v251, 57
	v_lshlrev_b64 v[28:29], 7, v[28:29]
	v_readlane_b32 s3, v251, 58
	v_readlane_b32 s4, v254, 22
	v_pk_add_f32 v[48:49], v[54:55], v[74:75]
	v_lshl_add_u64 v[28:29], s[2:3], 0, v[28:29]
	s_lshl_b32 s2, s21, 4
	s_mov_b32 s3, s4
	v_lshl_add_u64 v[28:29], v[28:29], 0, s[2:3]
	v_add_f32_e32 v55, v30, v53
	v_mov_b32_e32 v53, v48
	v_mov_b32_e32 v54, v49
	v_readlane_b32 s5, v254, 23
	global_store_dwordx4 v[28:29], v[52:55], off
	s_branch .LBB0_1058

.LBB0_1475:
	s_waitcnt lgkmcnt(0)
	v_add_f32_e32 v30, v30, v93
	v_fmamk_f32 v30, v30, 0x3a800000, v188
	s_mov_b32 s0, 0xf800000
	v_mul_f32_e32 v36, 0x4f800000, v30
	v_cmp_gt_f32_e32 vcc, s0, v30
	s_nop 1
	v_cndmask_b32_e32 v30, v30, v36, vcc
	v_sqrt_f32_e32 v36, v30
	s_nop 0
	v_add_u32_e32 v37, -1, v36
	v_fma_f32 v39, -v37, v36, v30
	v_add_u32_e32 v38, 1, v36
	v_cmp_ge_f32_e64 s[0:1], 0, v39
	s_nop 1
	v_cndmask_b32_e64 v37, v36, v37, s[0:1]
	v_fma_f32 v36, -v38, v36, v30
	v_cmp_lt_f32_e64 s[0:1], 0, v36
	s_nop 1
	v_cndmask_b32_e64 v36, v37, v38, s[0:1]
	v_mul_f32_e32 v37, 0x37800000, v36
	v_cndmask_b32_e32 v36, v36, v37, vcc
	v_cmp_class_f32_e32 vcc, v30, v189
	s_nop 1
	v_cndmask_b32_e32 v30, v36, v30, vcc
	s_nop 0
	v_rcp_f32_e32 v30, v30
	s_nop 0
	v_pk_mul_f32 v[32:33], v[32:33], v[30:31] op_sel_hi:[1,0]
	v_pk_mul_f32 v[24:25], v[24:25], v[30:31] op_sel_hi:[1,0]
	v_pk_mul_f32 v[20:21], v[20:21], v[30:31] op_sel_hi:[1,0]
	v_pk_mul_f32 v[16:17], v[16:17], v[30:31] op_sel_hi:[1,0]
	v_mad_i64_i32 v[36:37], s[0:1], s8, v194, v[84:85]
	v_pk_mul_f32 v[34:35], v[34:35], v[30:31] op_sel_hi:[1,0]
	v_pk_mul_f32 v[32:33], v[0:1], v[32:33]
	v_pk_mul_f32 v[26:27], v[26:27], v[30:31] op_sel_hi:[1,0]
	v_pk_mul_f32 v[24:25], v[4:5], v[24:25]
	v_pk_mul_f32 v[22:23], v[22:23], v[30:31] op_sel_hi:[1,0]
	v_pk_mul_f32 v[20:21], v[8:9], v[20:21]
	v_pk_mul_f32 v[18:19], v[18:19], v[30:31] op_sel_hi:[1,0]
	v_pk_mul_f32 v[16:17], v[12:13], v[16:17]
	v_pk_mul_f32 v[34:35], v[2:3], v[34:35]
	v_cvt_pk_bf16_f32 v32, v32, v33
	v_pk_mul_f32 v[26:27], v[6:7], v[26:27]
	v_cvt_pk_bf16_f32 v33, v34, v35
	global_store_dwordx2 v[36:37], v[32:33], off
	v_cvt_pk_bf16_f32 v24, v24, v25
	v_cvt_pk_bf16_f32 v25, v26, v27
	global_store_dwordx2 v[36:37], v[24:25], off offset:512
	v_pk_mul_f32 v[22:23], v[10:11], v[22:23]
	v_cvt_pk_bf16_f32 v20, v20, v21
	v_pk_mul_f32 v[18:19], v[14:15], v[18:19]
	v_cvt_pk_bf16_f32 v21, v22, v23
	global_store_dwordx2 v[36:37], v[20:21], off offset:1024
	v_cvt_pk_bf16_f32 v16, v16, v17
	v_cvt_pk_bf16_f32 v17, v18, v19
	global_store_dwordx2 v[36:37], v[16:17], off offset:1536
	s_branch .LBB0_1469
